# v46 + P11 FFN2 weight transposes with the same WG-cooperative scheme
# speedup vs baseline: 1.0045x; 1.0014x over previous
; #define LAS __attribute__((address_space(3)))
;     if (ldw == 0) ldw = N;
;     LAS float* scr = (LAS float*)(F.lds + F.wave * 16384); const int lane = F.lane;
;     const int nblk = N / 32, nitems = (K / 64) * nblk;
;     for (int item = F.gw; item < nitems; item += F.NGW) { const int kb = item / nblk, nb = item % nblk, k0 = 64 * kb, n0 = 32 * nb;
;         int dr0 = n0; if (MAP == 1) { if (n0 < DFF) dr0 = (n0 >> 7) * 256 + (n0 & 127); else { const int uo = n0 - DFF; dr0 = (uo >> 7) * 256 + 128 + (uo & 127); } }
; #pragma unroll 8
;         for (int i = 0; i < 32; ++i) { const int kk = 2 * i + (lane >> 5); scr[kk * 33 + (lane & 31)] = W[(size_t)(k0 + kk) * ldw + n0 + (lane & 31)]; }
; __device__ __forceinline__ void p0_prologue(Frame& F) {
;     ...
;     transpose_f8_matrix<1, true>(F, F.in[I_F1IN], D, NFF, F.ws + WS_WFI, I8_W);
.LBB0_11:
	s_or_b64 exec, exec, s[0:1]
	s_lshr_b32 s0, s86, 6
	s_lshl_b32 s79, s2, 3
	s_add_i32 s94, s0, s79
	s_lshl_b32 s92, s96, 3
	s_cmp_lt_i32 s94, 0xac00
	v_and_b32_e32 v178, 63, v0
	v_writelane_b32 v240, s0, 2
	s_cselect_b64 s[0:1], -1, 0
	v_writelane_b32 v240, s0, 3
	s_cmp_gt_i32 s94, 0xabff
	v_lshrrev_b32_e32 v162, 5, v178
	v_and_b32_e32 v164, 31, v0
	v_lshrrev_b32_e32 v163, 2, v178
	v_lshlrev_b32_e32 v167, 4, v0
	v_and_b32_e32 v165, 60, v178
	v_writelane_b32 v240, s1, 4
	s_cbranch_scc1 .LBB0_20
	s_barrier
	s_load_dwordx2 s[50:51], s[74:75], 0x38
	v_readlane_b32 s16, v240, 2
	v_lshlrev_b32_e32 v212, 4, v178
	v_mov_b32_e32 v216, 0x42fe0000
	s_mov_b32 s36, 0x44fe0000
	s_mov_b32 s37, 0
	s_mov_b32 s38, 0x4b400000
	s_mov_b32 s39, 0
	s_mov_b32 s40, 0xc2fe0000
	s_mov_b32 s41, 0x0c0c0400
	s_mov_b32 s42, 0x05040100
	s_lshl_b32 s17, s16, 5
	s_and_b32 s18, s16, 4
	s_lshl_b32 s18, s18, 5
	s_add_i32 s17, s17, s18
	v_mul_u32_u24_e32 v213, 0x240, v178
	s_lshl_b32 s18, s16, 4
	v_add_u32_e32 v213, s18, v213
	v_lshrrev_b32_e32 v204, 3, v178
	v_and_b32_e32 v205, 7, v178
	s_lshl_b32 s18, s16, 5
	v_add_u32_e32 v206, s18, v204
	v_mul_u32_u24_e32 v214, 0x90, v206
	v_lshl_add_u32 v214, v205, 4, v214
	v_mul_u32_u24_e32 v215, 0x1000, v204
	v_lshl_add_u32 v215, v205, 4, v215
	s_lshl_b32 s16, s16, 4
	s_waitcnt lgkmcnt(0)
	s_add_u32 s44, s90, 0x8300000
	s_addc_u32 s45, s91, 0
	s_mov_b32 s19, s2
	s_cmp_lt_u32 s19, 0xac0
	s_cbranch_scc0 .Lf8t_f1in0_end
	s_mul_hi_u32 s20, s19, 0x2fa0be9
	s_mul_i32 s21, s20, 86
	s_sub_i32 s21, s19, s21
	s_lshl_b32 s60, s20, 7
	s_lshl_b32 s61, s21, 8
	s_add_i32 s24, s60, s16
	s_mul_i32 s24, s24, 0x15800
	s_lshl_b32 s25, s61, 2
	s_add_u32 s24, s24, s25
	s_add_u32 s52, s50, s24
	s_addc_u32 s53, s51, 0
	global_load_dwordx4 v[80:83], v212, s[52:53]
	s_add_u32 s52, s52, 0x15800
	s_addc_u32 s53, s53, 0
	global_load_dwordx4 v[84:87], v212, s[52:53]
	s_add_u32 s52, s52, 0x15800
	s_addc_u32 s53, s53, 0
	global_load_dwordx4 v[88:91], v212, s[52:53]
	s_add_u32 s52, s52, 0x15800
	s_addc_u32 s53, s53, 0
	global_load_dwordx4 v[92:95], v212, s[52:53]
	s_add_u32 s52, s52, 0x15800
	s_addc_u32 s53, s53, 0
	global_load_dwordx4 v[96:99], v212, s[52:53]
	s_add_u32 s52, s52, 0x15800
	s_addc_u32 s53, s53, 0
	global_load_dwordx4 v[100:103], v212, s[52:53]
	s_add_u32 s52, s52, 0x15800
	s_addc_u32 s53, s53, 0
	global_load_dwordx4 v[104:107], v212, s[52:53]
	s_add_u32 s52, s52, 0x15800
	s_addc_u32 s53, s53, 0
	global_load_dwordx4 v[108:111], v212, s[52:53]
	s_add_u32 s52, s52, 0x15800
	s_addc_u32 s53, s53, 0
	global_load_dwordx4 v[112:115], v212, s[52:53]
	s_add_u32 s52, s52, 0x15800
	s_addc_u32 s53, s53, 0
	global_load_dwordx4 v[116:119], v212, s[52:53]
	s_add_u32 s52, s52, 0x15800
	s_addc_u32 s53, s53, 0
	global_load_dwordx4 v[120:123], v212, s[52:53]
	s_add_u32 s52, s52, 0x15800
	s_addc_u32 s53, s53, 0
	global_load_dwordx4 v[124:127], v212, s[52:53]
	s_add_u32 s52, s52, 0x15800
	s_addc_u32 s53, s53, 0
	global_load_dwordx4 v[128:131], v212, s[52:53]
	s_add_u32 s52, s52, 0x15800
	s_addc_u32 s53, s53, 0
	global_load_dwordx4 v[132:135], v212, s[52:53]
	s_add_u32 s52, s52, 0x15800
	s_addc_u32 s53, s53, 0
	global_load_dwordx4 v[136:139], v212, s[52:53]
	s_add_u32 s52, s52, 0x15800
	s_addc_u32 s53, s53, 0
	global_load_dwordx4 v[140:143], v212, s[52:53]
	s_mov_b32 s58, 1
.Lf8t_f1in0_loop:
	s_add_i32 s59, s19, s96
	s_cmp_lt_u32 s59, 0xac0
	s_cbranch_scc0 .Lf8t_f1in0_a_nonext
	s_mul_hi_u32 s20, s59, 0x2fa0be9
	s_mul_i32 s21, s20, 86
	s_sub_i32 s21, s59, s21
	s_lshl_b32 s62, s20, 7
	s_lshl_b32 s63, s21, 8
	s_add_i32 s24, s62, s16
	s_mul_i32 s24, s24, 0x15800
	s_lshl_b32 s25, s63, 2
	s_add_u32 s24, s24, s25
	s_add_u32 s52, s50, s24
	s_addc_u32 s53, s51, 0
	global_load_dwordx4 v[16:19], v212, s[52:53]
	s_add_u32 s52, s52, 0x15800
	s_addc_u32 s53, s53, 0
	global_load_dwordx4 v[20:23], v212, s[52:53]
	s_add_u32 s52, s52, 0x15800
	s_addc_u32 s53, s53, 0
	global_load_dwordx4 v[24:27], v212, s[52:53]
	s_add_u32 s52, s52, 0x15800
	s_addc_u32 s53, s53, 0
	global_load_dwordx4 v[28:31], v212, s[52:53]
	s_add_u32 s52, s52, 0x15800
	s_addc_u32 s53, s53, 0
	global_load_dwordx4 v[32:35], v212, s[52:53]
	s_add_u32 s52, s52, 0x15800
	s_addc_u32 s53, s53, 0
	global_load_dwordx4 v[36:39], v212, s[52:53]
	s_add_u32 s52, s52, 0x15800
	s_addc_u32 s53, s53, 0
	global_load_dwordx4 v[40:43], v212, s[52:53]
	s_add_u32 s52, s52, 0x15800
	s_addc_u32 s53, s53, 0
	global_load_dwordx4 v[44:47], v212, s[52:53]
	s_add_u32 s52, s52, 0x15800
	s_addc_u32 s53, s53, 0
	global_load_dwordx4 v[48:51], v212, s[52:53]
	s_add_u32 s52, s52, 0x15800
	s_addc_u32 s53, s53, 0
	global_load_dwordx4 v[52:55], v212, s[52:53]
	s_add_u32 s52, s52, 0x15800
	s_addc_u32 s53, s53, 0
	global_load_dwordx4 v[56:59], v212, s[52:53]
	s_add_u32 s52, s52, 0x15800
	s_addc_u32 s53, s53, 0
	global_load_dwordx4 v[60:63], v212, s[52:53]
	s_add_u32 s52, s52, 0x15800
	s_addc_u32 s53, s53, 0
	global_load_dwordx4 v[64:67], v212, s[52:53]
	s_add_u32 s52, s52, 0x15800
	s_addc_u32 s53, s53, 0
	global_load_dwordx4 v[68:71], v212, s[52:53]
	s_add_u32 s52, s52, 0x15800
	s_addc_u32 s53, s53, 0
	global_load_dwordx4 v[144:147], v212, s[52:53]
	s_add_u32 s52, s52, 0x15800
	s_addc_u32 s53, s53, 0
	global_load_dwordx4 v[148:151], v212, s[52:53]
	s_cmp_eq_u32 s58, 1
	s_cbranch_scc1 .Lf8t_f1in0_a_first
	s_waitcnt vmcnt(20)
	s_branch .Lf8t_f1in0_a_go

; __device__ __forceinline__ unsigned pk4_i8(float a, float b, float c, float d, float s) {
;     const unsigned ua = __float_as_uint(__builtin_amdgcn_fmed3f(a * s, -127.f, 127.f) + 12582912.f), ub = __float_as_uint(__builtin_amdgcn_fmed3f(b * s, -127.f, 127.f) + 12582912.f);
;     const unsigned uc = __float_as_uint(__builtin_amdgcn_fmed3f(c * s, -127.f, 127.f) + 12582912.f), ud = __float_as_uint(__builtin_amdgcn_fmed3f(d * s, -127.f, 127.f) + 12582912.f);
.Lf8t_f1in0_a_go:
	s_mov_b32 s58, 0
	v_pk_mul_f32 v[80:81], v[80:81], s[36:37] op_sel_hi:[1,0]
	v_pk_mul_f32 v[82:83], v[82:83], s[36:37] op_sel_hi:[1,0]
	v_pk_mul_f32 v[84:85], v[84:85], s[36:37] op_sel_hi:[1,0]
	v_pk_mul_f32 v[86:87], v[86:87], s[36:37] op_sel_hi:[1,0]
	v_pk_mul_f32 v[88:89], v[88:89], s[36:37] op_sel_hi:[1,0]
	v_pk_mul_f32 v[90:91], v[90:91], s[36:37] op_sel_hi:[1,0]
	v_pk_mul_f32 v[92:93], v[92:93], s[36:37] op_sel_hi:[1,0]
	v_pk_mul_f32 v[94:95], v[94:95], s[36:37] op_sel_hi:[1,0]
	v_pk_mul_f32 v[96:97], v[96:97], s[36:37] op_sel_hi:[1,0]
	v_pk_mul_f32 v[98:99], v[98:99], s[36:37] op_sel_hi:[1,0]
	v_pk_mul_f32 v[100:101], v[100:101], s[36:37] op_sel_hi:[1,0]
	v_pk_mul_f32 v[102:103], v[102:103], s[36:37] op_sel_hi:[1,0]
	v_pk_mul_f32 v[104:105], v[104:105], s[36:37] op_sel_hi:[1,0]
	v_pk_mul_f32 v[106:107], v[106:107], s[36:37] op_sel_hi:[1,0]
	v_pk_mul_f32 v[108:109], v[108:109], s[36:37] op_sel_hi:[1,0]
	v_pk_mul_f32 v[110:111], v[110:111], s[36:37] op_sel_hi:[1,0]
	v_pk_mul_f32 v[112:113], v[112:113], s[36:37] op_sel_hi:[1,0]
	v_pk_mul_f32 v[114:115], v[114:115], s[36:37] op_sel_hi:[1,0]
	v_pk_mul_f32 v[116:117], v[116:117], s[36:37] op_sel_hi:[1,0]
	v_pk_mul_f32 v[118:119], v[118:119], s[36:37] op_sel_hi:[1,0]
	v_pk_mul_f32 v[120:121], v[120:121], s[36:37] op_sel_hi:[1,0]
	v_pk_mul_f32 v[122:123], v[122:123], s[36:37] op_sel_hi:[1,0]
	v_pk_mul_f32 v[124:125], v[124:125], s[36:37] op_sel_hi:[1,0]
	v_pk_mul_f32 v[126:127], v[126:127], s[36:37] op_sel_hi:[1,0]
	v_pk_mul_f32 v[128:129], v[128:129], s[36:37] op_sel_hi:[1,0]
	v_pk_mul_f32 v[130:131], v[130:131], s[36:37] op_sel_hi:[1,0]
	v_pk_mul_f32 v[132:133], v[132:133], s[36:37] op_sel_hi:[1,0]
	v_pk_mul_f32 v[134:135], v[134:135], s[36:37] op_sel_hi:[1,0]
	v_pk_mul_f32 v[136:137], v[136:137], s[36:37] op_sel_hi:[1,0]
	v_pk_mul_f32 v[138:139], v[138:139], s[36:37] op_sel_hi:[1,0]
	v_pk_mul_f32 v[140:141], v[140:141], s[36:37] op_sel_hi:[1,0]
	v_pk_mul_f32 v[142:143], v[142:143], s[36:37] op_sel_hi:[1,0]
	v_med3_f32 v80, v80, s40, v216
	v_med3_f32 v81, v81, s40, v216
	v_med3_f32 v82, v82, s40, v216
	v_med3_f32 v83, v83, s40, v216
	v_med3_f32 v84, v84, s40, v216
	v_med3_f32 v85, v85, s40, v216
	v_med3_f32 v86, v86, s40, v216
	v_med3_f32 v87, v87, s40, v216
	v_med3_f32 v88, v88, s40, v216
	v_med3_f32 v89, v89, s40, v216
	v_med3_f32 v90, v90, s40, v216
	v_med3_f32 v91, v91, s40, v216
	v_med3_f32 v92, v92, s40, v216
	v_med3_f32 v93, v93, s40, v216
	v_med3_f32 v94, v94, s40, v216
	v_med3_f32 v95, v95, s40, v216
	v_med3_f32 v96, v96, s40, v216
	v_med3_f32 v97, v97, s40, v216
	v_med3_f32 v98, v98, s40, v216
	v_med3_f32 v99, v99, s40, v216
	v_med3_f32 v100, v100, s40, v216
	v_med3_f32 v101, v101, s40, v216
	v_med3_f32 v102, v102, s40, v216
	v_med3_f32 v103, v103, s40, v216
	v_med3_f32 v104, v104, s40, v216
	v_med3_f32 v105, v105, s40, v216
	v_med3_f32 v106, v106, s40, v216
	v_med3_f32 v107, v107, s40, v216
	v_med3_f32 v108, v108, s40, v216
	v_med3_f32 v109, v109, s40, v216
	v_med3_f32 v110, v110, s40, v216
	v_med3_f32 v111, v111, s40, v216
	v_med3_f32 v112, v112, s40, v216
	v_med3_f32 v113, v113, s40, v216
	v_med3_f32 v114, v114, s40, v216
	v_med3_f32 v115, v115, s40, v216
	v_med3_f32 v116, v116, s40, v216
	v_med3_f32 v117, v117, s40, v216
	v_med3_f32 v118, v118, s40, v216
	v_med3_f32 v119, v119, s40, v216
	v_med3_f32 v120, v120, s40, v216
	v_med3_f32 v121, v121, s40, v216
	v_med3_f32 v122, v122, s40, v216
	v_med3_f32 v123, v123, s40, v216
	v_med3_f32 v124, v124, s40, v216
	v_med3_f32 v125, v125, s40, v216
	v_med3_f32 v126, v126, s40, v216
	v_med3_f32 v127, v127, s40, v216
	v_med3_f32 v128, v128, s40, v216
	v_med3_f32 v129, v129, s40, v216
	v_med3_f32 v130, v130, s40, v216
	v_med3_f32 v131, v131, s40, v216
	v_med3_f32 v132, v132, s40, v216
	v_med3_f32 v133, v133, s40, v216
	v_med3_f32 v134, v134, s40, v216
	v_med3_f32 v135, v135, s40, v216
	v_med3_f32 v136, v136, s40, v216
	v_med3_f32 v137, v137, s40, v216
	v_med3_f32 v138, v138, s40, v216
	v_med3_f32 v139, v139, s40, v216
	v_med3_f32 v140, v140, s40, v216
	v_med3_f32 v141, v141, s40, v216
	v_med3_f32 v142, v142, s40, v216
	v_med3_f32 v143, v143, s40, v216
	v_pk_add_f32 v[80:81], v[80:81], s[38:39] op_sel_hi:[1,0]
	v_pk_add_f32 v[82:83], v[82:83], s[38:39] op_sel_hi:[1,0]
	v_pk_add_f32 v[84:85], v[84:85], s[38:39] op_sel_hi:[1,0]
	v_pk_add_f32 v[86:87], v[86:87], s[38:39] op_sel_hi:[1,0]
	v_pk_add_f32 v[88:89], v[88:89], s[38:39] op_sel_hi:[1,0]
	v_pk_add_f32 v[90:91], v[90:91], s[38:39] op_sel_hi:[1,0]
	v_pk_add_f32 v[92:93], v[92:93], s[38:39] op_sel_hi:[1,0]
	v_pk_add_f32 v[94:95], v[94:95], s[38:39] op_sel_hi:[1,0]
	v_pk_add_f32 v[96:97], v[96:97], s[38:39] op_sel_hi:[1,0]
	v_pk_add_f32 v[98:99], v[98:99], s[38:39] op_sel_hi:[1,0]
	v_pk_add_f32 v[100:101], v[100:101], s[38:39] op_sel_hi:[1,0]
	v_pk_add_f32 v[102:103], v[102:103], s[38:39] op_sel_hi:[1,0]
	v_pk_add_f32 v[104:105], v[104:105], s[38:39] op_sel_hi:[1,0]
	v_pk_add_f32 v[106:107], v[106:107], s[38:39] op_sel_hi:[1,0]
	v_pk_add_f32 v[108:109], v[108:109], s[38:39] op_sel_hi:[1,0]
	v_pk_add_f32 v[110:111], v[110:111], s[38:39] op_sel_hi:[1,0]
	v_pk_add_f32 v[112:113], v[112:113], s[38:39] op_sel_hi:[1,0]
	v_pk_add_f32 v[114:115], v[114:115], s[38:39] op_sel_hi:[1,0]
	v_pk_add_f32 v[116:117], v[116:117], s[38:39] op_sel_hi:[1,0]
	v_pk_add_f32 v[118:119], v[118:119], s[38:39] op_sel_hi:[1,0]
	v_pk_add_f32 v[120:121], v[120:121], s[38:39] op_sel_hi:[1,0]
; #define LAS __attribute__((address_space(3)))
; __device__ __forceinline__ unsigned pk4_f8(float a, float b, float c, float d) { int w = __builtin_amdgcn_cvt_pk_fp8_f32(a, b, 0, false); w = __builtin_amdgcn_cvt_pk_fp8_f32(c, d, w, true); return (unsigned)w; }
; #define LDS_WAIT() asm volatile("s_waitcnt lgkmcnt(0)" ::: "memory")
;     ...
;         int dr0 = n0; if (MAP == 1) { if (n0 < DFF) dr0 = (n0 >> 7) * 256 + (n0 & 127); else { const int uo = n0 - DFF; dr0 = (uo >> 7) * 256 + 128 + (uo & 127); } }
;     ...
;         for (int j = 0; j < 2; ++j) { const int n = (lane >> 2) + 16 * j; const LAS float* sp = scr + (16 * c) * 33 + n;
;             u32x4 o;
;             if (QI8) { o.x = pk4_i8(sp[0 * 33], sp[1 * 33], sp[2 * 33], sp[3 * 33], scl); o.y = pk4_i8(sp[4 * 33], sp[5 * 33], sp[6 * 33], sp[7 * 33], scl);
;                 o.z = pk4_i8(sp[8 * 33], sp[9 * 33], sp[10 * 33], sp[11 * 33], scl); o.w = pk4_i8(sp[12 * 33], sp[13 * 33], sp[14 * 33], sp[15 * 33], scl); }
;             else {
;             o.x = pk4_f8(sp[0 * 33] * scl, sp[1 * 33] * scl, sp[2 * 33] * scl, sp[3 * 33] * scl); o.y = pk4_f8(sp[4 * 33] * scl, sp[5 * 33] * scl, sp[6 * 33] * scl, sp[7 * 33] * scl);
;             o.z = pk4_f8(sp[8 * 33] * scl, sp[9 * 33] * scl, sp[10 * 33] * scl, sp[11 * 33] * scl); o.w = pk4_f8(sp[12 * 33] * scl, sp[13 * 33] * scl, sp[14 * 33] * scl, sp[15 * 33] * scl); }
;             *(u32x4*)(WT + (size_t)(dr0 + n) * K + k0 + 16 * c) = o; }
;         LDS_WAIT(); asm volatile("" ::: "memory"); }
	v_pk_add_f32 v[122:123], v[122:123], s[38:39] op_sel_hi:[1,0]
	v_pk_add_f32 v[124:125], v[124:125], s[38:39] op_sel_hi:[1,0]
	v_pk_add_f32 v[126:127], v[126:127], s[38:39] op_sel_hi:[1,0]
	v_pk_add_f32 v[128:129], v[128:129], s[38:39] op_sel_hi:[1,0]
	v_pk_add_f32 v[130:131], v[130:131], s[38:39] op_sel_hi:[1,0]
	v_pk_add_f32 v[132:133], v[132:133], s[38:39] op_sel_hi:[1,0]
	v_pk_add_f32 v[134:135], v[134:135], s[38:39] op_sel_hi:[1,0]
	v_pk_add_f32 v[136:137], v[136:137], s[38:39] op_sel_hi:[1,0]
	v_pk_add_f32 v[138:139], v[138:139], s[38:39] op_sel_hi:[1,0]
	v_pk_add_f32 v[140:141], v[140:141], s[38:39] op_sel_hi:[1,0]
	v_pk_add_f32 v[142:143], v[142:143], s[38:39] op_sel_hi:[1,0]
	v_perm_b32 v204, v84, v80, s41
	v_perm_b32 v205, v92, v88, s41
	v_perm_b32 v184, v205, v204, s42
	v_perm_b32 v204, v100, v96, s41
	v_perm_b32 v205, v108, v104, s41
	v_perm_b32 v185, v205, v204, s42
	v_perm_b32 v204, v116, v112, s41
	v_perm_b32 v205, v124, v120, s41
	v_perm_b32 v186, v205, v204, s42
	v_perm_b32 v204, v132, v128, s41
	v_perm_b32 v205, v140, v136, s41
	v_perm_b32 v187, v205, v204, s42
	v_perm_b32 v204, v85, v81, s41
	v_perm_b32 v205, v93, v89, s41
	v_perm_b32 v188, v205, v204, s42
	v_perm_b32 v204, v101, v97, s41
	v_perm_b32 v205, v109, v105, s41
	v_perm_b32 v189, v205, v204, s42
	v_perm_b32 v204, v117, v113, s41
	v_perm_b32 v205, v125, v121, s41
	v_perm_b32 v190, v205, v204, s42
	v_perm_b32 v204, v133, v129, s41
	v_perm_b32 v205, v141, v137, s41
	v_perm_b32 v191, v205, v204, s42
	v_perm_b32 v204, v86, v82, s41
	v_perm_b32 v205, v94, v90, s41
	v_perm_b32 v192, v205, v204, s42
	v_perm_b32 v204, v102, v98, s41
	v_perm_b32 v205, v110, v106, s41
	v_perm_b32 v193, v205, v204, s42
	v_perm_b32 v204, v118, v114, s41
	v_perm_b32 v205, v126, v122, s41
	v_perm_b32 v194, v205, v204, s42
	v_perm_b32 v204, v134, v130, s41
	v_perm_b32 v205, v142, v138, s41
	v_perm_b32 v195, v205, v204, s42
	v_perm_b32 v204, v87, v83, s41
	v_perm_b32 v205, v95, v91, s41
	v_perm_b32 v196, v205, v204, s42
	v_perm_b32 v204, v103, v99, s41
	v_perm_b32 v205, v111, v107, s41
	v_perm_b32 v197, v205, v204, s42
	v_perm_b32 v204, v119, v115, s41
	v_perm_b32 v205, v127, v123, s41
	v_perm_b32 v198, v205, v204, s42
	v_perm_b32 v204, v135, v131, s41
	v_perm_b32 v205, v143, v139, s41
	v_perm_b32 v199, v205, v204, s42
	ds_write_b128 v213, v[184:187] offset:0
	ds_write_b128 v213, v[188:191] offset:144
	ds_write_b128 v213, v[192:195] offset:288
	ds_write_b128 v213, v[196:199] offset:432
	s_lshl_b32 s26, s61, 1
	s_add_i32 s27, s26, 0xffffaa80
	s_cmp_lt_u32 s61, 0x2b00
	s_cselect_b32 s26, s26, s27
	s_add_i32 s26, s26, s17
	s_mul_i32 s26, s26, 0x1000
	s_add_u32 s26, s26, s60
	s_add_u32 s54, s44, s26
	s_addc_u32 s55, s45, 0
	s_waitcnt lgkmcnt(0)
	s_barrier
	ds_read_b128 v[184:187], v214 offset:0
	ds_read_b128 v[188:191], v214 offset:1152
	ds_read_b128 v[192:195], v214 offset:2304
	ds_read_b128 v[196:199], v214 offset:3456
	s_waitcnt lgkmcnt(3)
	global_store_dwordx4 v215, v[184:187], s[54:55]
	s_add_u32 s54, s54, 0x8000
	s_addc_u32 s55, s55, 0
	s_waitcnt lgkmcnt(2)
	global_store_dwordx4 v215, v[188:191], s[54:55]
	s_add_u32 s54, s54, 0x8000
	s_addc_u32 s55, s55, 0
	s_waitcnt lgkmcnt(1)
	global_store_dwordx4 v215, v[192:195], s[54:55]
	s_add_u32 s54, s54, 0x8000
	s_addc_u32 s55, s55, 0
	s_waitcnt lgkmcnt(0)
	global_store_dwordx4 v215, v[196:199], s[54:55]
	s_mov_b32 s19, s59
	s_cmp_lt_u32 s19, 0xac0
	s_cbranch_scc0 .Lf8t_f1in0_end
	s_add_i32 s59, s19, s96
	s_cmp_lt_u32 s59, 0xac0
	s_cbranch_scc0 .Lf8t_f1in0_b_nonext
	s_mul_hi_u32 s20, s59, 0x2fa0be9
	s_mul_i32 s21, s20, 86
	s_sub_i32 s21, s59, s21
	s_lshl_b32 s60, s20, 7
	s_lshl_b32 s61, s21, 8
	s_add_i32 s24, s60, s16
	s_mul_i32 s24, s24, 0x15800
	s_lshl_b32 s25, s61, 2
	s_add_u32 s24, s24, s25
	s_add_u32 s52, s50, s24
	s_addc_u32 s53, s51, 0
	global_load_dwordx4 v[80:83], v212, s[52:53]
	s_add_u32 s52, s52, 0x15800
	s_addc_u32 s53, s53, 0
	global_load_dwordx4 v[84:87], v212, s[52:53]
	s_add_u32 s52, s52, 0x15800
	s_addc_u32 s53, s53, 0
	global_load_dwordx4 v[88:91], v212, s[52:53]
	s_add_u32 s52, s52, 0x15800
	s_addc_u32 s53, s53, 0
	global_load_dwordx4 v[92:95], v212, s[52:53]
	s_add_u32 s52, s52, 0x15800
	s_addc_u32 s53, s53, 0
	global_load_dwordx4 v[96:99], v212, s[52:53]
	s_add_u32 s52, s52, 0x15800
	s_addc_u32 s53, s53, 0
	global_load_dwordx4 v[100:103], v212, s[52:53]
	s_add_u32 s52, s52, 0x15800
	s_addc_u32 s53, s53, 0
	global_load_dwordx4 v[104:107], v212, s[52:53]
	s_add_u32 s52, s52, 0x15800
	s_addc_u32 s53, s53, 0
	global_load_dwordx4 v[108:111], v212, s[52:53]
	s_add_u32 s52, s52, 0x15800
	s_addc_u32 s53, s53, 0
	global_load_dwordx4 v[112:115], v212, s[52:53]
	s_add_u32 s52, s52, 0x15800
	s_addc_u32 s53, s53, 0
	global_load_dwordx4 v[116:119], v212, s[52:53]
	s_add_u32 s52, s52, 0x15800
	s_addc_u32 s53, s53, 0
	global_load_dwordx4 v[120:123], v212, s[52:53]
	s_add_u32 s52, s52, 0x15800
	s_addc_u32 s53, s53, 0
	global_load_dwordx4 v[124:127], v212, s[52:53]
	s_add_u32 s52, s52, 0x15800
	s_addc_u32 s53, s53, 0
	global_load_dwordx4 v[128:131], v212, s[52:53]
	s_add_u32 s52, s52, 0x15800
	s_addc_u32 s53, s53, 0
	global_load_dwordx4 v[132:135], v212, s[52:53]
	s_add_u32 s52, s52, 0x15800
	s_addc_u32 s53, s53, 0
	global_load_dwordx4 v[136:139], v212, s[52:53]
	s_add_u32 s52, s52, 0x15800
	s_addc_u32 s53, s53, 0
	global_load_dwordx4 v[140:143], v212, s[52:53]
	s_waitcnt vmcnt(20)
	s_branch .Lf8t_f1in0_b_go

; #define LAS __attribute__((address_space(3)))
; __device__ __forceinline__ unsigned pk4_i8(float a, float b, float c, float d, float s) {
;     const unsigned ua = __float_as_uint(__builtin_amdgcn_fmed3f(a * s, -127.f, 127.f) + 12582912.f), ub = __float_as_uint(__builtin_amdgcn_fmed3f(b * s, -127.f, 127.f) + 12582912.f);
;     const unsigned uc = __float_as_uint(__builtin_amdgcn_fmed3f(c * s, -127.f, 127.f) + 12582912.f), ud = __float_as_uint(__builtin_amdgcn_fmed3f(d * s, -127.f, 127.f) + 12582912.f);
;     return (ua & 0xffu) | ((ub & 0xffu) << 8) | ((uc & 0xffu) << 16) | (ud << 24);
;     ...
;         for (int j = 0; j < 2; ++j) { const int n = (lane >> 2) + 16 * j; const LAS float* sp = scr + (16 * c) * 33 + n;
;             u32x4 o;
;             if (QI8) { o.x = pk4_i8(sp[0 * 33], sp[1 * 33], sp[2 * 33], sp[3 * 33], scl); o.y = pk4_i8(sp[4 * 33], sp[5 * 33], sp[6 * 33], sp[7 * 33], scl);
;                 o.z = pk4_i8(sp[8 * 33], sp[9 * 33], sp[10 * 33], sp[11 * 33], scl); o.w = pk4_i8(sp[12 * 33], sp[13 * 33], sp[14 * 33], sp[15 * 33], scl); }
.Lf8t_f1in0_b_go:
	v_pk_mul_f32 v[16:17], v[16:17], s[36:37] op_sel_hi:[1,0]
	v_pk_mul_f32 v[18:19], v[18:19], s[36:37] op_sel_hi:[1,0]
	v_pk_mul_f32 v[20:21], v[20:21], s[36:37] op_sel_hi:[1,0]
	v_pk_mul_f32 v[22:23], v[22:23], s[36:37] op_sel_hi:[1,0]
	v_pk_mul_f32 v[24:25], v[24:25], s[36:37] op_sel_hi:[1,0]
	v_pk_mul_f32 v[26:27], v[26:27], s[36:37] op_sel_hi:[1,0]
	v_pk_mul_f32 v[28:29], v[28:29], s[36:37] op_sel_hi:[1,0]
	v_pk_mul_f32 v[30:31], v[30:31], s[36:37] op_sel_hi:[1,0]
	v_pk_mul_f32 v[32:33], v[32:33], s[36:37] op_sel_hi:[1,0]
	v_pk_mul_f32 v[34:35], v[34:35], s[36:37] op_sel_hi:[1,0]
	v_pk_mul_f32 v[36:37], v[36:37], s[36:37] op_sel_hi:[1,0]
	v_pk_mul_f32 v[38:39], v[38:39], s[36:37] op_sel_hi:[1,0]
	v_pk_mul_f32 v[40:41], v[40:41], s[36:37] op_sel_hi:[1,0]
	v_pk_mul_f32 v[42:43], v[42:43], s[36:37] op_sel_hi:[1,0]
	v_pk_mul_f32 v[44:45], v[44:45], s[36:37] op_sel_hi:[1,0]
	v_pk_mul_f32 v[46:47], v[46:47], s[36:37] op_sel_hi:[1,0]
	v_pk_mul_f32 v[48:49], v[48:49], s[36:37] op_sel_hi:[1,0]
	v_pk_mul_f32 v[50:51], v[50:51], s[36:37] op_sel_hi:[1,0]
	v_pk_mul_f32 v[52:53], v[52:53], s[36:37] op_sel_hi:[1,0]
	v_pk_mul_f32 v[54:55], v[54:55], s[36:37] op_sel_hi:[1,0]
	v_pk_mul_f32 v[56:57], v[56:57], s[36:37] op_sel_hi:[1,0]
	v_pk_mul_f32 v[58:59], v[58:59], s[36:37] op_sel_hi:[1,0]
	v_pk_mul_f32 v[60:61], v[60:61], s[36:37] op_sel_hi:[1,0]
	v_pk_mul_f32 v[62:63], v[62:63], s[36:37] op_sel_hi:[1,0]
	v_pk_mul_f32 v[64:65], v[64:65], s[36:37] op_sel_hi:[1,0]
	v_pk_mul_f32 v[66:67], v[66:67], s[36:37] op_sel_hi:[1,0]
	v_pk_mul_f32 v[68:69], v[68:69], s[36:37] op_sel_hi:[1,0]
	v_pk_mul_f32 v[70:71], v[70:71], s[36:37] op_sel_hi:[1,0]
	v_pk_mul_f32 v[144:145], v[144:145], s[36:37] op_sel_hi:[1,0]
	v_pk_mul_f32 v[146:147], v[146:147], s[36:37] op_sel_hi:[1,0]
	v_pk_mul_f32 v[148:149], v[148:149], s[36:37] op_sel_hi:[1,0]
	v_pk_mul_f32 v[150:151], v[150:151], s[36:37] op_sel_hi:[1,0]
	v_med3_f32 v16, v16, s40, v216
	v_med3_f32 v17, v17, s40, v216
	v_med3_f32 v18, v18, s40, v216
	v_med3_f32 v19, v19, s40, v216
	v_med3_f32 v20, v20, s40, v216
	v_med3_f32 v21, v21, s40, v216
	v_med3_f32 v22, v22, s40, v216
	v_med3_f32 v23, v23, s40, v216
	v_med3_f32 v24, v24, s40, v216
	v_med3_f32 v25, v25, s40, v216
	v_med3_f32 v26, v26, s40, v216
	v_med3_f32 v27, v27, s40, v216
	v_med3_f32 v28, v28, s40, v216
	v_med3_f32 v29, v29, s40, v216
	v_med3_f32 v30, v30, s40, v216
	v_med3_f32 v31, v31, s40, v216
	v_med3_f32 v32, v32, s40, v216
	v_med3_f32 v33, v33, s40, v216
	v_med3_f32 v34, v34, s40, v216
	v_med3_f32 v35, v35, s40, v216
	v_med3_f32 v36, v36, s40, v216
	v_med3_f32 v37, v37, s40, v216
	v_med3_f32 v38, v38, s40, v216
	v_med3_f32 v39, v39, s40, v216
	v_med3_f32 v40, v40, s40, v216
	v_med3_f32 v41, v41, s40, v216
	v_med3_f32 v42, v42, s40, v216
	v_med3_f32 v43, v43, s40, v216
	v_med3_f32 v44, v44, s40, v216
	v_med3_f32 v45, v45, s40, v216
	v_med3_f32 v46, v46, s40, v216
	v_med3_f32 v47, v47, s40, v216
	v_med3_f32 v48, v48, s40, v216
	v_med3_f32 v49, v49, s40, v216
	v_med3_f32 v50, v50, s40, v216
	v_med3_f32 v51, v51, s40, v216
	v_med3_f32 v52, v52, s40, v216
	v_med3_f32 v53, v53, s40, v216
	v_med3_f32 v54, v54, s40, v216
	v_med3_f32 v55, v55, s40, v216
	v_med3_f32 v56, v56, s40, v216
	v_med3_f32 v57, v57, s40, v216
	v_med3_f32 v58, v58, s40, v216
	v_med3_f32 v59, v59, s40, v216
	v_med3_f32 v60, v60, s40, v216
	v_med3_f32 v61, v61, s40, v216
	v_med3_f32 v62, v62, s40, v216
	v_med3_f32 v63, v63, s40, v216
	v_med3_f32 v64, v64, s40, v216
	v_med3_f32 v65, v65, s40, v216
	v_med3_f32 v66, v66, s40, v216
	v_med3_f32 v67, v67, s40, v216
	v_med3_f32 v68, v68, s40, v216
	v_med3_f32 v69, v69, s40, v216
	v_med3_f32 v70, v70, s40, v216
	v_med3_f32 v71, v71, s40, v216
	v_med3_f32 v144, v144, s40, v216
	v_med3_f32 v145, v145, s40, v216
	v_med3_f32 v146, v146, s40, v216
	v_med3_f32 v147, v147, s40, v216
	v_med3_f32 v148, v148, s40, v216
	v_med3_f32 v149, v149, s40, v216
	v_med3_f32 v150, v150, s40, v216
	v_med3_f32 v151, v151, s40, v216
	v_pk_add_f32 v[16:17], v[16:17], s[38:39] op_sel_hi:[1,0]
	v_pk_add_f32 v[18:19], v[18:19], s[38:39] op_sel_hi:[1,0]
	v_pk_add_f32 v[20:21], v[20:21], s[38:39] op_sel_hi:[1,0]
	v_pk_add_f32 v[22:23], v[22:23], s[38:39] op_sel_hi:[1,0]
	v_pk_add_f32 v[24:25], v[24:25], s[38:39] op_sel_hi:[1,0]
; #define LAS __attribute__((address_space(3)))
; __device__ __forceinline__ unsigned pk4_f8(float a, float b, float c, float d) { int w = __builtin_amdgcn_cvt_pk_fp8_f32(a, b, 0, false); w = __builtin_amdgcn_cvt_pk_fp8_f32(c, d, w, true); return (unsigned)w; }
; #define LDS_WAIT() asm volatile("s_waitcnt lgkmcnt(0)" ::: "memory")
;     ...
;     for (int item = F.gw; item < nitems; item += F.NGW) { const int kb = item / nblk, nb = item % nblk, k0 = 64 * kb, n0 = 32 * nb;
;         int dr0 = n0; if (MAP == 1) { if (n0 < DFF) dr0 = (n0 >> 7) * 256 + (n0 & 127); else { const int uo = n0 - DFF; dr0 = (uo >> 7) * 256 + 128 + (uo & 127); } }
; #pragma unroll 8
;         for (int i = 0; i < 32; ++i) { const int kk = 2 * i + (lane >> 5); scr[kk * 33 + (lane & 31)] = W[(size_t)(k0 + kk) * ldw + n0 + (lane & 31)]; }
;         LDS_WAIT(); asm volatile("" ::: "memory");
;         const int c = lane & 3;
; #pragma unroll
;         for (int j = 0; j < 2; ++j) { const int n = (lane >> 2) + 16 * j; const LAS float* sp = scr + (16 * c) * 33 + n;
;             u32x4 o;
;             if (QI8) { o.x = pk4_i8(sp[0 * 33], sp[1 * 33], sp[2 * 33], sp[3 * 33], scl); o.y = pk4_i8(sp[4 * 33], sp[5 * 33], sp[6 * 33], sp[7 * 33], scl);
;                 o.z = pk4_i8(sp[8 * 33], sp[9 * 33], sp[10 * 33], sp[11 * 33], scl); o.w = pk4_i8(sp[12 * 33], sp[13 * 33], sp[14 * 33], sp[15 * 33], scl); }
;             else {
;             o.x = pk4_f8(sp[0 * 33] * scl, sp[1 * 33] * scl, sp[2 * 33] * scl, sp[3 * 33] * scl); o.y = pk4_f8(sp[4 * 33] * scl, sp[5 * 33] * scl, sp[6 * 33] * scl, sp[7 * 33] * scl);
;             o.z = pk4_f8(sp[8 * 33] * scl, sp[9 * 33] * scl, sp[10 * 33] * scl, sp[11 * 33] * scl); o.w = pk4_f8(sp[12 * 33] * scl, sp[13 * 33] * scl, sp[14 * 33] * scl, sp[15 * 33] * scl); }
;             *(u32x4*)(WT + (size_t)(dr0 + n) * K + k0 + 16 * c) = o; }
;         LDS_WAIT(); asm volatile("" ::: "memory"); }
	v_pk_add_f32 v[26:27], v[26:27], s[38:39] op_sel_hi:[1,0]
	v_pk_add_f32 v[28:29], v[28:29], s[38:39] op_sel_hi:[1,0]
	v_pk_add_f32 v[30:31], v[30:31], s[38:39] op_sel_hi:[1,0]
	v_pk_add_f32 v[32:33], v[32:33], s[38:39] op_sel_hi:[1,0]
	v_pk_add_f32 v[34:35], v[34:35], s[38:39] op_sel_hi:[1,0]
	v_pk_add_f32 v[36:37], v[36:37], s[38:39] op_sel_hi:[1,0]
	v_pk_add_f32 v[38:39], v[38:39], s[38:39] op_sel_hi:[1,0]
	v_pk_add_f32 v[40:41], v[40:41], s[38:39] op_sel_hi:[1,0]
	v_pk_add_f32 v[42:43], v[42:43], s[38:39] op_sel_hi:[1,0]
	v_pk_add_f32 v[44:45], v[44:45], s[38:39] op_sel_hi:[1,0]
	v_pk_add_f32 v[46:47], v[46:47], s[38:39] op_sel_hi:[1,0]
	v_pk_add_f32 v[48:49], v[48:49], s[38:39] op_sel_hi:[1,0]
	v_pk_add_f32 v[50:51], v[50:51], s[38:39] op_sel_hi:[1,0]
	v_pk_add_f32 v[52:53], v[52:53], s[38:39] op_sel_hi:[1,0]
	v_pk_add_f32 v[54:55], v[54:55], s[38:39] op_sel_hi:[1,0]
	v_pk_add_f32 v[56:57], v[56:57], s[38:39] op_sel_hi:[1,0]
	v_pk_add_f32 v[58:59], v[58:59], s[38:39] op_sel_hi:[1,0]
	v_pk_add_f32 v[60:61], v[60:61], s[38:39] op_sel_hi:[1,0]
	v_pk_add_f32 v[62:63], v[62:63], s[38:39] op_sel_hi:[1,0]
	v_pk_add_f32 v[64:65], v[64:65], s[38:39] op_sel_hi:[1,0]
	v_pk_add_f32 v[66:67], v[66:67], s[38:39] op_sel_hi:[1,0]
	v_pk_add_f32 v[68:69], v[68:69], s[38:39] op_sel_hi:[1,0]
	v_pk_add_f32 v[70:71], v[70:71], s[38:39] op_sel_hi:[1,0]
	v_pk_add_f32 v[144:145], v[144:145], s[38:39] op_sel_hi:[1,0]
	v_pk_add_f32 v[146:147], v[146:147], s[38:39] op_sel_hi:[1,0]
	v_pk_add_f32 v[148:149], v[148:149], s[38:39] op_sel_hi:[1,0]
	v_pk_add_f32 v[150:151], v[150:151], s[38:39] op_sel_hi:[1,0]
	v_perm_b32 v204, v20, v16, s41
	v_perm_b32 v205, v28, v24, s41
	v_perm_b32 v184, v205, v204, s42
	v_perm_b32 v204, v36, v32, s41
	v_perm_b32 v205, v44, v40, s41
	v_perm_b32 v185, v205, v204, s42
	v_perm_b32 v204, v52, v48, s41
	v_perm_b32 v205, v60, v56, s41
	v_perm_b32 v186, v205, v204, s42
	v_perm_b32 v204, v68, v64, s41
	v_perm_b32 v205, v148, v144, s41
	v_perm_b32 v187, v205, v204, s42
	v_perm_b32 v204, v21, v17, s41
	v_perm_b32 v205, v29, v25, s41
	v_perm_b32 v188, v205, v204, s42
	v_perm_b32 v204, v37, v33, s41
	v_perm_b32 v205, v45, v41, s41
	v_perm_b32 v189, v205, v204, s42
	v_perm_b32 v204, v53, v49, s41
	v_perm_b32 v205, v61, v57, s41
	v_perm_b32 v190, v205, v204, s42
	v_perm_b32 v204, v69, v65, s41
	v_perm_b32 v205, v149, v145, s41
	v_perm_b32 v191, v205, v204, s42
	v_perm_b32 v204, v22, v18, s41
	v_perm_b32 v205, v30, v26, s41
	v_perm_b32 v192, v205, v204, s42
	v_perm_b32 v204, v38, v34, s41
	v_perm_b32 v205, v46, v42, s41
	v_perm_b32 v193, v205, v204, s42
	v_perm_b32 v204, v54, v50, s41
	v_perm_b32 v205, v62, v58, s41
	v_perm_b32 v194, v205, v204, s42
	v_perm_b32 v204, v70, v66, s41
	v_perm_b32 v205, v150, v146, s41
	v_perm_b32 v195, v205, v204, s42
	v_perm_b32 v204, v23, v19, s41
	v_perm_b32 v205, v31, v27, s41
	v_perm_b32 v196, v205, v204, s42
	v_perm_b32 v204, v39, v35, s41
	v_perm_b32 v205, v47, v43, s41
	v_perm_b32 v197, v205, v204, s42
	v_perm_b32 v204, v55, v51, s41
	v_perm_b32 v205, v63, v59, s41
	v_perm_b32 v198, v205, v204, s42
	v_perm_b32 v204, v71, v67, s41
	v_perm_b32 v205, v151, v147, s41
	v_perm_b32 v199, v205, v204, s42
	ds_write_b128 v213, v[184:187] offset:36864
	ds_write_b128 v213, v[188:191] offset:37008
	ds_write_b128 v213, v[192:195] offset:37152
	ds_write_b128 v213, v[196:199] offset:37296
	s_lshl_b32 s26, s63, 1
	s_add_i32 s27, s26, 0xffffaa80
	s_cmp_lt_u32 s63, 0x2b00
	s_cselect_b32 s26, s26, s27
	s_add_i32 s26, s26, s17
	s_mul_i32 s26, s26, 0x1000
	s_add_u32 s26, s26, s62
	s_add_u32 s54, s44, s26
	s_addc_u32 s55, s45, 0
	s_waitcnt lgkmcnt(0)
	s_barrier
	ds_read_b128 v[184:187], v214 offset:36864
	ds_read_b128 v[188:191], v214 offset:38016
	ds_read_b128 v[192:195], v214 offset:39168
	ds_read_b128 v[196:199], v214 offset:40320
	s_waitcnt lgkmcnt(3)
	global_store_dwordx4 v215, v[184:187], s[54:55]
	s_add_u32 s54, s54, 0x8000
	s_addc_u32 s55, s55, 0
	s_waitcnt lgkmcnt(2)
	global_store_dwordx4 v215, v[188:191], s[54:55]
	s_add_u32 s54, s54, 0x8000
	s_addc_u32 s55, s55, 0
	s_waitcnt lgkmcnt(1)
	global_store_dwordx4 v215, v[192:195], s[54:55]
	s_add_u32 s54, s54, 0x8000
	s_addc_u32 s55, s55, 0
	s_waitcnt lgkmcnt(0)
	global_store_dwordx4 v215, v[196:199], s[54:55]
	s_mov_b32 s19, s59
	s_cmp_lt_u32 s19, 0xac0
	s_cbranch_scc1 .Lf8t_f1in0_loop

; #define LAS __attribute__((address_space(3)))
; #define LDS_WAIT() asm volatile("s_waitcnt lgkmcnt(0)" ::: "memory")
;     if (ldw == 0) ldw = N;
;     LAS float* scr = (LAS float*)(F.lds + F.wave * 16384); const int lane = F.lane;
;     const int nblk = N / 32, nitems = (K / 64) * nblk;
;     for (int item = F.gw; item < nitems; item += F.NGW) { const int kb = item / nblk, nb = item % nblk, k0 = 64 * kb, n0 = 32 * nb;
;         int dr0 = n0; if (MAP == 1) { if (n0 < DFF) dr0 = (n0 >> 7) * 256 + (n0 & 127); else { const int uo = n0 - DFF; dr0 = (uo >> 7) * 256 + 128 + (uo & 127); } }
; #pragma unroll 8
;         for (int i = 0; i < 32; ++i) { const int kk = 2 * i + (lane >> 5); scr[kk * 33 + (lane & 31)] = W[(size_t)(k0 + kk) * ldw + n0 + (lane & 31)]; }
;         LDS_WAIT(); asm volatile("" ::: "memory");
; __device__ __forceinline__ void p0_prologue(Frame& F) {
;     ...
;     transpose_f8_matrix<0>(F, F.in[I_F1DN], DFF, D, F.ws + WS_WFD, pg8::W8SCALE_DN);
.LBB0_22:
.LBB0_23:
	s_barrier
	s_load_dwordx2 s[50:51], s[74:75], 0x40
	v_readlane_b32 s16, v240, 2
	v_lshlrev_b32_e32 v212, 4, v178
	v_mov_b32_e32 v216, 0x42fe0000
	s_mov_b32 s36, 0x43000000
	s_mov_b32 s37, 0
	s_mov_b32 s38, 0x4b400000
	s_mov_b32 s39, 0
	s_mov_b32 s40, 0xc2fe0000
	s_mov_b32 s41, 0x0c0c0400
	s_mov_b32 s42, 0x05040100
	s_lshl_b32 s17, s16, 5
	v_mul_u32_u24_e32 v213, 0x240, v178
	s_lshl_b32 s18, s16, 4
	v_add_u32_e32 v213, s18, v213
	v_lshrrev_b32_e32 v204, 3, v178
	v_and_b32_e32 v205, 7, v178
	s_lshl_b32 s18, s16, 5
	v_add_u32_e32 v206, s18, v204
	v_mul_u32_u24_e32 v214, 0x90, v206
	v_lshl_add_u32 v214, v205, 4, v214
	v_mul_u32_u24_e32 v215, 0x2b00, v204
	v_lshl_add_u32 v215, v205, 4, v215
	s_lshl_b32 s16, s16, 4
	s_waitcnt lgkmcnt(0)
	s_add_u32 s44, s90, 0x12f00000
	s_addc_u32 s45, s91, 0
	s_mov_b32 s19, s2
	s_cmp_lt_u32 s19, 0x560
	s_cbranch_scc0 .Lf8t_f1dn0_end
	s_mul_hi_u32 s20, s19, 0x10000000
	s_mul_i32 s21, s20, 16
	s_sub_i32 s21, s19, s21
	s_lshl_b32 s60, s20, 7
	s_lshl_b32 s61, s21, 8
	s_add_i32 s24, s60, s16
	s_mul_i32 s24, s24, 0x4000
	s_lshl_b32 s25, s61, 2
	s_add_u32 s24, s24, s25
	s_add_u32 s52, s50, s24
	s_addc_u32 s53, s51, 0
	global_load_dwordx4 v[80:83], v212, s[52:53]
	s_add_u32 s52, s52, 0x4000
	s_addc_u32 s53, s53, 0
	global_load_dwordx4 v[84:87], v212, s[52:53]
	s_add_u32 s52, s52, 0x4000
	s_addc_u32 s53, s53, 0
	global_load_dwordx4 v[88:91], v212, s[52:53]
	s_add_u32 s52, s52, 0x4000
	s_addc_u32 s53, s53, 0
	global_load_dwordx4 v[92:95], v212, s[52:53]
	s_add_u32 s52, s52, 0x4000
	s_addc_u32 s53, s53, 0
	global_load_dwordx4 v[96:99], v212, s[52:53]
	s_add_u32 s52, s52, 0x4000
	s_addc_u32 s53, s53, 0
	global_load_dwordx4 v[100:103], v212, s[52:53]
	s_add_u32 s52, s52, 0x4000
	s_addc_u32 s53, s53, 0
	global_load_dwordx4 v[104:107], v212, s[52:53]
	s_add_u32 s52, s52, 0x4000
	s_addc_u32 s53, s53, 0
	global_load_dwordx4 v[108:111], v212, s[52:53]
	s_add_u32 s52, s52, 0x4000
	s_addc_u32 s53, s53, 0
	global_load_dwordx4 v[112:115], v212, s[52:53]
	s_add_u32 s52, s52, 0x4000
	s_addc_u32 s53, s53, 0
	global_load_dwordx4 v[116:119], v212, s[52:53]
	s_add_u32 s52, s52, 0x4000
	s_addc_u32 s53, s53, 0
	global_load_dwordx4 v[120:123], v212, s[52:53]
	s_add_u32 s52, s52, 0x4000
	s_addc_u32 s53, s53, 0
	global_load_dwordx4 v[124:127], v212, s[52:53]
	s_add_u32 s52, s52, 0x4000
	s_addc_u32 s53, s53, 0
	global_load_dwordx4 v[128:131], v212, s[52:53]
	s_add_u32 s52, s52, 0x4000
	s_addc_u32 s53, s53, 0
	global_load_dwordx4 v[132:135], v212, s[52:53]
	s_add_u32 s52, s52, 0x4000
	s_addc_u32 s53, s53, 0
	global_load_dwordx4 v[136:139], v212, s[52:53]
	s_add_u32 s52, s52, 0x4000
	s_addc_u32 s53, s53, 0
	global_load_dwordx4 v[140:143], v212, s[52:53]
	s_mov_b32 s58, 1
.Lf8t_f1dn0_loop:
	s_add_i32 s59, s19, s96
	s_cmp_lt_u32 s59, 0x560
	s_cbranch_scc0 .Lf8t_f1dn0_a_nonext
	s_mul_hi_u32 s20, s59, 0x10000000
	s_mul_i32 s21, s20, 16
	s_sub_i32 s21, s59, s21
	s_lshl_b32 s62, s20, 7
	s_lshl_b32 s63, s21, 8
	s_add_i32 s24, s62, s16
	s_mul_i32 s24, s24, 0x4000
	s_lshl_b32 s25, s63, 2
	s_add_u32 s24, s24, s25
	s_add_u32 s52, s50, s24
	s_addc_u32 s53, s51, 0
	global_load_dwordx4 v[16:19], v212, s[52:53]
	s_add_u32 s52, s52, 0x4000
	s_addc_u32 s53, s53, 0
	global_load_dwordx4 v[20:23], v212, s[52:53]
	s_add_u32 s52, s52, 0x4000
	s_addc_u32 s53, s53, 0
	global_load_dwordx4 v[24:27], v212, s[52:53]
	s_add_u32 s52, s52, 0x4000
	s_addc_u32 s53, s53, 0
	global_load_dwordx4 v[28:31], v212, s[52:53]
	s_add_u32 s52, s52, 0x4000
	s_addc_u32 s53, s53, 0
	global_load_dwordx4 v[32:35], v212, s[52:53]
	s_add_u32 s52, s52, 0x4000
	s_addc_u32 s53, s53, 0
	global_load_dwordx4 v[36:39], v212, s[52:53]
	s_add_u32 s52, s52, 0x4000
	s_addc_u32 s53, s53, 0
	global_load_dwordx4 v[40:43], v212, s[52:53]
	s_add_u32 s52, s52, 0x4000
	s_addc_u32 s53, s53, 0
	global_load_dwordx4 v[44:47], v212, s[52:53]
	s_add_u32 s52, s52, 0x4000
	s_addc_u32 s53, s53, 0
	global_load_dwordx4 v[48:51], v212, s[52:53]
	s_add_u32 s52, s52, 0x4000
	s_addc_u32 s53, s53, 0
	global_load_dwordx4 v[52:55], v212, s[52:53]
	s_add_u32 s52, s52, 0x4000
	s_addc_u32 s53, s53, 0
	global_load_dwordx4 v[56:59], v212, s[52:53]
	s_add_u32 s52, s52, 0x4000
	s_addc_u32 s53, s53, 0
	global_load_dwordx4 v[60:63], v212, s[52:53]
	s_add_u32 s52, s52, 0x4000
	s_addc_u32 s53, s53, 0
	global_load_dwordx4 v[64:67], v212, s[52:53]
	s_add_u32 s52, s52, 0x4000
	s_addc_u32 s53, s53, 0
	global_load_dwordx4 v[68:71], v212, s[52:53]
	s_add_u32 s52, s52, 0x4000
	s_addc_u32 s53, s53, 0
	global_load_dwordx4 v[144:147], v212, s[52:53]
	s_add_u32 s52, s52, 0x4000
	s_addc_u32 s53, s53, 0
	global_load_dwordx4 v[148:151], v212, s[52:53]
	s_cmp_eq_u32 s58, 1
	s_cbranch_scc1 .Lf8t_f1dn0_a_first
	s_waitcnt vmcnt(20)
	s_branch .Lf8t_f1dn0_a_go

; #define LAS __attribute__((address_space(3)))
; __device__ __forceinline__ unsigned pk4_f8(float a, float b, float c, float d) { int w = __builtin_amdgcn_cvt_pk_fp8_f32(a, b, 0, false); w = __builtin_amdgcn_cvt_pk_fp8_f32(c, d, w, true); return (unsigned)w; }
; #define LDS_WAIT() asm volatile("s_waitcnt lgkmcnt(0)" ::: "memory")
;     ...
;         for (int j = 0; j < 2; ++j) { const int n = (lane >> 2) + 16 * j; const LAS float* sp = scr + (16 * c) * 33 + n;
;             u32x4 o;
;             if (QI8) { o.x = pk4_i8(sp[0 * 33], sp[1 * 33], sp[2 * 33], sp[3 * 33], scl); o.y = pk4_i8(sp[4 * 33], sp[5 * 33], sp[6 * 33], sp[7 * 33], scl);
;                 o.z = pk4_i8(sp[8 * 33], sp[9 * 33], sp[10 * 33], sp[11 * 33], scl); o.w = pk4_i8(sp[12 * 33], sp[13 * 33], sp[14 * 33], sp[15 * 33], scl); }
;             else {
;             o.x = pk4_f8(sp[0 * 33] * scl, sp[1 * 33] * scl, sp[2 * 33] * scl, sp[3 * 33] * scl); o.y = pk4_f8(sp[4 * 33] * scl, sp[5 * 33] * scl, sp[6 * 33] * scl, sp[7 * 33] * scl);
;             o.z = pk4_f8(sp[8 * 33] * scl, sp[9 * 33] * scl, sp[10 * 33] * scl, sp[11 * 33] * scl); o.w = pk4_f8(sp[12 * 33] * scl, sp[13 * 33] * scl, sp[14 * 33] * scl, sp[15 * 33] * scl); }
;             *(u32x4*)(WT + (size_t)(dr0 + n) * K + k0 + 16 * c) = o; }
;         LDS_WAIT(); asm volatile("" ::: "memory"); }
.Lf8t_f1dn0_a_go:
	s_mov_b32 s58, 0
	v_pk_mul_f32 v[80:81], v[80:81], s[36:37] op_sel_hi:[1,0]
	v_pk_mul_f32 v[82:83], v[82:83], s[36:37] op_sel_hi:[1,0]
	v_pk_mul_f32 v[84:85], v[84:85], s[36:37] op_sel_hi:[1,0]
	v_pk_mul_f32 v[86:87], v[86:87], s[36:37] op_sel_hi:[1,0]
	v_pk_mul_f32 v[88:89], v[88:89], s[36:37] op_sel_hi:[1,0]
	v_pk_mul_f32 v[90:91], v[90:91], s[36:37] op_sel_hi:[1,0]
	v_pk_mul_f32 v[92:93], v[92:93], s[36:37] op_sel_hi:[1,0]
	v_pk_mul_f32 v[94:95], v[94:95], s[36:37] op_sel_hi:[1,0]
	v_pk_mul_f32 v[96:97], v[96:97], s[36:37] op_sel_hi:[1,0]
	v_pk_mul_f32 v[98:99], v[98:99], s[36:37] op_sel_hi:[1,0]
	v_pk_mul_f32 v[100:101], v[100:101], s[36:37] op_sel_hi:[1,0]
	v_pk_mul_f32 v[102:103], v[102:103], s[36:37] op_sel_hi:[1,0]
	v_pk_mul_f32 v[104:105], v[104:105], s[36:37] op_sel_hi:[1,0]
	v_pk_mul_f32 v[106:107], v[106:107], s[36:37] op_sel_hi:[1,0]
	v_pk_mul_f32 v[108:109], v[108:109], s[36:37] op_sel_hi:[1,0]
	v_pk_mul_f32 v[110:111], v[110:111], s[36:37] op_sel_hi:[1,0]
	v_pk_mul_f32 v[112:113], v[112:113], s[36:37] op_sel_hi:[1,0]
	v_pk_mul_f32 v[114:115], v[114:115], s[36:37] op_sel_hi:[1,0]
	v_pk_mul_f32 v[116:117], v[116:117], s[36:37] op_sel_hi:[1,0]
	v_pk_mul_f32 v[118:119], v[118:119], s[36:37] op_sel_hi:[1,0]
	v_pk_mul_f32 v[120:121], v[120:121], s[36:37] op_sel_hi:[1,0]
	v_pk_mul_f32 v[122:123], v[122:123], s[36:37] op_sel_hi:[1,0]
	v_pk_mul_f32 v[124:125], v[124:125], s[36:37] op_sel_hi:[1,0]
	v_pk_mul_f32 v[126:127], v[126:127], s[36:37] op_sel_hi:[1,0]
	v_pk_mul_f32 v[128:129], v[128:129], s[36:37] op_sel_hi:[1,0]
	v_pk_mul_f32 v[130:131], v[130:131], s[36:37] op_sel_hi:[1,0]
	v_pk_mul_f32 v[132:133], v[132:133], s[36:37] op_sel_hi:[1,0]
	v_pk_mul_f32 v[134:135], v[134:135], s[36:37] op_sel_hi:[1,0]
	v_pk_mul_f32 v[136:137], v[136:137], s[36:37] op_sel_hi:[1,0]
	v_pk_mul_f32 v[138:139], v[138:139], s[36:37] op_sel_hi:[1,0]
	v_pk_mul_f32 v[140:141], v[140:141], s[36:37] op_sel_hi:[1,0]
	v_pk_mul_f32 v[142:143], v[142:143], s[36:37] op_sel_hi:[1,0]
	v_cvt_pk_fp8_f32 v184, v80, v84
	v_cvt_pk_fp8_f32 v184, v88, v92 op_sel:[0,0,1]
	v_cvt_pk_fp8_f32 v185, v96, v100
	v_cvt_pk_fp8_f32 v185, v104, v108 op_sel:[0,0,1]
	v_cvt_pk_fp8_f32 v186, v112, v116
	v_cvt_pk_fp8_f32 v186, v120, v124 op_sel:[0,0,1]
	v_cvt_pk_fp8_f32 v187, v128, v132
	v_cvt_pk_fp8_f32 v187, v136, v140 op_sel:[0,0,1]
	v_cvt_pk_fp8_f32 v188, v81, v85
	v_cvt_pk_fp8_f32 v188, v89, v93 op_sel:[0,0,1]
	v_cvt_pk_fp8_f32 v189, v97, v101
	v_cvt_pk_fp8_f32 v189, v105, v109 op_sel:[0,0,1]
	v_cvt_pk_fp8_f32 v190, v113, v117
	v_cvt_pk_fp8_f32 v190, v121, v125 op_sel:[0,0,1]
	v_cvt_pk_fp8_f32 v191, v129, v133
	v_cvt_pk_fp8_f32 v191, v137, v141 op_sel:[0,0,1]
	v_cvt_pk_fp8_f32 v192, v82, v86
	v_cvt_pk_fp8_f32 v192, v90, v94 op_sel:[0,0,1]
	v_cvt_pk_fp8_f32 v193, v98, v102
	v_cvt_pk_fp8_f32 v193, v106, v110 op_sel:[0,0,1]
	v_cvt_pk_fp8_f32 v194, v114, v118
	v_cvt_pk_fp8_f32 v194, v122, v126 op_sel:[0,0,1]
	v_cvt_pk_fp8_f32 v195, v130, v134
	v_cvt_pk_fp8_f32 v195, v138, v142 op_sel:[0,0,1]
	v_cvt_pk_fp8_f32 v196, v83, v87
	v_cvt_pk_fp8_f32 v196, v91, v95 op_sel:[0,0,1]
	v_cvt_pk_fp8_f32 v197, v99, v103
	v_cvt_pk_fp8_f32 v197, v107, v111 op_sel:[0,0,1]
	v_cvt_pk_fp8_f32 v198, v115, v119
	v_cvt_pk_fp8_f32 v198, v123, v127 op_sel:[0,0,1]
	v_cvt_pk_fp8_f32 v199, v131, v135
	v_cvt_pk_fp8_f32 v199, v139, v143 op_sel:[0,0,1]
	ds_write_b128 v213, v[184:187] offset:0
	ds_write_b128 v213, v[188:191] offset:144
	ds_write_b128 v213, v[192:195] offset:288
	ds_write_b128 v213, v[196:199] offset:432
	s_mov_b32 s26, s61
	s_add_i32 s26, s26, s17
	s_mul_i32 s26, s26, 0x2b00
	s_add_u32 s26, s26, s60
	s_add_u32 s54, s44, s26
	s_addc_u32 s55, s45, 0
	s_waitcnt lgkmcnt(0)
	s_barrier
	ds_read_b128 v[184:187], v214 offset:0
	ds_read_b128 v[188:191], v214 offset:1152
	ds_read_b128 v[192:195], v214 offset:2304
	ds_read_b128 v[196:199], v214 offset:3456
	s_waitcnt lgkmcnt(3)
	global_store_dwordx4 v215, v[184:187], s[54:55]
	s_add_u32 s54, s54, 0x15800
	s_addc_u32 s55, s55, 0
	s_waitcnt lgkmcnt(2)
	global_store_dwordx4 v215, v[188:191], s[54:55]
	s_add_u32 s54, s54, 0x15800
	s_addc_u32 s55, s55, 0
	s_waitcnt lgkmcnt(1)
	global_store_dwordx4 v215, v[192:195], s[54:55]
	s_add_u32 s54, s54, 0x15800
	s_addc_u32 s55, s55, 0
	s_waitcnt lgkmcnt(0)
	global_store_dwordx4 v215, v[196:199], s[54:55]
	s_mov_b32 s19, s59
	s_cmp_lt_u32 s19, 0x560
	s_cbranch_scc0 .Lf8t_f1dn0_end
	s_add_i32 s59, s19, s96
	s_cmp_lt_u32 s59, 0x560
	s_cbranch_scc0 .Lf8t_f1dn0_b_nonext
	s_mul_hi_u32 s20, s59, 0x10000000
	s_mul_i32 s21, s20, 16
	s_sub_i32 s21, s59, s21
	s_lshl_b32 s60, s20, 7
	s_lshl_b32 s61, s21, 8
	s_add_i32 s24, s60, s16
	s_mul_i32 s24, s24, 0x4000
	s_lshl_b32 s25, s61, 2
	s_add_u32 s24, s24, s25
	s_add_u32 s52, s50, s24
	s_addc_u32 s53, s51, 0
	global_load_dwordx4 v[80:83], v212, s[52:53]
	s_add_u32 s52, s52, 0x4000
	s_addc_u32 s53, s53, 0
	global_load_dwordx4 v[84:87], v212, s[52:53]
	s_add_u32 s52, s52, 0x4000
	s_addc_u32 s53, s53, 0
	global_load_dwordx4 v[88:91], v212, s[52:53]
	s_add_u32 s52, s52, 0x4000
	s_addc_u32 s53, s53, 0
	global_load_dwordx4 v[92:95], v212, s[52:53]
	s_add_u32 s52, s52, 0x4000
	s_addc_u32 s53, s53, 0
	global_load_dwordx4 v[96:99], v212, s[52:53]
	s_add_u32 s52, s52, 0x4000
	s_addc_u32 s53, s53, 0
	global_load_dwordx4 v[100:103], v212, s[52:53]
	s_add_u32 s52, s52, 0x4000
	s_addc_u32 s53, s53, 0
	global_load_dwordx4 v[104:107], v212, s[52:53]
	s_add_u32 s52, s52, 0x4000
	s_addc_u32 s53, s53, 0
	global_load_dwordx4 v[108:111], v212, s[52:53]
	s_add_u32 s52, s52, 0x4000
	s_addc_u32 s53, s53, 0
	global_load_dwordx4 v[112:115], v212, s[52:53]
	s_add_u32 s52, s52, 0x4000
	s_addc_u32 s53, s53, 0
	global_load_dwordx4 v[116:119], v212, s[52:53]
	s_add_u32 s52, s52, 0x4000
	s_addc_u32 s53, s53, 0
	global_load_dwordx4 v[120:123], v212, s[52:53]
	s_add_u32 s52, s52, 0x4000
	s_addc_u32 s53, s53, 0
	global_load_dwordx4 v[124:127], v212, s[52:53]
	s_add_u32 s52, s52, 0x4000
	s_addc_u32 s53, s53, 0
	global_load_dwordx4 v[128:131], v212, s[52:53]
	s_add_u32 s52, s52, 0x4000
	s_addc_u32 s53, s53, 0
	global_load_dwordx4 v[132:135], v212, s[52:53]
	s_add_u32 s52, s52, 0x4000
	s_addc_u32 s53, s53, 0
	global_load_dwordx4 v[136:139], v212, s[52:53]
	s_add_u32 s52, s52, 0x4000
	s_addc_u32 s53, s53, 0
	global_load_dwordx4 v[140:143], v212, s[52:53]
	s_waitcnt vmcnt(20)
	s_branch .Lf8t_f1dn0_b_go

; #define LAS __attribute__((address_space(3)))
; __device__ __forceinline__ unsigned pk4_f8(float a, float b, float c, float d) { int w = __builtin_amdgcn_cvt_pk_fp8_f32(a, b, 0, false); w = __builtin_amdgcn_cvt_pk_fp8_f32(c, d, w, true); return (unsigned)w; }
; #define LDS_WAIT() asm volatile("s_waitcnt lgkmcnt(0)" ::: "memory")
;     ...
;         for (int j = 0; j < 2; ++j) { const int n = (lane >> 2) + 16 * j; const LAS float* sp = scr + (16 * c) * 33 + n;
;             u32x4 o;
;             if (QI8) { o.x = pk4_i8(sp[0 * 33], sp[1 * 33], sp[2 * 33], sp[3 * 33], scl); o.y = pk4_i8(sp[4 * 33], sp[5 * 33], sp[6 * 33], sp[7 * 33], scl);
;                 o.z = pk4_i8(sp[8 * 33], sp[9 * 33], sp[10 * 33], sp[11 * 33], scl); o.w = pk4_i8(sp[12 * 33], sp[13 * 33], sp[14 * 33], sp[15 * 33], scl); }
;             else {
;             o.x = pk4_f8(sp[0 * 33] * scl, sp[1 * 33] * scl, sp[2 * 33] * scl, sp[3 * 33] * scl); o.y = pk4_f8(sp[4 * 33] * scl, sp[5 * 33] * scl, sp[6 * 33] * scl, sp[7 * 33] * scl);
;             o.z = pk4_f8(sp[8 * 33] * scl, sp[9 * 33] * scl, sp[10 * 33] * scl, sp[11 * 33] * scl); o.w = pk4_f8(sp[12 * 33] * scl, sp[13 * 33] * scl, sp[14 * 33] * scl, sp[15 * 33] * scl); }
;             *(u32x4*)(WT + (size_t)(dr0 + n) * K + k0 + 16 * c) = o; }
;         LDS_WAIT(); asm volatile("" ::: "memory"); }
.Lf8t_f1dn0_b_go:
	v_pk_mul_f32 v[16:17], v[16:17], s[36:37] op_sel_hi:[1,0]
	v_pk_mul_f32 v[18:19], v[18:19], s[36:37] op_sel_hi:[1,0]
	v_pk_mul_f32 v[20:21], v[20:21], s[36:37] op_sel_hi:[1,0]
	v_pk_mul_f32 v[22:23], v[22:23], s[36:37] op_sel_hi:[1,0]
	v_pk_mul_f32 v[24:25], v[24:25], s[36:37] op_sel_hi:[1,0]
	v_pk_mul_f32 v[26:27], v[26:27], s[36:37] op_sel_hi:[1,0]
	v_pk_mul_f32 v[28:29], v[28:29], s[36:37] op_sel_hi:[1,0]
	v_pk_mul_f32 v[30:31], v[30:31], s[36:37] op_sel_hi:[1,0]
	v_pk_mul_f32 v[32:33], v[32:33], s[36:37] op_sel_hi:[1,0]
	v_pk_mul_f32 v[34:35], v[34:35], s[36:37] op_sel_hi:[1,0]
	v_pk_mul_f32 v[36:37], v[36:37], s[36:37] op_sel_hi:[1,0]
	v_pk_mul_f32 v[38:39], v[38:39], s[36:37] op_sel_hi:[1,0]
	v_pk_mul_f32 v[40:41], v[40:41], s[36:37] op_sel_hi:[1,0]
	v_pk_mul_f32 v[42:43], v[42:43], s[36:37] op_sel_hi:[1,0]
	v_pk_mul_f32 v[44:45], v[44:45], s[36:37] op_sel_hi:[1,0]
	v_pk_mul_f32 v[46:47], v[46:47], s[36:37] op_sel_hi:[1,0]
	v_pk_mul_f32 v[48:49], v[48:49], s[36:37] op_sel_hi:[1,0]
	v_pk_mul_f32 v[50:51], v[50:51], s[36:37] op_sel_hi:[1,0]
	v_pk_mul_f32 v[52:53], v[52:53], s[36:37] op_sel_hi:[1,0]
	v_pk_mul_f32 v[54:55], v[54:55], s[36:37] op_sel_hi:[1,0]
	v_pk_mul_f32 v[56:57], v[56:57], s[36:37] op_sel_hi:[1,0]
	v_pk_mul_f32 v[58:59], v[58:59], s[36:37] op_sel_hi:[1,0]
	v_pk_mul_f32 v[60:61], v[60:61], s[36:37] op_sel_hi:[1,0]
	v_pk_mul_f32 v[62:63], v[62:63], s[36:37] op_sel_hi:[1,0]
	v_pk_mul_f32 v[64:65], v[64:65], s[36:37] op_sel_hi:[1,0]
	v_pk_mul_f32 v[66:67], v[66:67], s[36:37] op_sel_hi:[1,0]
	v_pk_mul_f32 v[68:69], v[68:69], s[36:37] op_sel_hi:[1,0]
	v_pk_mul_f32 v[70:71], v[70:71], s[36:37] op_sel_hi:[1,0]
	v_pk_mul_f32 v[144:145], v[144:145], s[36:37] op_sel_hi:[1,0]
	v_pk_mul_f32 v[146:147], v[146:147], s[36:37] op_sel_hi:[1,0]
	v_pk_mul_f32 v[148:149], v[148:149], s[36:37] op_sel_hi:[1,0]
	v_pk_mul_f32 v[150:151], v[150:151], s[36:37] op_sel_hi:[1,0]
	v_cvt_pk_fp8_f32 v184, v16, v20
	v_cvt_pk_fp8_f32 v184, v24, v28 op_sel:[0,0,1]
	v_cvt_pk_fp8_f32 v185, v32, v36
	v_cvt_pk_fp8_f32 v185, v40, v44 op_sel:[0,0,1]
	v_cvt_pk_fp8_f32 v186, v48, v52
	v_cvt_pk_fp8_f32 v186, v56, v60 op_sel:[0,0,1]
	v_cvt_pk_fp8_f32 v187, v64, v68
	v_cvt_pk_fp8_f32 v187, v144, v148 op_sel:[0,0,1]
	v_cvt_pk_fp8_f32 v188, v17, v21
	v_cvt_pk_fp8_f32 v188, v25, v29 op_sel:[0,0,1]
	v_cvt_pk_fp8_f32 v189, v33, v37
	v_cvt_pk_fp8_f32 v189, v41, v45 op_sel:[0,0,1]
	v_cvt_pk_fp8_f32 v190, v49, v53
	v_cvt_pk_fp8_f32 v190, v57, v61 op_sel:[0,0,1]
	v_cvt_pk_fp8_f32 v191, v65, v69
	v_cvt_pk_fp8_f32 v191, v145, v149 op_sel:[0,0,1]
	v_cvt_pk_fp8_f32 v192, v18, v22
	v_cvt_pk_fp8_f32 v192, v26, v30 op_sel:[0,0,1]
	v_cvt_pk_fp8_f32 v193, v34, v38
	v_cvt_pk_fp8_f32 v193, v42, v46 op_sel:[0,0,1]
	v_cvt_pk_fp8_f32 v194, v50, v54
	v_cvt_pk_fp8_f32 v194, v58, v62 op_sel:[0,0,1]
	v_cvt_pk_fp8_f32 v195, v66, v70
	v_cvt_pk_fp8_f32 v195, v146, v150 op_sel:[0,0,1]
	v_cvt_pk_fp8_f32 v196, v19, v23
	v_cvt_pk_fp8_f32 v196, v27, v31 op_sel:[0,0,1]
	v_cvt_pk_fp8_f32 v197, v35, v39
	v_cvt_pk_fp8_f32 v197, v43, v47 op_sel:[0,0,1]
	v_cvt_pk_fp8_f32 v198, v51, v55
	v_cvt_pk_fp8_f32 v198, v59, v63 op_sel:[0,0,1]
	v_cvt_pk_fp8_f32 v199, v67, v71
	v_cvt_pk_fp8_f32 v199, v147, v151 op_sel:[0,0,1]
	ds_write_b128 v213, v[184:187] offset:36864
	ds_write_b128 v213, v[188:191] offset:37008
	ds_write_b128 v213, v[192:195] offset:37152
	ds_write_b128 v213, v[196:199] offset:37296
	s_mov_b32 s26, s63
	s_add_i32 s26, s26, s17
	s_mul_i32 s26, s26, 0x2b00
	s_add_u32 s26, s26, s62
	s_add_u32 s54, s44, s26
	s_addc_u32 s55, s45, 0
	s_waitcnt lgkmcnt(0)
	s_barrier
	ds_read_b128 v[184:187], v214 offset:36864
	ds_read_b128 v[188:191], v214 offset:38016
	ds_read_b128 v[192:195], v214 offset:39168
	ds_read_b128 v[196:199], v214 offset:40320
	s_waitcnt lgkmcnt(3)
	global_store_dwordx4 v215, v[184:187], s[54:55]
	s_add_u32 s54, s54, 0x15800
	s_addc_u32 s55, s55, 0
	s_waitcnt lgkmcnt(2)
	global_store_dwordx4 v215, v[188:191], s[54:55]
	s_add_u32 s54, s54, 0x15800
	s_addc_u32 s55, s55, 0
	s_waitcnt lgkmcnt(1)
	global_store_dwordx4 v215, v[192:195], s[54:55]
	s_add_u32 s54, s54, 0x15800
	s_addc_u32 s55, s55, 0
	s_waitcnt lgkmcnt(0)
	global_store_dwordx4 v215, v[196:199], s[54:55]
	s_mov_b32 s19, s59
	s_cmp_lt_u32 s19, 0x560
	s_cbranch_scc1 .Lf8t_f1dn0_loop

; #define LAS __attribute__((address_space(3)))
; #define LDS_WAIT() asm volatile("s_waitcnt lgkmcnt(0)" ::: "memory")
;     if (ldw == 0) ldw = N;
;     LAS float* scr = (LAS float*)(F.lds + F.wave * 16384); const int lane = F.lane;
;     const int nblk = N / 32, nitems = (K / 64) * nblk;
;     for (int item = F.gw; item < nitems; item += F.NGW) { const int kb = item / nblk, nb = item % nblk, k0 = 64 * kb, n0 = 32 * nb;
;         int dr0 = n0; if (MAP == 1) { if (n0 < DFF) dr0 = (n0 >> 7) * 256 + (n0 & 127); else { const int uo = n0 - DFF; dr0 = (uo >> 7) * 256 + 128 + (uo & 127); } }
; #pragma unroll 8
;         for (int i = 0; i < 32; ++i) { const int kk = 2 * i + (lane >> 5); scr[kk * 33 + (lane & 31)] = W[(size_t)(k0 + kk) * ldw + n0 + (lane & 31)]; }
;         LDS_WAIT(); asm volatile("" ::: "memory");
; __device__ __forceinline__ void p0_prologue(Frame& F) {
;     ...
;       transpose_f8_matrix<0, true>(F, W + 8192 + DRIN, D, 8192, w8, I8_W, ldw);
.LBB0_37:
	s_cmpk_gt_i32 s94, 0x3fff
	s_cbranch_scc1 .LBB0_42
	s_barrier
	s_load_dwordx2 s[50:51], s[74:75], 0x58
	v_readlane_b32 s16, v240, 2
	v_lshlrev_b32_e32 v212, 4, v178
	v_mov_b32_e32 v216, 0x42fe0000
	s_mov_b32 s36, 0x44fe0000
	s_mov_b32 s37, 0
	s_mov_b32 s38, 0x4b400000
	s_mov_b32 s39, 0
	s_mov_b32 s40, 0xc2fe0000
	s_mov_b32 s41, 0x0c0c0400
	s_mov_b32 s42, 0x05040100
	s_lshl_b32 s17, s16, 5
	v_mul_u32_u24_e32 v213, 0x240, v178
	s_lshl_b32 s18, s16, 4
	v_add_u32_e32 v213, s18, v213
	v_lshrrev_b32_e32 v204, 3, v178
	v_and_b32_e32 v205, 7, v178
	s_lshl_b32 s18, s16, 5
	v_add_u32_e32 v206, s18, v204
	v_mul_u32_u24_e32 v214, 0x90, v206
	v_lshl_add_u32 v214, v205, 4, v214
	v_mul_u32_u24_e32 v215, 0x1000, v204
	v_lshl_add_u32 v215, v205, 4, v215
	s_lshl_b32 s16, s16, 4
	s_waitcnt lgkmcnt(0)
	s_add_u32 s50, s50, 0xeb80
	s_addc_u32 s51, s51, 0
	s_add_u32 s44, s90, 0x35b00000
	s_addc_u32 s45, s91, 0
	s_mov_b32 s19, s2
	s_cmp_lt_u32 s19, 0x400
	s_cbranch_scc0 .Lf8t_win8a0_end
	s_mul_hi_u32 s20, s19, 0x8000000
	s_mul_i32 s21, s20, 32
	s_sub_i32 s21, s19, s21
	s_lshl_b32 s60, s20, 7
	s_lshl_b32 s61, s21, 8
	s_add_i32 s24, s60, s16
	s_mul_i32 s24, s24, 0x16b80
	s_lshl_b32 s25, s61, 2
	s_add_u32 s24, s24, s25
	s_add_u32 s52, s50, s24
	s_addc_u32 s53, s51, 0
	global_load_dwordx4 v[80:83], v212, s[52:53]
	s_add_u32 s52, s52, 0x16b80
	s_addc_u32 s53, s53, 0
	global_load_dwordx4 v[84:87], v212, s[52:53]
	s_add_u32 s52, s52, 0x16b80
	s_addc_u32 s53, s53, 0
	global_load_dwordx4 v[88:91], v212, s[52:53]
	s_add_u32 s52, s52, 0x16b80
	s_addc_u32 s53, s53, 0
	global_load_dwordx4 v[92:95], v212, s[52:53]
	s_add_u32 s52, s52, 0x16b80
	s_addc_u32 s53, s53, 0
	global_load_dwordx4 v[96:99], v212, s[52:53]
	s_add_u32 s52, s52, 0x16b80
	s_addc_u32 s53, s53, 0
	global_load_dwordx4 v[100:103], v212, s[52:53]
	s_add_u32 s52, s52, 0x16b80
	s_addc_u32 s53, s53, 0
	global_load_dwordx4 v[104:107], v212, s[52:53]
	s_add_u32 s52, s52, 0x16b80
	s_addc_u32 s53, s53, 0
	global_load_dwordx4 v[108:111], v212, s[52:53]
	s_add_u32 s52, s52, 0x16b80
	s_addc_u32 s53, s53, 0
	global_load_dwordx4 v[112:115], v212, s[52:53]
	s_add_u32 s52, s52, 0x16b80
	s_addc_u32 s53, s53, 0
	global_load_dwordx4 v[116:119], v212, s[52:53]
	s_add_u32 s52, s52, 0x16b80
	s_addc_u32 s53, s53, 0
	global_load_dwordx4 v[120:123], v212, s[52:53]
	s_add_u32 s52, s52, 0x16b80
	s_addc_u32 s53, s53, 0
	global_load_dwordx4 v[124:127], v212, s[52:53]
	s_add_u32 s52, s52, 0x16b80
	s_addc_u32 s53, s53, 0
	global_load_dwordx4 v[128:131], v212, s[52:53]
	s_add_u32 s52, s52, 0x16b80
	s_addc_u32 s53, s53, 0
	global_load_dwordx4 v[132:135], v212, s[52:53]
	s_add_u32 s52, s52, 0x16b80
	s_addc_u32 s53, s53, 0
	global_load_dwordx4 v[136:139], v212, s[52:53]
	s_add_u32 s52, s52, 0x16b80
	s_addc_u32 s53, s53, 0
	global_load_dwordx4 v[140:143], v212, s[52:53]
	s_mov_b32 s58, 1
.Lf8t_win8a0_loop:
	s_add_i32 s59, s19, s96
	s_cmp_lt_u32 s59, 0x400
	s_cbranch_scc0 .Lf8t_win8a0_a_nonext
	s_mul_hi_u32 s20, s59, 0x8000000
	s_mul_i32 s21, s20, 32
	s_sub_i32 s21, s59, s21
	s_lshl_b32 s62, s20, 7
	s_lshl_b32 s63, s21, 8
	s_add_i32 s24, s62, s16
	s_mul_i32 s24, s24, 0x16b80
	s_lshl_b32 s25, s63, 2
	s_add_u32 s24, s24, s25
	s_add_u32 s52, s50, s24
	s_addc_u32 s53, s51, 0
	global_load_dwordx4 v[16:19], v212, s[52:53]
	s_add_u32 s52, s52, 0x16b80
	s_addc_u32 s53, s53, 0
	global_load_dwordx4 v[20:23], v212, s[52:53]
	s_add_u32 s52, s52, 0x16b80
	s_addc_u32 s53, s53, 0
	global_load_dwordx4 v[24:27], v212, s[52:53]
	s_add_u32 s52, s52, 0x16b80
	s_addc_u32 s53, s53, 0
	global_load_dwordx4 v[28:31], v212, s[52:53]
	s_add_u32 s52, s52, 0x16b80
	s_addc_u32 s53, s53, 0
	global_load_dwordx4 v[32:35], v212, s[52:53]
	s_add_u32 s52, s52, 0x16b80
	s_addc_u32 s53, s53, 0
	global_load_dwordx4 v[36:39], v212, s[52:53]
	s_add_u32 s52, s52, 0x16b80
	s_addc_u32 s53, s53, 0
	global_load_dwordx4 v[40:43], v212, s[52:53]
	s_add_u32 s52, s52, 0x16b80
	s_addc_u32 s53, s53, 0
	global_load_dwordx4 v[44:47], v212, s[52:53]
	s_add_u32 s52, s52, 0x16b80
	s_addc_u32 s53, s53, 0
	global_load_dwordx4 v[48:51], v212, s[52:53]
	s_add_u32 s52, s52, 0x16b80
	s_addc_u32 s53, s53, 0
	global_load_dwordx4 v[52:55], v212, s[52:53]
	s_add_u32 s52, s52, 0x16b80
	s_addc_u32 s53, s53, 0
	global_load_dwordx4 v[56:59], v212, s[52:53]
	s_add_u32 s52, s52, 0x16b80
	s_addc_u32 s53, s53, 0
	global_load_dwordx4 v[60:63], v212, s[52:53]
	s_add_u32 s52, s52, 0x16b80
	s_addc_u32 s53, s53, 0
	global_load_dwordx4 v[64:67], v212, s[52:53]
	s_add_u32 s52, s52, 0x16b80
	s_addc_u32 s53, s53, 0
	global_load_dwordx4 v[68:71], v212, s[52:53]
	s_add_u32 s52, s52, 0x16b80
	s_addc_u32 s53, s53, 0
	global_load_dwordx4 v[144:147], v212, s[52:53]
	s_add_u32 s52, s52, 0x16b80
	s_addc_u32 s53, s53, 0
	global_load_dwordx4 v[148:151], v212, s[52:53]
	s_cmp_eq_u32 s58, 1
	s_cbranch_scc1 .Lf8t_win8a0_a_first
	s_waitcnt vmcnt(20)
	s_branch .Lf8t_win8a0_a_go

; #define LAS __attribute__((address_space(3)))
; __device__ __forceinline__ unsigned pk4_i8(float a, float b, float c, float d, float s) {
;     const unsigned ua = __float_as_uint(__builtin_amdgcn_fmed3f(a * s, -127.f, 127.f) + 12582912.f), ub = __float_as_uint(__builtin_amdgcn_fmed3f(b * s, -127.f, 127.f) + 12582912.f);
;     const unsigned uc = __float_as_uint(__builtin_amdgcn_fmed3f(c * s, -127.f, 127.f) + 12582912.f), ud = __float_as_uint(__builtin_amdgcn_fmed3f(d * s, -127.f, 127.f) + 12582912.f);
;     return (ua & 0xffu) | ((ub & 0xffu) << 8) | ((uc & 0xffu) << 16) | (ud << 24);
;     ...
;         for (int j = 0; j < 2; ++j) { const int n = (lane >> 2) + 16 * j; const LAS float* sp = scr + (16 * c) * 33 + n;
;             u32x4 o;
;             if (QI8) { o.x = pk4_i8(sp[0 * 33], sp[1 * 33], sp[2 * 33], sp[3 * 33], scl); o.y = pk4_i8(sp[4 * 33], sp[5 * 33], sp[6 * 33], sp[7 * 33], scl);
;                 o.z = pk4_i8(sp[8 * 33], sp[9 * 33], sp[10 * 33], sp[11 * 33], scl); o.w = pk4_i8(sp[12 * 33], sp[13 * 33], sp[14 * 33], sp[15 * 33], scl); }
.Lf8t_win8a0_a_go:
	s_mov_b32 s58, 0
	v_pk_mul_f32 v[80:81], v[80:81], s[36:37] op_sel_hi:[1,0]
	v_pk_mul_f32 v[82:83], v[82:83], s[36:37] op_sel_hi:[1,0]
	v_pk_mul_f32 v[84:85], v[84:85], s[36:37] op_sel_hi:[1,0]
	v_pk_mul_f32 v[86:87], v[86:87], s[36:37] op_sel_hi:[1,0]
	v_pk_mul_f32 v[88:89], v[88:89], s[36:37] op_sel_hi:[1,0]
	v_pk_mul_f32 v[90:91], v[90:91], s[36:37] op_sel_hi:[1,0]
	v_pk_mul_f32 v[92:93], v[92:93], s[36:37] op_sel_hi:[1,0]
	v_pk_mul_f32 v[94:95], v[94:95], s[36:37] op_sel_hi:[1,0]
	v_pk_mul_f32 v[96:97], v[96:97], s[36:37] op_sel_hi:[1,0]
	v_pk_mul_f32 v[98:99], v[98:99], s[36:37] op_sel_hi:[1,0]
	v_pk_mul_f32 v[100:101], v[100:101], s[36:37] op_sel_hi:[1,0]
	v_pk_mul_f32 v[102:103], v[102:103], s[36:37] op_sel_hi:[1,0]
	v_pk_mul_f32 v[104:105], v[104:105], s[36:37] op_sel_hi:[1,0]
	v_pk_mul_f32 v[106:107], v[106:107], s[36:37] op_sel_hi:[1,0]
	v_pk_mul_f32 v[108:109], v[108:109], s[36:37] op_sel_hi:[1,0]
	v_pk_mul_f32 v[110:111], v[110:111], s[36:37] op_sel_hi:[1,0]
	v_pk_mul_f32 v[112:113], v[112:113], s[36:37] op_sel_hi:[1,0]
	v_pk_mul_f32 v[114:115], v[114:115], s[36:37] op_sel_hi:[1,0]
	v_pk_mul_f32 v[116:117], v[116:117], s[36:37] op_sel_hi:[1,0]
	v_pk_mul_f32 v[118:119], v[118:119], s[36:37] op_sel_hi:[1,0]
	v_pk_mul_f32 v[120:121], v[120:121], s[36:37] op_sel_hi:[1,0]
	v_pk_mul_f32 v[122:123], v[122:123], s[36:37] op_sel_hi:[1,0]
	v_pk_mul_f32 v[124:125], v[124:125], s[36:37] op_sel_hi:[1,0]
	v_pk_mul_f32 v[126:127], v[126:127], s[36:37] op_sel_hi:[1,0]
	v_pk_mul_f32 v[128:129], v[128:129], s[36:37] op_sel_hi:[1,0]
	v_pk_mul_f32 v[130:131], v[130:131], s[36:37] op_sel_hi:[1,0]
	v_pk_mul_f32 v[132:133], v[132:133], s[36:37] op_sel_hi:[1,0]
	v_pk_mul_f32 v[134:135], v[134:135], s[36:37] op_sel_hi:[1,0]
	v_pk_mul_f32 v[136:137], v[136:137], s[36:37] op_sel_hi:[1,0]
	v_pk_mul_f32 v[138:139], v[138:139], s[36:37] op_sel_hi:[1,0]
	v_pk_mul_f32 v[140:141], v[140:141], s[36:37] op_sel_hi:[1,0]
	v_pk_mul_f32 v[142:143], v[142:143], s[36:37] op_sel_hi:[1,0]
	v_med3_f32 v80, v80, s40, v216
	v_med3_f32 v81, v81, s40, v216
	v_med3_f32 v82, v82, s40, v216
	v_med3_f32 v83, v83, s40, v216
	v_med3_f32 v84, v84, s40, v216
	v_med3_f32 v85, v85, s40, v216
	v_med3_f32 v86, v86, s40, v216
	v_med3_f32 v87, v87, s40, v216
	v_med3_f32 v88, v88, s40, v216
	v_med3_f32 v89, v89, s40, v216
	v_med3_f32 v90, v90, s40, v216
	v_med3_f32 v91, v91, s40, v216
	v_med3_f32 v92, v92, s40, v216
	v_med3_f32 v93, v93, s40, v216
	v_med3_f32 v94, v94, s40, v216
	v_med3_f32 v95, v95, s40, v216
	v_med3_f32 v96, v96, s40, v216
	v_med3_f32 v97, v97, s40, v216
	v_med3_f32 v98, v98, s40, v216
	v_med3_f32 v99, v99, s40, v216
	v_med3_f32 v100, v100, s40, v216
	v_med3_f32 v101, v101, s40, v216
	v_med3_f32 v102, v102, s40, v216
	v_med3_f32 v103, v103, s40, v216
	v_med3_f32 v104, v104, s40, v216
	v_med3_f32 v105, v105, s40, v216
	v_med3_f32 v106, v106, s40, v216
	v_med3_f32 v107, v107, s40, v216
	v_med3_f32 v108, v108, s40, v216
	v_med3_f32 v109, v109, s40, v216
	v_med3_f32 v110, v110, s40, v216
	v_med3_f32 v111, v111, s40, v216
	v_med3_f32 v112, v112, s40, v216
	v_med3_f32 v113, v113, s40, v216
	v_med3_f32 v114, v114, s40, v216
	v_med3_f32 v115, v115, s40, v216
	v_med3_f32 v116, v116, s40, v216
	v_med3_f32 v117, v117, s40, v216
	v_med3_f32 v118, v118, s40, v216
	v_med3_f32 v119, v119, s40, v216
	v_med3_f32 v120, v120, s40, v216
	v_med3_f32 v121, v121, s40, v216
	v_med3_f32 v122, v122, s40, v216
	v_med3_f32 v123, v123, s40, v216
	v_med3_f32 v124, v124, s40, v216
	v_med3_f32 v125, v125, s40, v216
	v_med3_f32 v126, v126, s40, v216
	v_med3_f32 v127, v127, s40, v216
	v_med3_f32 v128, v128, s40, v216
	v_med3_f32 v129, v129, s40, v216
	v_med3_f32 v130, v130, s40, v216
	v_med3_f32 v131, v131, s40, v216
	v_med3_f32 v132, v132, s40, v216
	v_med3_f32 v133, v133, s40, v216
	v_med3_f32 v134, v134, s40, v216
	v_med3_f32 v135, v135, s40, v216
	v_med3_f32 v136, v136, s40, v216
	v_med3_f32 v137, v137, s40, v216
	v_med3_f32 v138, v138, s40, v216
	v_med3_f32 v139, v139, s40, v216
	v_med3_f32 v140, v140, s40, v216
	v_med3_f32 v141, v141, s40, v216
	v_med3_f32 v142, v142, s40, v216
	v_med3_f32 v143, v143, s40, v216
	v_pk_add_f32 v[80:81], v[80:81], s[38:39] op_sel_hi:[1,0]
	v_pk_add_f32 v[82:83], v[82:83], s[38:39] op_sel_hi:[1,0]
	v_pk_add_f32 v[84:85], v[84:85], s[38:39] op_sel_hi:[1,0]
	v_pk_add_f32 v[86:87], v[86:87], s[38:39] op_sel_hi:[1,0]
	v_pk_add_f32 v[88:89], v[88:89], s[38:39] op_sel_hi:[1,0]
	v_pk_add_f32 v[90:91], v[90:91], s[38:39] op_sel_hi:[1,0]
	v_pk_add_f32 v[92:93], v[92:93], s[38:39] op_sel_hi:[1,0]
	v_pk_add_f32 v[94:95], v[94:95], s[38:39] op_sel_hi:[1,0]
	v_pk_add_f32 v[96:97], v[96:97], s[38:39] op_sel_hi:[1,0]
	v_pk_add_f32 v[98:99], v[98:99], s[38:39] op_sel_hi:[1,0]
	v_pk_add_f32 v[100:101], v[100:101], s[38:39] op_sel_hi:[1,0]
	v_pk_add_f32 v[102:103], v[102:103], s[38:39] op_sel_hi:[1,0]
	v_pk_add_f32 v[104:105], v[104:105], s[38:39] op_sel_hi:[1,0]
	v_pk_add_f32 v[106:107], v[106:107], s[38:39] op_sel_hi:[1,0]
	v_pk_add_f32 v[108:109], v[108:109], s[38:39] op_sel_hi:[1,0]
	v_pk_add_f32 v[110:111], v[110:111], s[38:39] op_sel_hi:[1,0]
	v_pk_add_f32 v[112:113], v[112:113], s[38:39] op_sel_hi:[1,0]
	v_pk_add_f32 v[114:115], v[114:115], s[38:39] op_sel_hi:[1,0]
	v_pk_add_f32 v[116:117], v[116:117], s[38:39] op_sel_hi:[1,0]
	v_pk_add_f32 v[118:119], v[118:119], s[38:39] op_sel_hi:[1,0]
; #define LAS __attribute__((address_space(3)))
; __device__ __forceinline__ unsigned pk4_f8(float a, float b, float c, float d) { int w = __builtin_amdgcn_cvt_pk_fp8_f32(a, b, 0, false); w = __builtin_amdgcn_cvt_pk_fp8_f32(c, d, w, true); return (unsigned)w; }
; #define LDS_WAIT() asm volatile("s_waitcnt lgkmcnt(0)" ::: "memory")
;     ...
;     for (int item = F.gw; item < nitems; item += F.NGW) { const int kb = item / nblk, nb = item % nblk, k0 = 64 * kb, n0 = 32 * nb;
;         int dr0 = n0; if (MAP == 1) { if (n0 < DFF) dr0 = (n0 >> 7) * 256 + (n0 & 127); else { const int uo = n0 - DFF; dr0 = (uo >> 7) * 256 + 128 + (uo & 127); } }
; #pragma unroll 8
;         for (int i = 0; i < 32; ++i) { const int kk = 2 * i + (lane >> 5); scr[kk * 33 + (lane & 31)] = W[(size_t)(k0 + kk) * ldw + n0 + (lane & 31)]; }
;         LDS_WAIT(); asm volatile("" ::: "memory");
;         const int c = lane & 3;
; #pragma unroll
;         for (int j = 0; j < 2; ++j) { const int n = (lane >> 2) + 16 * j; const LAS float* sp = scr + (16 * c) * 33 + n;
;             u32x4 o;
;             if (QI8) { o.x = pk4_i8(sp[0 * 33], sp[1 * 33], sp[2 * 33], sp[3 * 33], scl); o.y = pk4_i8(sp[4 * 33], sp[5 * 33], sp[6 * 33], sp[7 * 33], scl);
;                 o.z = pk4_i8(sp[8 * 33], sp[9 * 33], sp[10 * 33], sp[11 * 33], scl); o.w = pk4_i8(sp[12 * 33], sp[13 * 33], sp[14 * 33], sp[15 * 33], scl); }
;             else {
;             o.x = pk4_f8(sp[0 * 33] * scl, sp[1 * 33] * scl, sp[2 * 33] * scl, sp[3 * 33] * scl); o.y = pk4_f8(sp[4 * 33] * scl, sp[5 * 33] * scl, sp[6 * 33] * scl, sp[7 * 33] * scl);
;             o.z = pk4_f8(sp[8 * 33] * scl, sp[9 * 33] * scl, sp[10 * 33] * scl, sp[11 * 33] * scl); o.w = pk4_f8(sp[12 * 33] * scl, sp[13 * 33] * scl, sp[14 * 33] * scl, sp[15 * 33] * scl); }
;             *(u32x4*)(WT + (size_t)(dr0 + n) * K + k0 + 16 * c) = o; }
;         LDS_WAIT(); asm volatile("" ::: "memory"); }
	v_pk_add_f32 v[120:121], v[120:121], s[38:39] op_sel_hi:[1,0]
	v_pk_add_f32 v[122:123], v[122:123], s[38:39] op_sel_hi:[1,0]
	v_pk_add_f32 v[124:125], v[124:125], s[38:39] op_sel_hi:[1,0]
	v_pk_add_f32 v[126:127], v[126:127], s[38:39] op_sel_hi:[1,0]
	v_pk_add_f32 v[128:129], v[128:129], s[38:39] op_sel_hi:[1,0]
	v_pk_add_f32 v[130:131], v[130:131], s[38:39] op_sel_hi:[1,0]
	v_pk_add_f32 v[132:133], v[132:133], s[38:39] op_sel_hi:[1,0]
	v_pk_add_f32 v[134:135], v[134:135], s[38:39] op_sel_hi:[1,0]
	v_pk_add_f32 v[136:137], v[136:137], s[38:39] op_sel_hi:[1,0]
	v_pk_add_f32 v[138:139], v[138:139], s[38:39] op_sel_hi:[1,0]
	v_pk_add_f32 v[140:141], v[140:141], s[38:39] op_sel_hi:[1,0]
	v_pk_add_f32 v[142:143], v[142:143], s[38:39] op_sel_hi:[1,0]
	v_perm_b32 v204, v84, v80, s41
	v_perm_b32 v205, v92, v88, s41
	v_perm_b32 v184, v205, v204, s42
	v_perm_b32 v204, v100, v96, s41
	v_perm_b32 v205, v108, v104, s41
	v_perm_b32 v185, v205, v204, s42
	v_perm_b32 v204, v116, v112, s41
	v_perm_b32 v205, v124, v120, s41
	v_perm_b32 v186, v205, v204, s42
	v_perm_b32 v204, v132, v128, s41
	v_perm_b32 v205, v140, v136, s41
	v_perm_b32 v187, v205, v204, s42
	v_perm_b32 v204, v85, v81, s41
	v_perm_b32 v205, v93, v89, s41
	v_perm_b32 v188, v205, v204, s42
	v_perm_b32 v204, v101, v97, s41
	v_perm_b32 v205, v109, v105, s41
	v_perm_b32 v189, v205, v204, s42
	v_perm_b32 v204, v117, v113, s41
	v_perm_b32 v205, v125, v121, s41
	v_perm_b32 v190, v205, v204, s42
	v_perm_b32 v204, v133, v129, s41
	v_perm_b32 v205, v141, v137, s41
	v_perm_b32 v191, v205, v204, s42
	v_perm_b32 v204, v86, v82, s41
	v_perm_b32 v205, v94, v90, s41
	v_perm_b32 v192, v205, v204, s42
	v_perm_b32 v204, v102, v98, s41
	v_perm_b32 v205, v110, v106, s41
	v_perm_b32 v193, v205, v204, s42
	v_perm_b32 v204, v118, v114, s41
	v_perm_b32 v205, v126, v122, s41
	v_perm_b32 v194, v205, v204, s42
	v_perm_b32 v204, v134, v130, s41
	v_perm_b32 v205, v142, v138, s41
	v_perm_b32 v195, v205, v204, s42
	v_perm_b32 v204, v87, v83, s41
	v_perm_b32 v205, v95, v91, s41
	v_perm_b32 v196, v205, v204, s42
	v_perm_b32 v204, v103, v99, s41
	v_perm_b32 v205, v111, v107, s41
	v_perm_b32 v197, v205, v204, s42
	v_perm_b32 v204, v119, v115, s41
	v_perm_b32 v205, v127, v123, s41
	v_perm_b32 v198, v205, v204, s42
	v_perm_b32 v204, v135, v131, s41
	v_perm_b32 v205, v143, v139, s41
	v_perm_b32 v199, v205, v204, s42
	ds_write_b128 v213, v[184:187] offset:0
	ds_write_b128 v213, v[188:191] offset:144
	ds_write_b128 v213, v[192:195] offset:288
	ds_write_b128 v213, v[196:199] offset:432
	s_mov_b32 s26, s61
	s_add_i32 s26, s26, s17
	s_mul_i32 s26, s26, 0x1000
	s_add_u32 s26, s26, s60
	s_add_u32 s54, s44, s26
	s_addc_u32 s55, s45, 0
	s_waitcnt lgkmcnt(0)
	s_barrier
	ds_read_b128 v[184:187], v214 offset:0
	ds_read_b128 v[188:191], v214 offset:1152
	ds_read_b128 v[192:195], v214 offset:2304
	ds_read_b128 v[196:199], v214 offset:3456
	s_waitcnt lgkmcnt(3)
	global_store_dwordx4 v215, v[184:187], s[54:55]
	s_add_u32 s54, s54, 0x8000
	s_addc_u32 s55, s55, 0
	s_waitcnt lgkmcnt(2)
	global_store_dwordx4 v215, v[188:191], s[54:55]
	s_add_u32 s54, s54, 0x8000
	s_addc_u32 s55, s55, 0
	s_waitcnt lgkmcnt(1)
	global_store_dwordx4 v215, v[192:195], s[54:55]
	s_add_u32 s54, s54, 0x8000
	s_addc_u32 s55, s55, 0
	s_waitcnt lgkmcnt(0)
	global_store_dwordx4 v215, v[196:199], s[54:55]
	s_mov_b32 s19, s59
	s_cmp_lt_u32 s19, 0x400
	s_cbranch_scc0 .Lf8t_win8a0_end
	s_add_i32 s59, s19, s96
	s_cmp_lt_u32 s59, 0x400
	s_cbranch_scc0 .Lf8t_win8a0_b_nonext
	s_mul_hi_u32 s20, s59, 0x8000000
	s_mul_i32 s21, s20, 32
	s_sub_i32 s21, s59, s21
	s_lshl_b32 s60, s20, 7
	s_lshl_b32 s61, s21, 8
	s_add_i32 s24, s60, s16
	s_mul_i32 s24, s24, 0x16b80
	s_lshl_b32 s25, s61, 2
	s_add_u32 s24, s24, s25
	s_add_u32 s52, s50, s24
	s_addc_u32 s53, s51, 0
	global_load_dwordx4 v[80:83], v212, s[52:53]
	s_add_u32 s52, s52, 0x16b80
	s_addc_u32 s53, s53, 0
	global_load_dwordx4 v[84:87], v212, s[52:53]
	s_add_u32 s52, s52, 0x16b80
	s_addc_u32 s53, s53, 0
	global_load_dwordx4 v[88:91], v212, s[52:53]
	s_add_u32 s52, s52, 0x16b80
	s_addc_u32 s53, s53, 0
	global_load_dwordx4 v[92:95], v212, s[52:53]
	s_add_u32 s52, s52, 0x16b80
	s_addc_u32 s53, s53, 0
	global_load_dwordx4 v[96:99], v212, s[52:53]
	s_add_u32 s52, s52, 0x16b80
	s_addc_u32 s53, s53, 0
	global_load_dwordx4 v[100:103], v212, s[52:53]
	s_add_u32 s52, s52, 0x16b80
	s_addc_u32 s53, s53, 0
	global_load_dwordx4 v[104:107], v212, s[52:53]
	s_add_u32 s52, s52, 0x16b80
	s_addc_u32 s53, s53, 0
	global_load_dwordx4 v[108:111], v212, s[52:53]
	s_add_u32 s52, s52, 0x16b80
	s_addc_u32 s53, s53, 0
	global_load_dwordx4 v[112:115], v212, s[52:53]
	s_add_u32 s52, s52, 0x16b80
	s_addc_u32 s53, s53, 0
	global_load_dwordx4 v[116:119], v212, s[52:53]
	s_add_u32 s52, s52, 0x16b80
	s_addc_u32 s53, s53, 0
	global_load_dwordx4 v[120:123], v212, s[52:53]
	s_add_u32 s52, s52, 0x16b80
	s_addc_u32 s53, s53, 0
	global_load_dwordx4 v[124:127], v212, s[52:53]
	s_add_u32 s52, s52, 0x16b80
	s_addc_u32 s53, s53, 0
	global_load_dwordx4 v[128:131], v212, s[52:53]
	s_add_u32 s52, s52, 0x16b80
	s_addc_u32 s53, s53, 0
	global_load_dwordx4 v[132:135], v212, s[52:53]
	s_add_u32 s52, s52, 0x16b80
	s_addc_u32 s53, s53, 0
	global_load_dwordx4 v[136:139], v212, s[52:53]
	s_add_u32 s52, s52, 0x16b80
	s_addc_u32 s53, s53, 0
	global_load_dwordx4 v[140:143], v212, s[52:53]
	s_waitcnt vmcnt(20)
	s_branch .Lf8t_win8a0_b_go

; #define LAS __attribute__((address_space(3)))
; __device__ __forceinline__ unsigned pk4_i8(float a, float b, float c, float d, float s) {
;     const unsigned ua = __float_as_uint(__builtin_amdgcn_fmed3f(a * s, -127.f, 127.f) + 12582912.f), ub = __float_as_uint(__builtin_amdgcn_fmed3f(b * s, -127.f, 127.f) + 12582912.f);
;     const unsigned uc = __float_as_uint(__builtin_amdgcn_fmed3f(c * s, -127.f, 127.f) + 12582912.f), ud = __float_as_uint(__builtin_amdgcn_fmed3f(d * s, -127.f, 127.f) + 12582912.f);
;     return (ua & 0xffu) | ((ub & 0xffu) << 8) | ((uc & 0xffu) << 16) | (ud << 24);
;     ...
;         for (int j = 0; j < 2; ++j) { const int n = (lane >> 2) + 16 * j; const LAS float* sp = scr + (16 * c) * 33 + n;
;             u32x4 o;
;             if (QI8) { o.x = pk4_i8(sp[0 * 33], sp[1 * 33], sp[2 * 33], sp[3 * 33], scl); o.y = pk4_i8(sp[4 * 33], sp[5 * 33], sp[6 * 33], sp[7 * 33], scl);
;                 o.z = pk4_i8(sp[8 * 33], sp[9 * 33], sp[10 * 33], sp[11 * 33], scl); o.w = pk4_i8(sp[12 * 33], sp[13 * 33], sp[14 * 33], sp[15 * 33], scl); }
.Lf8t_win8a0_b_go:
	v_pk_mul_f32 v[16:17], v[16:17], s[36:37] op_sel_hi:[1,0]
	v_pk_mul_f32 v[18:19], v[18:19], s[36:37] op_sel_hi:[1,0]
	v_pk_mul_f32 v[20:21], v[20:21], s[36:37] op_sel_hi:[1,0]
	v_pk_mul_f32 v[22:23], v[22:23], s[36:37] op_sel_hi:[1,0]
	v_pk_mul_f32 v[24:25], v[24:25], s[36:37] op_sel_hi:[1,0]
	v_pk_mul_f32 v[26:27], v[26:27], s[36:37] op_sel_hi:[1,0]
	v_pk_mul_f32 v[28:29], v[28:29], s[36:37] op_sel_hi:[1,0]
	v_pk_mul_f32 v[30:31], v[30:31], s[36:37] op_sel_hi:[1,0]
	v_pk_mul_f32 v[32:33], v[32:33], s[36:37] op_sel_hi:[1,0]
	v_pk_mul_f32 v[34:35], v[34:35], s[36:37] op_sel_hi:[1,0]
	v_pk_mul_f32 v[36:37], v[36:37], s[36:37] op_sel_hi:[1,0]
	v_pk_mul_f32 v[38:39], v[38:39], s[36:37] op_sel_hi:[1,0]
	v_pk_mul_f32 v[40:41], v[40:41], s[36:37] op_sel_hi:[1,0]
	v_pk_mul_f32 v[42:43], v[42:43], s[36:37] op_sel_hi:[1,0]
	v_pk_mul_f32 v[44:45], v[44:45], s[36:37] op_sel_hi:[1,0]
	v_pk_mul_f32 v[46:47], v[46:47], s[36:37] op_sel_hi:[1,0]
	v_pk_mul_f32 v[48:49], v[48:49], s[36:37] op_sel_hi:[1,0]
	v_pk_mul_f32 v[50:51], v[50:51], s[36:37] op_sel_hi:[1,0]
	v_pk_mul_f32 v[52:53], v[52:53], s[36:37] op_sel_hi:[1,0]
	v_pk_mul_f32 v[54:55], v[54:55], s[36:37] op_sel_hi:[1,0]
	v_pk_mul_f32 v[56:57], v[56:57], s[36:37] op_sel_hi:[1,0]
	v_pk_mul_f32 v[58:59], v[58:59], s[36:37] op_sel_hi:[1,0]
	v_pk_mul_f32 v[60:61], v[60:61], s[36:37] op_sel_hi:[1,0]
	v_pk_mul_f32 v[62:63], v[62:63], s[36:37] op_sel_hi:[1,0]
	v_pk_mul_f32 v[64:65], v[64:65], s[36:37] op_sel_hi:[1,0]
	v_pk_mul_f32 v[66:67], v[66:67], s[36:37] op_sel_hi:[1,0]
	v_pk_mul_f32 v[68:69], v[68:69], s[36:37] op_sel_hi:[1,0]
	v_pk_mul_f32 v[70:71], v[70:71], s[36:37] op_sel_hi:[1,0]
	v_pk_mul_f32 v[144:145], v[144:145], s[36:37] op_sel_hi:[1,0]
	v_pk_mul_f32 v[146:147], v[146:147], s[36:37] op_sel_hi:[1,0]
	v_pk_mul_f32 v[148:149], v[148:149], s[36:37] op_sel_hi:[1,0]
	v_pk_mul_f32 v[150:151], v[150:151], s[36:37] op_sel_hi:[1,0]
	v_med3_f32 v16, v16, s40, v216
	v_med3_f32 v17, v17, s40, v216
	v_med3_f32 v18, v18, s40, v216
	v_med3_f32 v19, v19, s40, v216
	v_med3_f32 v20, v20, s40, v216
	v_med3_f32 v21, v21, s40, v216
	v_med3_f32 v22, v22, s40, v216
	v_med3_f32 v23, v23, s40, v216
	v_med3_f32 v24, v24, s40, v216
	v_med3_f32 v25, v25, s40, v216
	v_med3_f32 v26, v26, s40, v216
	v_med3_f32 v27, v27, s40, v216
	v_med3_f32 v28, v28, s40, v216
	v_med3_f32 v29, v29, s40, v216
	v_med3_f32 v30, v30, s40, v216
	v_med3_f32 v31, v31, s40, v216
	v_med3_f32 v32, v32, s40, v216
	v_med3_f32 v33, v33, s40, v216
	v_med3_f32 v34, v34, s40, v216
	v_med3_f32 v35, v35, s40, v216
	v_med3_f32 v36, v36, s40, v216
	v_med3_f32 v37, v37, s40, v216
	v_med3_f32 v38, v38, s40, v216
	v_med3_f32 v39, v39, s40, v216
	v_med3_f32 v40, v40, s40, v216
	v_med3_f32 v41, v41, s40, v216
	v_med3_f32 v42, v42, s40, v216
	v_med3_f32 v43, v43, s40, v216
	v_med3_f32 v44, v44, s40, v216
	v_med3_f32 v45, v45, s40, v216
	v_med3_f32 v46, v46, s40, v216
	v_med3_f32 v47, v47, s40, v216
	v_med3_f32 v48, v48, s40, v216
	v_med3_f32 v49, v49, s40, v216
	v_med3_f32 v50, v50, s40, v216
	v_med3_f32 v51, v51, s40, v216
	v_med3_f32 v52, v52, s40, v216
	v_med3_f32 v53, v53, s40, v216
	v_med3_f32 v54, v54, s40, v216
	v_med3_f32 v55, v55, s40, v216
	v_med3_f32 v56, v56, s40, v216
	v_med3_f32 v57, v57, s40, v216
	v_med3_f32 v58, v58, s40, v216
	v_med3_f32 v59, v59, s40, v216
	v_med3_f32 v60, v60, s40, v216
	v_med3_f32 v61, v61, s40, v216
	v_med3_f32 v62, v62, s40, v216
	v_med3_f32 v63, v63, s40, v216
	v_med3_f32 v64, v64, s40, v216
	v_med3_f32 v65, v65, s40, v216
	v_med3_f32 v66, v66, s40, v216
	v_med3_f32 v67, v67, s40, v216
	v_med3_f32 v68, v68, s40, v216
	v_med3_f32 v69, v69, s40, v216
	v_med3_f32 v70, v70, s40, v216
	v_med3_f32 v71, v71, s40, v216
	v_med3_f32 v144, v144, s40, v216
	v_med3_f32 v145, v145, s40, v216
	v_med3_f32 v146, v146, s40, v216
	v_med3_f32 v147, v147, s40, v216
	v_med3_f32 v148, v148, s40, v216
	v_med3_f32 v149, v149, s40, v216
	v_med3_f32 v150, v150, s40, v216
	v_med3_f32 v151, v151, s40, v216
	v_pk_add_f32 v[16:17], v[16:17], s[38:39] op_sel_hi:[1,0]
	v_pk_add_f32 v[18:19], v[18:19], s[38:39] op_sel_hi:[1,0]
	v_pk_add_f32 v[20:21], v[20:21], s[38:39] op_sel_hi:[1,0]
	v_pk_add_f32 v[22:23], v[22:23], s[38:39] op_sel_hi:[1,0]
	v_pk_add_f32 v[24:25], v[24:25], s[38:39] op_sel_hi:[1,0]
; #define LAS __attribute__((address_space(3)))
; __device__ __forceinline__ unsigned pk4_f8(float a, float b, float c, float d) { int w = __builtin_amdgcn_cvt_pk_fp8_f32(a, b, 0, false); w = __builtin_amdgcn_cvt_pk_fp8_f32(c, d, w, true); return (unsigned)w; }
; #define LDS_WAIT() asm volatile("s_waitcnt lgkmcnt(0)" ::: "memory")
;     ...
;     for (int item = F.gw; item < nitems; item += F.NGW) { const int kb = item / nblk, nb = item % nblk, k0 = 64 * kb, n0 = 32 * nb;
;         int dr0 = n0; if (MAP == 1) { if (n0 < DFF) dr0 = (n0 >> 7) * 256 + (n0 & 127); else { const int uo = n0 - DFF; dr0 = (uo >> 7) * 256 + 128 + (uo & 127); } }
; #pragma unroll 8
;         for (int i = 0; i < 32; ++i) { const int kk = 2 * i + (lane >> 5); scr[kk * 33 + (lane & 31)] = W[(size_t)(k0 + kk) * ldw + n0 + (lane & 31)]; }
;         LDS_WAIT(); asm volatile("" ::: "memory");
;         const int c = lane & 3;
; #pragma unroll
;         for (int j = 0; j < 2; ++j) { const int n = (lane >> 2) + 16 * j; const LAS float* sp = scr + (16 * c) * 33 + n;
;             u32x4 o;
;             if (QI8) { o.x = pk4_i8(sp[0 * 33], sp[1 * 33], sp[2 * 33], sp[3 * 33], scl); o.y = pk4_i8(sp[4 * 33], sp[5 * 33], sp[6 * 33], sp[7 * 33], scl);
;                 o.z = pk4_i8(sp[8 * 33], sp[9 * 33], sp[10 * 33], sp[11 * 33], scl); o.w = pk4_i8(sp[12 * 33], sp[13 * 33], sp[14 * 33], sp[15 * 33], scl); }
;             else {
;             o.x = pk4_f8(sp[0 * 33] * scl, sp[1 * 33] * scl, sp[2 * 33] * scl, sp[3 * 33] * scl); o.y = pk4_f8(sp[4 * 33] * scl, sp[5 * 33] * scl, sp[6 * 33] * scl, sp[7 * 33] * scl);
;             o.z = pk4_f8(sp[8 * 33] * scl, sp[9 * 33] * scl, sp[10 * 33] * scl, sp[11 * 33] * scl); o.w = pk4_f8(sp[12 * 33] * scl, sp[13 * 33] * scl, sp[14 * 33] * scl, sp[15 * 33] * scl); }
;             *(u32x4*)(WT + (size_t)(dr0 + n) * K + k0 + 16 * c) = o; }
;         LDS_WAIT(); asm volatile("" ::: "memory"); }
	v_pk_add_f32 v[26:27], v[26:27], s[38:39] op_sel_hi:[1,0]
	v_pk_add_f32 v[28:29], v[28:29], s[38:39] op_sel_hi:[1,0]
	v_pk_add_f32 v[30:31], v[30:31], s[38:39] op_sel_hi:[1,0]
	v_pk_add_f32 v[32:33], v[32:33], s[38:39] op_sel_hi:[1,0]
	v_pk_add_f32 v[34:35], v[34:35], s[38:39] op_sel_hi:[1,0]
	v_pk_add_f32 v[36:37], v[36:37], s[38:39] op_sel_hi:[1,0]
	v_pk_add_f32 v[38:39], v[38:39], s[38:39] op_sel_hi:[1,0]
	v_pk_add_f32 v[40:41], v[40:41], s[38:39] op_sel_hi:[1,0]
	v_pk_add_f32 v[42:43], v[42:43], s[38:39] op_sel_hi:[1,0]
	v_pk_add_f32 v[44:45], v[44:45], s[38:39] op_sel_hi:[1,0]
	v_pk_add_f32 v[46:47], v[46:47], s[38:39] op_sel_hi:[1,0]
	v_pk_add_f32 v[48:49], v[48:49], s[38:39] op_sel_hi:[1,0]
	v_pk_add_f32 v[50:51], v[50:51], s[38:39] op_sel_hi:[1,0]
	v_pk_add_f32 v[52:53], v[52:53], s[38:39] op_sel_hi:[1,0]
	v_pk_add_f32 v[54:55], v[54:55], s[38:39] op_sel_hi:[1,0]
	v_pk_add_f32 v[56:57], v[56:57], s[38:39] op_sel_hi:[1,0]
	v_pk_add_f32 v[58:59], v[58:59], s[38:39] op_sel_hi:[1,0]
	v_pk_add_f32 v[60:61], v[60:61], s[38:39] op_sel_hi:[1,0]
	v_pk_add_f32 v[62:63], v[62:63], s[38:39] op_sel_hi:[1,0]
	v_pk_add_f32 v[64:65], v[64:65], s[38:39] op_sel_hi:[1,0]
	v_pk_add_f32 v[66:67], v[66:67], s[38:39] op_sel_hi:[1,0]
	v_pk_add_f32 v[68:69], v[68:69], s[38:39] op_sel_hi:[1,0]
	v_pk_add_f32 v[70:71], v[70:71], s[38:39] op_sel_hi:[1,0]
	v_pk_add_f32 v[144:145], v[144:145], s[38:39] op_sel_hi:[1,0]
	v_pk_add_f32 v[146:147], v[146:147], s[38:39] op_sel_hi:[1,0]
	v_pk_add_f32 v[148:149], v[148:149], s[38:39] op_sel_hi:[1,0]
	v_pk_add_f32 v[150:151], v[150:151], s[38:39] op_sel_hi:[1,0]
	v_perm_b32 v204, v20, v16, s41
	v_perm_b32 v205, v28, v24, s41
	v_perm_b32 v184, v205, v204, s42
	v_perm_b32 v204, v36, v32, s41
	v_perm_b32 v205, v44, v40, s41
	v_perm_b32 v185, v205, v204, s42
	v_perm_b32 v204, v52, v48, s41
	v_perm_b32 v205, v60, v56, s41
	v_perm_b32 v186, v205, v204, s42
	v_perm_b32 v204, v68, v64, s41
	v_perm_b32 v205, v148, v144, s41
	v_perm_b32 v187, v205, v204, s42
	v_perm_b32 v204, v21, v17, s41
	v_perm_b32 v205, v29, v25, s41
	v_perm_b32 v188, v205, v204, s42
	v_perm_b32 v204, v37, v33, s41
	v_perm_b32 v205, v45, v41, s41
	v_perm_b32 v189, v205, v204, s42
	v_perm_b32 v204, v53, v49, s41
	v_perm_b32 v205, v61, v57, s41
	v_perm_b32 v190, v205, v204, s42
	v_perm_b32 v204, v69, v65, s41
	v_perm_b32 v205, v149, v145, s41
	v_perm_b32 v191, v205, v204, s42
	v_perm_b32 v204, v22, v18, s41
	v_perm_b32 v205, v30, v26, s41
	v_perm_b32 v192, v205, v204, s42
	v_perm_b32 v204, v38, v34, s41
	v_perm_b32 v205, v46, v42, s41
	v_perm_b32 v193, v205, v204, s42
	v_perm_b32 v204, v54, v50, s41
	v_perm_b32 v205, v62, v58, s41
	v_perm_b32 v194, v205, v204, s42
	v_perm_b32 v204, v70, v66, s41
	v_perm_b32 v205, v150, v146, s41
	v_perm_b32 v195, v205, v204, s42
	v_perm_b32 v204, v23, v19, s41
	v_perm_b32 v205, v31, v27, s41
	v_perm_b32 v196, v205, v204, s42
	v_perm_b32 v204, v39, v35, s41
	v_perm_b32 v205, v47, v43, s41
	v_perm_b32 v197, v205, v204, s42
	v_perm_b32 v204, v55, v51, s41
	v_perm_b32 v205, v63, v59, s41
	v_perm_b32 v198, v205, v204, s42
	v_perm_b32 v204, v71, v67, s41
	v_perm_b32 v205, v151, v147, s41
	v_perm_b32 v199, v205, v204, s42
	ds_write_b128 v213, v[184:187] offset:36864
	ds_write_b128 v213, v[188:191] offset:37008
	ds_write_b128 v213, v[192:195] offset:37152
	ds_write_b128 v213, v[196:199] offset:37296
	s_mov_b32 s26, s63
	s_add_i32 s26, s26, s17
	s_mul_i32 s26, s26, 0x1000
	s_add_u32 s26, s26, s62
	s_add_u32 s54, s44, s26
	s_addc_u32 s55, s45, 0
	s_waitcnt lgkmcnt(0)
	s_barrier
	ds_read_b128 v[184:187], v214 offset:36864
	ds_read_b128 v[188:191], v214 offset:38016
	ds_read_b128 v[192:195], v214 offset:39168
	ds_read_b128 v[196:199], v214 offset:40320
	s_waitcnt lgkmcnt(3)
	global_store_dwordx4 v215, v[184:187], s[54:55]
	s_add_u32 s54, s54, 0x8000
	s_addc_u32 s55, s55, 0
	s_waitcnt lgkmcnt(2)
	global_store_dwordx4 v215, v[188:191], s[54:55]
	s_add_u32 s54, s54, 0x8000
	s_addc_u32 s55, s55, 0
	s_waitcnt lgkmcnt(1)
	global_store_dwordx4 v215, v[192:195], s[54:55]
	s_add_u32 s54, s54, 0x8000
	s_addc_u32 s55, s55, 0
	s_waitcnt lgkmcnt(0)
	global_store_dwordx4 v215, v[196:199], s[54:55]
	s_mov_b32 s19, s59
	s_cmp_lt_u32 s19, 0x400
	s_cbranch_scc1 .Lf8t_win8a0_loop

; #define LAS __attribute__((address_space(3)))
; #define LDS_WAIT() asm volatile("s_waitcnt lgkmcnt(0)" ::: "memory")
;     if (ldw == 0) ldw = N;
;     LAS float* scr = (LAS float*)(F.lds + F.wave * 16384); const int lane = F.lane;
;     const int nblk = N / 32, nitems = (K / 64) * nblk;
;     for (int item = F.gw; item < nitems; item += F.NGW) { const int kb = item / nblk, nb = item % nblk, k0 = 64 * kb, n0 = 32 * nb;
;         int dr0 = n0; if (MAP == 1) { if (n0 < DFF) dr0 = (n0 >> 7) * 256 + (n0 & 127); else { const int uo = n0 - DFF; dr0 = (uo >> 7) * 256 + 128 + (uo & 127); } }
; #pragma unroll 8
;         for (int i = 0; i < 32; ++i) { const int kk = 2 * i + (lane >> 5); scr[kk * 33 + (lane & 31)] = W[(size_t)(k0 + kk) * ldw + n0 + (lane & 31)]; }
;         LDS_WAIT(); asm volatile("" ::: "memory");
; __device__ __forceinline__ void p0_prologue(Frame& F) {
;     ...
;       transpose_f8_matrix<0, true>(F, W, D, 2048, w8 + (size_t)8192 * D, I8_W, ldw);
.LBB0_42:
	s_cmpk_lt_i32 s94, 0x1000
	s_cselect_b64 s[4:5], -1, 0
	s_cmpk_gt_i32 s94, 0xfff
	s_cbranch_scc1 .LBB0_55
	s_barrier
	s_load_dwordx2 s[50:51], s[74:75], 0x58
	v_readlane_b32 s16, v240, 2
	v_lshlrev_b32_e32 v212, 4, v178
	v_mov_b32_e32 v216, 0x42fe0000
	s_mov_b32 s36, 0x44fe0000
	s_mov_b32 s37, 0
	s_mov_b32 s38, 0x4b400000
	s_mov_b32 s39, 0
	s_mov_b32 s40, 0xc2fe0000
	s_mov_b32 s41, 0x0c0c0400
	s_mov_b32 s42, 0x05040100
	s_lshl_b32 s17, s16, 5
	v_mul_u32_u24_e32 v213, 0x240, v178
	s_lshl_b32 s18, s16, 4
	v_add_u32_e32 v213, s18, v213
	v_lshrrev_b32_e32 v204, 3, v178
	v_and_b32_e32 v205, 7, v178
	s_lshl_b32 s18, s16, 5
	v_add_u32_e32 v206, s18, v204
	v_mul_u32_u24_e32 v214, 0x90, v206
	v_lshl_add_u32 v214, v205, 4, v214
	v_mul_u32_u24_e32 v215, 0x1000, v204
	v_lshl_add_u32 v215, v205, 4, v215
	s_lshl_b32 s16, s16, 4
	s_waitcnt lgkmcnt(0)
	s_add_u32 s44, s90, 0x37b00000
	s_addc_u32 s45, s91, 0
	s_mov_b32 s19, s2
	s_cmp_lt_u32 s19, 0x100
	s_cbranch_scc0 .Lf8t_win8bcd0_end
	s_mul_hi_u32 s20, s19, 0x20000000
	s_mul_i32 s21, s20, 8
	s_sub_i32 s21, s19, s21
	s_lshl_b32 s60, s20, 7
	s_lshl_b32 s61, s21, 8
	s_add_i32 s24, s60, s16
	s_mul_i32 s24, s24, 0x16b80
	s_lshl_b32 s25, s61, 2
	s_add_u32 s24, s24, s25
	s_add_u32 s52, s50, s24
	s_addc_u32 s53, s51, 0
	global_load_dwordx4 v[80:83], v212, s[52:53]
	s_add_u32 s52, s52, 0x16b80
	s_addc_u32 s53, s53, 0
	global_load_dwordx4 v[84:87], v212, s[52:53]
	s_add_u32 s52, s52, 0x16b80
	s_addc_u32 s53, s53, 0
	global_load_dwordx4 v[88:91], v212, s[52:53]
	s_add_u32 s52, s52, 0x16b80
	s_addc_u32 s53, s53, 0
	global_load_dwordx4 v[92:95], v212, s[52:53]
	s_add_u32 s52, s52, 0x16b80
	s_addc_u32 s53, s53, 0
	global_load_dwordx4 v[96:99], v212, s[52:53]
	s_add_u32 s52, s52, 0x16b80
	s_addc_u32 s53, s53, 0
	global_load_dwordx4 v[100:103], v212, s[52:53]
	s_add_u32 s52, s52, 0x16b80
	s_addc_u32 s53, s53, 0
	global_load_dwordx4 v[104:107], v212, s[52:53]
	s_add_u32 s52, s52, 0x16b80
	s_addc_u32 s53, s53, 0
	global_load_dwordx4 v[108:111], v212, s[52:53]
	s_add_u32 s52, s52, 0x16b80
	s_addc_u32 s53, s53, 0
	global_load_dwordx4 v[112:115], v212, s[52:53]
	s_add_u32 s52, s52, 0x16b80
	s_addc_u32 s53, s53, 0
	global_load_dwordx4 v[116:119], v212, s[52:53]
	s_add_u32 s52, s52, 0x16b80
	s_addc_u32 s53, s53, 0
	global_load_dwordx4 v[120:123], v212, s[52:53]
	s_add_u32 s52, s52, 0x16b80
	s_addc_u32 s53, s53, 0
	global_load_dwordx4 v[124:127], v212, s[52:53]
	s_add_u32 s52, s52, 0x16b80
	s_addc_u32 s53, s53, 0
	global_load_dwordx4 v[128:131], v212, s[52:53]
	s_add_u32 s52, s52, 0x16b80
	s_addc_u32 s53, s53, 0
	global_load_dwordx4 v[132:135], v212, s[52:53]
	s_add_u32 s52, s52, 0x16b80
	s_addc_u32 s53, s53, 0
	global_load_dwordx4 v[136:139], v212, s[52:53]
	s_add_u32 s52, s52, 0x16b80
	s_addc_u32 s53, s53, 0
	global_load_dwordx4 v[140:143], v212, s[52:53]
	s_mov_b32 s58, 1
.Lf8t_win8bcd0_loop:
	s_add_i32 s59, s19, s96
	s_cmp_lt_u32 s59, 0x100
	s_cbranch_scc0 .Lf8t_win8bcd0_a_nonext
	s_mul_hi_u32 s20, s59, 0x20000000
	s_mul_i32 s21, s20, 8
	s_sub_i32 s21, s59, s21
	s_lshl_b32 s62, s20, 7
	s_lshl_b32 s63, s21, 8
	s_add_i32 s24, s62, s16
	s_mul_i32 s24, s24, 0x16b80
	s_lshl_b32 s25, s63, 2
	s_add_u32 s24, s24, s25
	s_add_u32 s52, s50, s24
	s_addc_u32 s53, s51, 0
	global_load_dwordx4 v[16:19], v212, s[52:53]
	s_add_u32 s52, s52, 0x16b80
	s_addc_u32 s53, s53, 0
	global_load_dwordx4 v[20:23], v212, s[52:53]
	s_add_u32 s52, s52, 0x16b80
	s_addc_u32 s53, s53, 0
	global_load_dwordx4 v[24:27], v212, s[52:53]
	s_add_u32 s52, s52, 0x16b80
	s_addc_u32 s53, s53, 0
	global_load_dwordx4 v[28:31], v212, s[52:53]
	s_add_u32 s52, s52, 0x16b80
	s_addc_u32 s53, s53, 0
	global_load_dwordx4 v[32:35], v212, s[52:53]
	s_add_u32 s52, s52, 0x16b80
	s_addc_u32 s53, s53, 0
	global_load_dwordx4 v[36:39], v212, s[52:53]
	s_add_u32 s52, s52, 0x16b80
	s_addc_u32 s53, s53, 0
	global_load_dwordx4 v[40:43], v212, s[52:53]
	s_add_u32 s52, s52, 0x16b80
	s_addc_u32 s53, s53, 0
	global_load_dwordx4 v[44:47], v212, s[52:53]
	s_add_u32 s52, s52, 0x16b80
	s_addc_u32 s53, s53, 0
	global_load_dwordx4 v[48:51], v212, s[52:53]
	s_add_u32 s52, s52, 0x16b80
	s_addc_u32 s53, s53, 0
	global_load_dwordx4 v[52:55], v212, s[52:53]
	s_add_u32 s52, s52, 0x16b80
	s_addc_u32 s53, s53, 0
	global_load_dwordx4 v[56:59], v212, s[52:53]
	s_add_u32 s52, s52, 0x16b80
	s_addc_u32 s53, s53, 0
	global_load_dwordx4 v[60:63], v212, s[52:53]
	s_add_u32 s52, s52, 0x16b80
	s_addc_u32 s53, s53, 0
	global_load_dwordx4 v[64:67], v212, s[52:53]
	s_add_u32 s52, s52, 0x16b80
	s_addc_u32 s53, s53, 0
	global_load_dwordx4 v[68:71], v212, s[52:53]
	s_add_u32 s52, s52, 0x16b80
	s_addc_u32 s53, s53, 0
	global_load_dwordx4 v[144:147], v212, s[52:53]
	s_add_u32 s52, s52, 0x16b80
	s_addc_u32 s53, s53, 0
	global_load_dwordx4 v[148:151], v212, s[52:53]
	s_cmp_eq_u32 s58, 1
	s_cbranch_scc1 .Lf8t_win8bcd0_a_first
	s_waitcnt vmcnt(20)
	s_branch .Lf8t_win8bcd0_a_go

; #define LAS __attribute__((address_space(3)))
; __device__ __forceinline__ unsigned pk4_i8(float a, float b, float c, float d, float s) {
;     const unsigned ua = __float_as_uint(__builtin_amdgcn_fmed3f(a * s, -127.f, 127.f) + 12582912.f), ub = __float_as_uint(__builtin_amdgcn_fmed3f(b * s, -127.f, 127.f) + 12582912.f);
;     const unsigned uc = __float_as_uint(__builtin_amdgcn_fmed3f(c * s, -127.f, 127.f) + 12582912.f), ud = __float_as_uint(__builtin_amdgcn_fmed3f(d * s, -127.f, 127.f) + 12582912.f);
;     return (ua & 0xffu) | ((ub & 0xffu) << 8) | ((uc & 0xffu) << 16) | (ud << 24);
;     ...
;         for (int j = 0; j < 2; ++j) { const int n = (lane >> 2) + 16 * j; const LAS float* sp = scr + (16 * c) * 33 + n;
;             u32x4 o;
;             if (QI8) { o.x = pk4_i8(sp[0 * 33], sp[1 * 33], sp[2 * 33], sp[3 * 33], scl); o.y = pk4_i8(sp[4 * 33], sp[5 * 33], sp[6 * 33], sp[7 * 33], scl);
;                 o.z = pk4_i8(sp[8 * 33], sp[9 * 33], sp[10 * 33], sp[11 * 33], scl); o.w = pk4_i8(sp[12 * 33], sp[13 * 33], sp[14 * 33], sp[15 * 33], scl); }
.Lf8t_win8bcd0_a_go:
	s_mov_b32 s58, 0
	v_pk_mul_f32 v[80:81], v[80:81], s[36:37] op_sel_hi:[1,0]
	v_pk_mul_f32 v[82:83], v[82:83], s[36:37] op_sel_hi:[1,0]
	v_pk_mul_f32 v[84:85], v[84:85], s[36:37] op_sel_hi:[1,0]
	v_pk_mul_f32 v[86:87], v[86:87], s[36:37] op_sel_hi:[1,0]
	v_pk_mul_f32 v[88:89], v[88:89], s[36:37] op_sel_hi:[1,0]
	v_pk_mul_f32 v[90:91], v[90:91], s[36:37] op_sel_hi:[1,0]
	v_pk_mul_f32 v[92:93], v[92:93], s[36:37] op_sel_hi:[1,0]
	v_pk_mul_f32 v[94:95], v[94:95], s[36:37] op_sel_hi:[1,0]
	v_pk_mul_f32 v[96:97], v[96:97], s[36:37] op_sel_hi:[1,0]
	v_pk_mul_f32 v[98:99], v[98:99], s[36:37] op_sel_hi:[1,0]
	v_pk_mul_f32 v[100:101], v[100:101], s[36:37] op_sel_hi:[1,0]
	v_pk_mul_f32 v[102:103], v[102:103], s[36:37] op_sel_hi:[1,0]
	v_pk_mul_f32 v[104:105], v[104:105], s[36:37] op_sel_hi:[1,0]
	v_pk_mul_f32 v[106:107], v[106:107], s[36:37] op_sel_hi:[1,0]
	v_pk_mul_f32 v[108:109], v[108:109], s[36:37] op_sel_hi:[1,0]
	v_pk_mul_f32 v[110:111], v[110:111], s[36:37] op_sel_hi:[1,0]
	v_pk_mul_f32 v[112:113], v[112:113], s[36:37] op_sel_hi:[1,0]
	v_pk_mul_f32 v[114:115], v[114:115], s[36:37] op_sel_hi:[1,0]
	v_pk_mul_f32 v[116:117], v[116:117], s[36:37] op_sel_hi:[1,0]
	v_pk_mul_f32 v[118:119], v[118:119], s[36:37] op_sel_hi:[1,0]
	v_pk_mul_f32 v[120:121], v[120:121], s[36:37] op_sel_hi:[1,0]
	v_pk_mul_f32 v[122:123], v[122:123], s[36:37] op_sel_hi:[1,0]
	v_pk_mul_f32 v[124:125], v[124:125], s[36:37] op_sel_hi:[1,0]
	v_pk_mul_f32 v[126:127], v[126:127], s[36:37] op_sel_hi:[1,0]
	v_pk_mul_f32 v[128:129], v[128:129], s[36:37] op_sel_hi:[1,0]
	v_pk_mul_f32 v[130:131], v[130:131], s[36:37] op_sel_hi:[1,0]
	v_pk_mul_f32 v[132:133], v[132:133], s[36:37] op_sel_hi:[1,0]
	v_pk_mul_f32 v[134:135], v[134:135], s[36:37] op_sel_hi:[1,0]
	v_pk_mul_f32 v[136:137], v[136:137], s[36:37] op_sel_hi:[1,0]
	v_pk_mul_f32 v[138:139], v[138:139], s[36:37] op_sel_hi:[1,0]
	v_pk_mul_f32 v[140:141], v[140:141], s[36:37] op_sel_hi:[1,0]
	v_pk_mul_f32 v[142:143], v[142:143], s[36:37] op_sel_hi:[1,0]
	v_med3_f32 v80, v80, s40, v216
	v_med3_f32 v81, v81, s40, v216
	v_med3_f32 v82, v82, s40, v216
	v_med3_f32 v83, v83, s40, v216
	v_med3_f32 v84, v84, s40, v216
	v_med3_f32 v85, v85, s40, v216
	v_med3_f32 v86, v86, s40, v216
	v_med3_f32 v87, v87, s40, v216
	v_med3_f32 v88, v88, s40, v216
	v_med3_f32 v89, v89, s40, v216
	v_med3_f32 v90, v90, s40, v216
	v_med3_f32 v91, v91, s40, v216
	v_med3_f32 v92, v92, s40, v216
	v_med3_f32 v93, v93, s40, v216
	v_med3_f32 v94, v94, s40, v216
	v_med3_f32 v95, v95, s40, v216
	v_med3_f32 v96, v96, s40, v216
	v_med3_f32 v97, v97, s40, v216
	v_med3_f32 v98, v98, s40, v216
	v_med3_f32 v99, v99, s40, v216
	v_med3_f32 v100, v100, s40, v216
	v_med3_f32 v101, v101, s40, v216
	v_med3_f32 v102, v102, s40, v216
	v_med3_f32 v103, v103, s40, v216
	v_med3_f32 v104, v104, s40, v216
	v_med3_f32 v105, v105, s40, v216
	v_med3_f32 v106, v106, s40, v216
	v_med3_f32 v107, v107, s40, v216
	v_med3_f32 v108, v108, s40, v216
	v_med3_f32 v109, v109, s40, v216
	v_med3_f32 v110, v110, s40, v216
	v_med3_f32 v111, v111, s40, v216
	v_med3_f32 v112, v112, s40, v216
	v_med3_f32 v113, v113, s40, v216
	v_med3_f32 v114, v114, s40, v216
	v_med3_f32 v115, v115, s40, v216
	v_med3_f32 v116, v116, s40, v216
	v_med3_f32 v117, v117, s40, v216
	v_med3_f32 v118, v118, s40, v216
	v_med3_f32 v119, v119, s40, v216
	v_med3_f32 v120, v120, s40, v216
	v_med3_f32 v121, v121, s40, v216
	v_med3_f32 v122, v122, s40, v216
	v_med3_f32 v123, v123, s40, v216
	v_med3_f32 v124, v124, s40, v216
	v_med3_f32 v125, v125, s40, v216
	v_med3_f32 v126, v126, s40, v216
	v_med3_f32 v127, v127, s40, v216
	v_med3_f32 v128, v128, s40, v216
	v_med3_f32 v129, v129, s40, v216
	v_med3_f32 v130, v130, s40, v216
	v_med3_f32 v131, v131, s40, v216
	v_med3_f32 v132, v132, s40, v216
	v_med3_f32 v133, v133, s40, v216
	v_med3_f32 v134, v134, s40, v216
	v_med3_f32 v135, v135, s40, v216
	v_med3_f32 v136, v136, s40, v216
	v_med3_f32 v137, v137, s40, v216
	v_med3_f32 v138, v138, s40, v216
	v_med3_f32 v139, v139, s40, v216
	v_med3_f32 v140, v140, s40, v216
	v_med3_f32 v141, v141, s40, v216
	v_med3_f32 v142, v142, s40, v216
	v_med3_f32 v143, v143, s40, v216
	v_pk_add_f32 v[80:81], v[80:81], s[38:39] op_sel_hi:[1,0]
	v_pk_add_f32 v[82:83], v[82:83], s[38:39] op_sel_hi:[1,0]
	v_pk_add_f32 v[84:85], v[84:85], s[38:39] op_sel_hi:[1,0]
	v_pk_add_f32 v[86:87], v[86:87], s[38:39] op_sel_hi:[1,0]
	v_pk_add_f32 v[88:89], v[88:89], s[38:39] op_sel_hi:[1,0]
	v_pk_add_f32 v[90:91], v[90:91], s[38:39] op_sel_hi:[1,0]
	v_pk_add_f32 v[92:93], v[92:93], s[38:39] op_sel_hi:[1,0]
	v_pk_add_f32 v[94:95], v[94:95], s[38:39] op_sel_hi:[1,0]
	v_pk_add_f32 v[96:97], v[96:97], s[38:39] op_sel_hi:[1,0]
	v_pk_add_f32 v[98:99], v[98:99], s[38:39] op_sel_hi:[1,0]
	v_pk_add_f32 v[100:101], v[100:101], s[38:39] op_sel_hi:[1,0]
	v_pk_add_f32 v[102:103], v[102:103], s[38:39] op_sel_hi:[1,0]
	v_pk_add_f32 v[104:105], v[104:105], s[38:39] op_sel_hi:[1,0]
	v_pk_add_f32 v[106:107], v[106:107], s[38:39] op_sel_hi:[1,0]
	v_pk_add_f32 v[108:109], v[108:109], s[38:39] op_sel_hi:[1,0]
	v_pk_add_f32 v[110:111], v[110:111], s[38:39] op_sel_hi:[1,0]
	v_pk_add_f32 v[112:113], v[112:113], s[38:39] op_sel_hi:[1,0]
	v_pk_add_f32 v[114:115], v[114:115], s[38:39] op_sel_hi:[1,0]
	v_pk_add_f32 v[116:117], v[116:117], s[38:39] op_sel_hi:[1,0]
	v_pk_add_f32 v[118:119], v[118:119], s[38:39] op_sel_hi:[1,0]
; #define LAS __attribute__((address_space(3)))
; __device__ __forceinline__ unsigned pk4_f8(float a, float b, float c, float d) { int w = __builtin_amdgcn_cvt_pk_fp8_f32(a, b, 0, false); w = __builtin_amdgcn_cvt_pk_fp8_f32(c, d, w, true); return (unsigned)w; }
; #define LDS_WAIT() asm volatile("s_waitcnt lgkmcnt(0)" ::: "memory")
;     ...
;     for (int item = F.gw; item < nitems; item += F.NGW) { const int kb = item / nblk, nb = item % nblk, k0 = 64 * kb, n0 = 32 * nb;
;         int dr0 = n0; if (MAP == 1) { if (n0 < DFF) dr0 = (n0 >> 7) * 256 + (n0 & 127); else { const int uo = n0 - DFF; dr0 = (uo >> 7) * 256 + 128 + (uo & 127); } }
; #pragma unroll 8
;         for (int i = 0; i < 32; ++i) { const int kk = 2 * i + (lane >> 5); scr[kk * 33 + (lane & 31)] = W[(size_t)(k0 + kk) * ldw + n0 + (lane & 31)]; }
;         LDS_WAIT(); asm volatile("" ::: "memory");
;         const int c = lane & 3;
; #pragma unroll
;         for (int j = 0; j < 2; ++j) { const int n = (lane >> 2) + 16 * j; const LAS float* sp = scr + (16 * c) * 33 + n;
;             u32x4 o;
;             if (QI8) { o.x = pk4_i8(sp[0 * 33], sp[1 * 33], sp[2 * 33], sp[3 * 33], scl); o.y = pk4_i8(sp[4 * 33], sp[5 * 33], sp[6 * 33], sp[7 * 33], scl);
;                 o.z = pk4_i8(sp[8 * 33], sp[9 * 33], sp[10 * 33], sp[11 * 33], scl); o.w = pk4_i8(sp[12 * 33], sp[13 * 33], sp[14 * 33], sp[15 * 33], scl); }
;             else {
;             o.x = pk4_f8(sp[0 * 33] * scl, sp[1 * 33] * scl, sp[2 * 33] * scl, sp[3 * 33] * scl); o.y = pk4_f8(sp[4 * 33] * scl, sp[5 * 33] * scl, sp[6 * 33] * scl, sp[7 * 33] * scl);
;             o.z = pk4_f8(sp[8 * 33] * scl, sp[9 * 33] * scl, sp[10 * 33] * scl, sp[11 * 33] * scl); o.w = pk4_f8(sp[12 * 33] * scl, sp[13 * 33] * scl, sp[14 * 33] * scl, sp[15 * 33] * scl); }
;             *(u32x4*)(WT + (size_t)(dr0 + n) * K + k0 + 16 * c) = o; }
;         LDS_WAIT(); asm volatile("" ::: "memory"); }
	v_pk_add_f32 v[120:121], v[120:121], s[38:39] op_sel_hi:[1,0]
	v_pk_add_f32 v[122:123], v[122:123], s[38:39] op_sel_hi:[1,0]
	v_pk_add_f32 v[124:125], v[124:125], s[38:39] op_sel_hi:[1,0]
	v_pk_add_f32 v[126:127], v[126:127], s[38:39] op_sel_hi:[1,0]
	v_pk_add_f32 v[128:129], v[128:129], s[38:39] op_sel_hi:[1,0]
	v_pk_add_f32 v[130:131], v[130:131], s[38:39] op_sel_hi:[1,0]
	v_pk_add_f32 v[132:133], v[132:133], s[38:39] op_sel_hi:[1,0]
	v_pk_add_f32 v[134:135], v[134:135], s[38:39] op_sel_hi:[1,0]
	v_pk_add_f32 v[136:137], v[136:137], s[38:39] op_sel_hi:[1,0]
	v_pk_add_f32 v[138:139], v[138:139], s[38:39] op_sel_hi:[1,0]
	v_pk_add_f32 v[140:141], v[140:141], s[38:39] op_sel_hi:[1,0]
	v_pk_add_f32 v[142:143], v[142:143], s[38:39] op_sel_hi:[1,0]
	v_perm_b32 v204, v84, v80, s41
	v_perm_b32 v205, v92, v88, s41
	v_perm_b32 v184, v205, v204, s42
	v_perm_b32 v204, v100, v96, s41
	v_perm_b32 v205, v108, v104, s41
	v_perm_b32 v185, v205, v204, s42
	v_perm_b32 v204, v116, v112, s41
	v_perm_b32 v205, v124, v120, s41
	v_perm_b32 v186, v205, v204, s42
	v_perm_b32 v204, v132, v128, s41
	v_perm_b32 v205, v140, v136, s41
	v_perm_b32 v187, v205, v204, s42
	v_perm_b32 v204, v85, v81, s41
	v_perm_b32 v205, v93, v89, s41
	v_perm_b32 v188, v205, v204, s42
	v_perm_b32 v204, v101, v97, s41
	v_perm_b32 v205, v109, v105, s41
	v_perm_b32 v189, v205, v204, s42
	v_perm_b32 v204, v117, v113, s41
	v_perm_b32 v205, v125, v121, s41
	v_perm_b32 v190, v205, v204, s42
	v_perm_b32 v204, v133, v129, s41
	v_perm_b32 v205, v141, v137, s41
	v_perm_b32 v191, v205, v204, s42
	v_perm_b32 v204, v86, v82, s41
	v_perm_b32 v205, v94, v90, s41
	v_perm_b32 v192, v205, v204, s42
	v_perm_b32 v204, v102, v98, s41
	v_perm_b32 v205, v110, v106, s41
	v_perm_b32 v193, v205, v204, s42
	v_perm_b32 v204, v118, v114, s41
	v_perm_b32 v205, v126, v122, s41
	v_perm_b32 v194, v205, v204, s42
	v_perm_b32 v204, v134, v130, s41
	v_perm_b32 v205, v142, v138, s41
	v_perm_b32 v195, v205, v204, s42
	v_perm_b32 v204, v87, v83, s41
	v_perm_b32 v205, v95, v91, s41
	v_perm_b32 v196, v205, v204, s42
	v_perm_b32 v204, v103, v99, s41
	v_perm_b32 v205, v111, v107, s41
	v_perm_b32 v197, v205, v204, s42
	v_perm_b32 v204, v119, v115, s41
	v_perm_b32 v205, v127, v123, s41
	v_perm_b32 v198, v205, v204, s42
	v_perm_b32 v204, v135, v131, s41
	v_perm_b32 v205, v143, v139, s41
	v_perm_b32 v199, v205, v204, s42
	ds_write_b128 v213, v[184:187] offset:0
	ds_write_b128 v213, v[188:191] offset:144
	ds_write_b128 v213, v[192:195] offset:288
	ds_write_b128 v213, v[196:199] offset:432
	s_mov_b32 s26, s61
	s_add_i32 s26, s26, s17
	s_mul_i32 s26, s26, 0x1000
	s_add_u32 s26, s26, s60
	s_add_u32 s54, s44, s26
	s_addc_u32 s55, s45, 0
	s_waitcnt lgkmcnt(0)
	s_barrier
	ds_read_b128 v[184:187], v214 offset:0
	ds_read_b128 v[188:191], v214 offset:1152
	ds_read_b128 v[192:195], v214 offset:2304
	ds_read_b128 v[196:199], v214 offset:3456
	s_waitcnt lgkmcnt(3)
	global_store_dwordx4 v215, v[184:187], s[54:55]
	s_add_u32 s54, s54, 0x8000
	s_addc_u32 s55, s55, 0
	s_waitcnt lgkmcnt(2)
	global_store_dwordx4 v215, v[188:191], s[54:55]
	s_add_u32 s54, s54, 0x8000
	s_addc_u32 s55, s55, 0
	s_waitcnt lgkmcnt(1)
	global_store_dwordx4 v215, v[192:195], s[54:55]
	s_add_u32 s54, s54, 0x8000
	s_addc_u32 s55, s55, 0
	s_waitcnt lgkmcnt(0)
	global_store_dwordx4 v215, v[196:199], s[54:55]
	s_mov_b32 s19, s59
	s_cmp_lt_u32 s19, 0x100
	s_cbranch_scc0 .Lf8t_win8bcd0_end
	s_add_i32 s59, s19, s96
	s_cmp_lt_u32 s59, 0x100
	s_cbranch_scc0 .Lf8t_win8bcd0_b_nonext
	s_mul_hi_u32 s20, s59, 0x20000000
	s_mul_i32 s21, s20, 8
	s_sub_i32 s21, s59, s21
	s_lshl_b32 s60, s20, 7
	s_lshl_b32 s61, s21, 8
	s_add_i32 s24, s60, s16
	s_mul_i32 s24, s24, 0x16b80
	s_lshl_b32 s25, s61, 2
	s_add_u32 s24, s24, s25
	s_add_u32 s52, s50, s24
	s_addc_u32 s53, s51, 0
	global_load_dwordx4 v[80:83], v212, s[52:53]
	s_add_u32 s52, s52, 0x16b80
	s_addc_u32 s53, s53, 0
	global_load_dwordx4 v[84:87], v212, s[52:53]
	s_add_u32 s52, s52, 0x16b80
	s_addc_u32 s53, s53, 0
	global_load_dwordx4 v[88:91], v212, s[52:53]
	s_add_u32 s52, s52, 0x16b80
	s_addc_u32 s53, s53, 0
	global_load_dwordx4 v[92:95], v212, s[52:53]
	s_add_u32 s52, s52, 0x16b80
	s_addc_u32 s53, s53, 0
	global_load_dwordx4 v[96:99], v212, s[52:53]
	s_add_u32 s52, s52, 0x16b80
	s_addc_u32 s53, s53, 0
	global_load_dwordx4 v[100:103], v212, s[52:53]
	s_add_u32 s52, s52, 0x16b80
	s_addc_u32 s53, s53, 0
	global_load_dwordx4 v[104:107], v212, s[52:53]
	s_add_u32 s52, s52, 0x16b80
	s_addc_u32 s53, s53, 0
	global_load_dwordx4 v[108:111], v212, s[52:53]
	s_add_u32 s52, s52, 0x16b80
	s_addc_u32 s53, s53, 0
	global_load_dwordx4 v[112:115], v212, s[52:53]
	s_add_u32 s52, s52, 0x16b80
	s_addc_u32 s53, s53, 0
	global_load_dwordx4 v[116:119], v212, s[52:53]
	s_add_u32 s52, s52, 0x16b80
	s_addc_u32 s53, s53, 0
	global_load_dwordx4 v[120:123], v212, s[52:53]
	s_add_u32 s52, s52, 0x16b80
	s_addc_u32 s53, s53, 0
	global_load_dwordx4 v[124:127], v212, s[52:53]
	s_add_u32 s52, s52, 0x16b80
	s_addc_u32 s53, s53, 0
	global_load_dwordx4 v[128:131], v212, s[52:53]
	s_add_u32 s52, s52, 0x16b80
	s_addc_u32 s53, s53, 0
	global_load_dwordx4 v[132:135], v212, s[52:53]
	s_add_u32 s52, s52, 0x16b80
	s_addc_u32 s53, s53, 0
	global_load_dwordx4 v[136:139], v212, s[52:53]
	s_add_u32 s52, s52, 0x16b80
	s_addc_u32 s53, s53, 0
	global_load_dwordx4 v[140:143], v212, s[52:53]
	s_waitcnt vmcnt(20)
	s_branch .Lf8t_win8bcd0_b_go

; #define LAS __attribute__((address_space(3)))
; __device__ __forceinline__ unsigned pk4_i8(float a, float b, float c, float d, float s) {
;     const unsigned ua = __float_as_uint(__builtin_amdgcn_fmed3f(a * s, -127.f, 127.f) + 12582912.f), ub = __float_as_uint(__builtin_amdgcn_fmed3f(b * s, -127.f, 127.f) + 12582912.f);
;     const unsigned uc = __float_as_uint(__builtin_amdgcn_fmed3f(c * s, -127.f, 127.f) + 12582912.f), ud = __float_as_uint(__builtin_amdgcn_fmed3f(d * s, -127.f, 127.f) + 12582912.f);
;     return (ua & 0xffu) | ((ub & 0xffu) << 8) | ((uc & 0xffu) << 16) | (ud << 24);
;     ...
;         for (int j = 0; j < 2; ++j) { const int n = (lane >> 2) + 16 * j; const LAS float* sp = scr + (16 * c) * 33 + n;
;             u32x4 o;
;             if (QI8) { o.x = pk4_i8(sp[0 * 33], sp[1 * 33], sp[2 * 33], sp[3 * 33], scl); o.y = pk4_i8(sp[4 * 33], sp[5 * 33], sp[6 * 33], sp[7 * 33], scl);
;                 o.z = pk4_i8(sp[8 * 33], sp[9 * 33], sp[10 * 33], sp[11 * 33], scl); o.w = pk4_i8(sp[12 * 33], sp[13 * 33], sp[14 * 33], sp[15 * 33], scl); }
.Lf8t_win8bcd0_b_go:
	v_pk_mul_f32 v[16:17], v[16:17], s[36:37] op_sel_hi:[1,0]
	v_pk_mul_f32 v[18:19], v[18:19], s[36:37] op_sel_hi:[1,0]
	v_pk_mul_f32 v[20:21], v[20:21], s[36:37] op_sel_hi:[1,0]
	v_pk_mul_f32 v[22:23], v[22:23], s[36:37] op_sel_hi:[1,0]
	v_pk_mul_f32 v[24:25], v[24:25], s[36:37] op_sel_hi:[1,0]
	v_pk_mul_f32 v[26:27], v[26:27], s[36:37] op_sel_hi:[1,0]
	v_pk_mul_f32 v[28:29], v[28:29], s[36:37] op_sel_hi:[1,0]
	v_pk_mul_f32 v[30:31], v[30:31], s[36:37] op_sel_hi:[1,0]
	v_pk_mul_f32 v[32:33], v[32:33], s[36:37] op_sel_hi:[1,0]
	v_pk_mul_f32 v[34:35], v[34:35], s[36:37] op_sel_hi:[1,0]
	v_pk_mul_f32 v[36:37], v[36:37], s[36:37] op_sel_hi:[1,0]
	v_pk_mul_f32 v[38:39], v[38:39], s[36:37] op_sel_hi:[1,0]
	v_pk_mul_f32 v[40:41], v[40:41], s[36:37] op_sel_hi:[1,0]
	v_pk_mul_f32 v[42:43], v[42:43], s[36:37] op_sel_hi:[1,0]
	v_pk_mul_f32 v[44:45], v[44:45], s[36:37] op_sel_hi:[1,0]
	v_pk_mul_f32 v[46:47], v[46:47], s[36:37] op_sel_hi:[1,0]
	v_pk_mul_f32 v[48:49], v[48:49], s[36:37] op_sel_hi:[1,0]
	v_pk_mul_f32 v[50:51], v[50:51], s[36:37] op_sel_hi:[1,0]
	v_pk_mul_f32 v[52:53], v[52:53], s[36:37] op_sel_hi:[1,0]
	v_pk_mul_f32 v[54:55], v[54:55], s[36:37] op_sel_hi:[1,0]
	v_pk_mul_f32 v[56:57], v[56:57], s[36:37] op_sel_hi:[1,0]
	v_pk_mul_f32 v[58:59], v[58:59], s[36:37] op_sel_hi:[1,0]
	v_pk_mul_f32 v[60:61], v[60:61], s[36:37] op_sel_hi:[1,0]
	v_pk_mul_f32 v[62:63], v[62:63], s[36:37] op_sel_hi:[1,0]
	v_pk_mul_f32 v[64:65], v[64:65], s[36:37] op_sel_hi:[1,0]
	v_pk_mul_f32 v[66:67], v[66:67], s[36:37] op_sel_hi:[1,0]
	v_pk_mul_f32 v[68:69], v[68:69], s[36:37] op_sel_hi:[1,0]
	v_pk_mul_f32 v[70:71], v[70:71], s[36:37] op_sel_hi:[1,0]
	v_pk_mul_f32 v[144:145], v[144:145], s[36:37] op_sel_hi:[1,0]
	v_pk_mul_f32 v[146:147], v[146:147], s[36:37] op_sel_hi:[1,0]
	v_pk_mul_f32 v[148:149], v[148:149], s[36:37] op_sel_hi:[1,0]
	v_pk_mul_f32 v[150:151], v[150:151], s[36:37] op_sel_hi:[1,0]
	v_med3_f32 v16, v16, s40, v216
	v_med3_f32 v17, v17, s40, v216
	v_med3_f32 v18, v18, s40, v216
	v_med3_f32 v19, v19, s40, v216
	v_med3_f32 v20, v20, s40, v216
	v_med3_f32 v21, v21, s40, v216
	v_med3_f32 v22, v22, s40, v216
	v_med3_f32 v23, v23, s40, v216
	v_med3_f32 v24, v24, s40, v216
	v_med3_f32 v25, v25, s40, v216
	v_med3_f32 v26, v26, s40, v216
	v_med3_f32 v27, v27, s40, v216
	v_med3_f32 v28, v28, s40, v216
	v_med3_f32 v29, v29, s40, v216
	v_med3_f32 v30, v30, s40, v216
	v_med3_f32 v31, v31, s40, v216
	v_med3_f32 v32, v32, s40, v216
	v_med3_f32 v33, v33, s40, v216
	v_med3_f32 v34, v34, s40, v216
	v_med3_f32 v35, v35, s40, v216
	v_med3_f32 v36, v36, s40, v216
	v_med3_f32 v37, v37, s40, v216
	v_med3_f32 v38, v38, s40, v216
	v_med3_f32 v39, v39, s40, v216
	v_med3_f32 v40, v40, s40, v216
	v_med3_f32 v41, v41, s40, v216
	v_med3_f32 v42, v42, s40, v216
	v_med3_f32 v43, v43, s40, v216
	v_med3_f32 v44, v44, s40, v216
	v_med3_f32 v45, v45, s40, v216
	v_med3_f32 v46, v46, s40, v216
	v_med3_f32 v47, v47, s40, v216
	v_med3_f32 v48, v48, s40, v216
	v_med3_f32 v49, v49, s40, v216
	v_med3_f32 v50, v50, s40, v216
	v_med3_f32 v51, v51, s40, v216
	v_med3_f32 v52, v52, s40, v216
	v_med3_f32 v53, v53, s40, v216
	v_med3_f32 v54, v54, s40, v216
	v_med3_f32 v55, v55, s40, v216
	v_med3_f32 v56, v56, s40, v216
	v_med3_f32 v57, v57, s40, v216
	v_med3_f32 v58, v58, s40, v216
	v_med3_f32 v59, v59, s40, v216
	v_med3_f32 v60, v60, s40, v216
	v_med3_f32 v61, v61, s40, v216
	v_med3_f32 v62, v62, s40, v216
	v_med3_f32 v63, v63, s40, v216
	v_med3_f32 v64, v64, s40, v216
	v_med3_f32 v65, v65, s40, v216
	v_med3_f32 v66, v66, s40, v216
	v_med3_f32 v67, v67, s40, v216
	v_med3_f32 v68, v68, s40, v216
	v_med3_f32 v69, v69, s40, v216
	v_med3_f32 v70, v70, s40, v216
	v_med3_f32 v71, v71, s40, v216
	v_med3_f32 v144, v144, s40, v216
	v_med3_f32 v145, v145, s40, v216
	v_med3_f32 v146, v146, s40, v216
	v_med3_f32 v147, v147, s40, v216
	v_med3_f32 v148, v148, s40, v216
	v_med3_f32 v149, v149, s40, v216
	v_med3_f32 v150, v150, s40, v216
	v_med3_f32 v151, v151, s40, v216
	v_pk_add_f32 v[16:17], v[16:17], s[38:39] op_sel_hi:[1,0]
	v_pk_add_f32 v[18:19], v[18:19], s[38:39] op_sel_hi:[1,0]
	v_pk_add_f32 v[20:21], v[20:21], s[38:39] op_sel_hi:[1,0]
	v_pk_add_f32 v[22:23], v[22:23], s[38:39] op_sel_hi:[1,0]
	v_pk_add_f32 v[24:25], v[24:25], s[38:39] op_sel_hi:[1,0]
	v_pk_add_f32 v[26:27], v[26:27], s[38:39] op_sel_hi:[1,0]
	v_pk_add_f32 v[28:29], v[28:29], s[38:39] op_sel_hi:[1,0]
	v_pk_add_f32 v[30:31], v[30:31], s[38:39] op_sel_hi:[1,0]
	v_pk_add_f32 v[32:33], v[32:33], s[38:39] op_sel_hi:[1,0]
	v_pk_add_f32 v[34:35], v[34:35], s[38:39] op_sel_hi:[1,0]
	v_pk_add_f32 v[36:37], v[36:37], s[38:39] op_sel_hi:[1,0]
	v_pk_add_f32 v[38:39], v[38:39], s[38:39] op_sel_hi:[1,0]
	v_pk_add_f32 v[40:41], v[40:41], s[38:39] op_sel_hi:[1,0]
	v_pk_add_f32 v[42:43], v[42:43], s[38:39] op_sel_hi:[1,0]
	v_pk_add_f32 v[44:45], v[44:45], s[38:39] op_sel_hi:[1,0]
	v_pk_add_f32 v[46:47], v[46:47], s[38:39] op_sel_hi:[1,0]
	v_pk_add_f32 v[48:49], v[48:49], s[38:39] op_sel_hi:[1,0]
	v_pk_add_f32 v[50:51], v[50:51], s[38:39] op_sel_hi:[1,0]
	v_pk_add_f32 v[52:53], v[52:53], s[38:39] op_sel_hi:[1,0]
	v_pk_add_f32 v[54:55], v[54:55], s[38:39] op_sel_hi:[1,0]
	v_pk_add_f32 v[56:57], v[56:57], s[38:39] op_sel_hi:[1,0]
	v_pk_add_f32 v[58:59], v[58:59], s[38:39] op_sel_hi:[1,0]
	v_pk_add_f32 v[60:61], v[60:61], s[38:39] op_sel_hi:[1,0]
	v_pk_add_f32 v[62:63], v[62:63], s[38:39] op_sel_hi:[1,0]
	v_pk_add_f32 v[64:65], v[64:65], s[38:39] op_sel_hi:[1,0]
	v_pk_add_f32 v[66:67], v[66:67], s[38:39] op_sel_hi:[1,0]
	v_pk_add_f32 v[68:69], v[68:69], s[38:39] op_sel_hi:[1,0]
	v_pk_add_f32 v[70:71], v[70:71], s[38:39] op_sel_hi:[1,0]
; #define LAS __attribute__((address_space(3)))
; __device__ __forceinline__ unsigned pk4_f8(float a, float b, float c, float d) { int w = __builtin_amdgcn_cvt_pk_fp8_f32(a, b, 0, false); w = __builtin_amdgcn_cvt_pk_fp8_f32(c, d, w, true); return (unsigned)w; }
; #define LDS_WAIT() asm volatile("s_waitcnt lgkmcnt(0)" ::: "memory")
;     ...
;     for (int item = F.gw; item < nitems; item += F.NGW) { const int kb = item / nblk, nb = item % nblk, k0 = 64 * kb, n0 = 32 * nb;
;         int dr0 = n0; if (MAP == 1) { if (n0 < DFF) dr0 = (n0 >> 7) * 256 + (n0 & 127); else { const int uo = n0 - DFF; dr0 = (uo >> 7) * 256 + 128 + (uo & 127); } }
; #pragma unroll 8
;         for (int i = 0; i < 32; ++i) { const int kk = 2 * i + (lane >> 5); scr[kk * 33 + (lane & 31)] = W[(size_t)(k0 + kk) * ldw + n0 + (lane & 31)]; }
;         LDS_WAIT(); asm volatile("" ::: "memory");
;         const int c = lane & 3;
; #pragma unroll
;         for (int j = 0; j < 2; ++j) { const int n = (lane >> 2) + 16 * j; const LAS float* sp = scr + (16 * c) * 33 + n;
;             u32x4 o;
;             if (QI8) { o.x = pk4_i8(sp[0 * 33], sp[1 * 33], sp[2 * 33], sp[3 * 33], scl); o.y = pk4_i8(sp[4 * 33], sp[5 * 33], sp[6 * 33], sp[7 * 33], scl);
;                 o.z = pk4_i8(sp[8 * 33], sp[9 * 33], sp[10 * 33], sp[11 * 33], scl); o.w = pk4_i8(sp[12 * 33], sp[13 * 33], sp[14 * 33], sp[15 * 33], scl); }
;             else {
;             o.x = pk4_f8(sp[0 * 33] * scl, sp[1 * 33] * scl, sp[2 * 33] * scl, sp[3 * 33] * scl); o.y = pk4_f8(sp[4 * 33] * scl, sp[5 * 33] * scl, sp[6 * 33] * scl, sp[7 * 33] * scl);
;             o.z = pk4_f8(sp[8 * 33] * scl, sp[9 * 33] * scl, sp[10 * 33] * scl, sp[11 * 33] * scl); o.w = pk4_f8(sp[12 * 33] * scl, sp[13 * 33] * scl, sp[14 * 33] * scl, sp[15 * 33] * scl); }
;             *(u32x4*)(WT + (size_t)(dr0 + n) * K + k0 + 16 * c) = o; }
;         LDS_WAIT(); asm volatile("" ::: "memory"); }
	v_pk_add_f32 v[144:145], v[144:145], s[38:39] op_sel_hi:[1,0]
	v_pk_add_f32 v[146:147], v[146:147], s[38:39] op_sel_hi:[1,0]
	v_pk_add_f32 v[148:149], v[148:149], s[38:39] op_sel_hi:[1,0]
	v_pk_add_f32 v[150:151], v[150:151], s[38:39] op_sel_hi:[1,0]
	v_perm_b32 v204, v20, v16, s41
	v_perm_b32 v205, v28, v24, s41
	v_perm_b32 v184, v205, v204, s42
	v_perm_b32 v204, v36, v32, s41
	v_perm_b32 v205, v44, v40, s41
	v_perm_b32 v185, v205, v204, s42
	v_perm_b32 v204, v52, v48, s41
	v_perm_b32 v205, v60, v56, s41
	v_perm_b32 v186, v205, v204, s42
	v_perm_b32 v204, v68, v64, s41
	v_perm_b32 v205, v148, v144, s41
	v_perm_b32 v187, v205, v204, s42
	v_perm_b32 v204, v21, v17, s41
	v_perm_b32 v205, v29, v25, s41
	v_perm_b32 v188, v205, v204, s42
	v_perm_b32 v204, v37, v33, s41
	v_perm_b32 v205, v45, v41, s41
	v_perm_b32 v189, v205, v204, s42
	v_perm_b32 v204, v53, v49, s41
	v_perm_b32 v205, v61, v57, s41
	v_perm_b32 v190, v205, v204, s42
	v_perm_b32 v204, v69, v65, s41
	v_perm_b32 v205, v149, v145, s41
	v_perm_b32 v191, v205, v204, s42
	v_perm_b32 v204, v22, v18, s41
	v_perm_b32 v205, v30, v26, s41
	v_perm_b32 v192, v205, v204, s42
	v_perm_b32 v204, v38, v34, s41
	v_perm_b32 v205, v46, v42, s41
	v_perm_b32 v193, v205, v204, s42
	v_perm_b32 v204, v54, v50, s41
	v_perm_b32 v205, v62, v58, s41
	v_perm_b32 v194, v205, v204, s42
	v_perm_b32 v204, v70, v66, s41
	v_perm_b32 v205, v150, v146, s41
	v_perm_b32 v195, v205, v204, s42
	v_perm_b32 v204, v23, v19, s41
	v_perm_b32 v205, v31, v27, s41
	v_perm_b32 v196, v205, v204, s42
	v_perm_b32 v204, v39, v35, s41
	v_perm_b32 v205, v47, v43, s41
	v_perm_b32 v197, v205, v204, s42
	v_perm_b32 v204, v55, v51, s41
	v_perm_b32 v205, v63, v59, s41
	v_perm_b32 v198, v205, v204, s42
	v_perm_b32 v204, v71, v67, s41
	v_perm_b32 v205, v151, v147, s41
	v_perm_b32 v199, v205, v204, s42
	ds_write_b128 v213, v[184:187] offset:36864
	ds_write_b128 v213, v[188:191] offset:37008
	ds_write_b128 v213, v[192:195] offset:37152
	ds_write_b128 v213, v[196:199] offset:37296
	s_mov_b32 s26, s63
	s_add_i32 s26, s26, s17
	s_mul_i32 s26, s26, 0x1000
	s_add_u32 s26, s26, s62
	s_add_u32 s54, s44, s26
	s_addc_u32 s55, s45, 0
	s_waitcnt lgkmcnt(0)
	s_barrier
	ds_read_b128 v[184:187], v214 offset:36864
	ds_read_b128 v[188:191], v214 offset:38016
	ds_read_b128 v[192:195], v214 offset:39168
	ds_read_b128 v[196:199], v214 offset:40320
	s_waitcnt lgkmcnt(3)
	global_store_dwordx4 v215, v[184:187], s[54:55]
	s_add_u32 s54, s54, 0x8000
	s_addc_u32 s55, s55, 0
	s_waitcnt lgkmcnt(2)
	global_store_dwordx4 v215, v[188:191], s[54:55]
	s_add_u32 s54, s54, 0x8000
	s_addc_u32 s55, s55, 0
	s_waitcnt lgkmcnt(1)
	global_store_dwordx4 v215, v[192:195], s[54:55]
	s_add_u32 s54, s54, 0x8000
	s_addc_u32 s55, s55, 0
	s_waitcnt lgkmcnt(0)
	global_store_dwordx4 v215, v[196:199], s[54:55]
	s_mov_b32 s19, s59
	s_cmp_lt_u32 s19, 0x100
	s_cbranch_scc1 .Lf8t_win8bcd0_loop
; #define LAS __attribute__((address_space(3)))
; #define LDS_WAIT() asm volatile("s_waitcnt lgkmcnt(0)" ::: "memory")
;     if (ldw == 0) ldw = N;
;     LAS float* scr = (LAS float*)(F.lds + F.wave * 16384); const int lane = F.lane;
;     const int nblk = N / 32, nitems = (K / 64) * nblk;
;     for (int item = F.gw; item < nitems; item += F.NGW) { const int kb = item / nblk, nb = item % nblk, k0 = 64 * kb, n0 = 32 * nb;
;         int dr0 = n0; if (MAP == 1) { if (n0 < DFF) dr0 = (n0 >> 7) * 256 + (n0 & 127); else { const int uo = n0 - DFF; dr0 = (uo >> 7) * 256 + 128 + (uo & 127); } }
; #pragma unroll 8
;         for (int i = 0; i < 32; ++i) { const int kk = 2 * i + (lane >> 5); scr[kk * 33 + (lane & 31)] = W[(size_t)(k0 + kk) * ldw + n0 + (lane & 31)]; }
;         LDS_WAIT(); asm volatile("" ::: "memory");
; __device__ __forceinline__ void p0_prologue(Frame& F) {
;     ...
;       transpose_f8_matrix<0, true>(F, W + 6144, D, 2048, w8 + (size_t)10240 * D, I8_W, ldw);
;       transpose_f8_matrix<0, true>(F, W + 8192, D, 2048, w8 + (size_t)12288 * D, I8_W, ldw); }
.Lf8t_win8bcd0_end:
	s_waitcnt vmcnt(0) lgkmcnt(0)
	s_barrier
	s_barrier
	s_load_dwordx2 s[50:51], s[74:75], 0x58
	v_readlane_b32 s16, v240, 2
	v_lshlrev_b32_e32 v212, 4, v178
	v_mov_b32_e32 v216, 0x42fe0000
	s_mov_b32 s36, 0x44fe0000
	s_mov_b32 s37, 0
	s_mov_b32 s38, 0x4b400000
	s_mov_b32 s39, 0
	s_mov_b32 s40, 0xc2fe0000
	s_mov_b32 s41, 0x0c0c0400
	s_mov_b32 s42, 0x05040100
	s_lshl_b32 s17, s16, 5
	v_mul_u32_u24_e32 v213, 0x240, v178
	s_lshl_b32 s18, s16, 4
	v_add_u32_e32 v213, s18, v213
	v_lshrrev_b32_e32 v204, 3, v178
	v_and_b32_e32 v205, 7, v178
	s_lshl_b32 s18, s16, 5
	v_add_u32_e32 v206, s18, v204
	v_mul_u32_u24_e32 v214, 0x90, v206
	v_lshl_add_u32 v214, v205, 4, v214
	v_mul_u32_u24_e32 v215, 0x1000, v204
	v_lshl_add_u32 v215, v205, 4, v215
	s_lshl_b32 s16, s16, 4
	s_waitcnt lgkmcnt(0)
	s_add_u32 s50, s50, 0x6000
	s_addc_u32 s51, s51, 0
	s_add_u32 s44, s90, 0x38300000
	s_addc_u32 s45, s91, 0
	s_mov_b32 s19, s2
	s_cmp_lt_u32 s19, 0x200
	s_cbranch_scc0 .Lf8t_win8bcd1_end
	s_mul_hi_u32 s20, s19, 0x10000000
	s_mul_i32 s21, s20, 16
	s_sub_i32 s21, s19, s21
	s_lshl_b32 s60, s20, 7
	s_lshl_b32 s61, s21, 8
	s_add_i32 s24, s60, s16
	s_mul_i32 s24, s24, 0x16b80
	s_lshl_b32 s25, s61, 2
	s_add_u32 s24, s24, s25
	s_add_u32 s52, s50, s24
	s_addc_u32 s53, s51, 0
	global_load_dwordx4 v[80:83], v212, s[52:53]
	s_add_u32 s52, s52, 0x16b80
	s_addc_u32 s53, s53, 0
	global_load_dwordx4 v[84:87], v212, s[52:53]
	s_add_u32 s52, s52, 0x16b80
	s_addc_u32 s53, s53, 0
	global_load_dwordx4 v[88:91], v212, s[52:53]
	s_add_u32 s52, s52, 0x16b80
	s_addc_u32 s53, s53, 0
	global_load_dwordx4 v[92:95], v212, s[52:53]
	s_add_u32 s52, s52, 0x16b80
	s_addc_u32 s53, s53, 0
	global_load_dwordx4 v[96:99], v212, s[52:53]
	s_add_u32 s52, s52, 0x16b80
	s_addc_u32 s53, s53, 0
	global_load_dwordx4 v[100:103], v212, s[52:53]
	s_add_u32 s52, s52, 0x16b80
	s_addc_u32 s53, s53, 0
	global_load_dwordx4 v[104:107], v212, s[52:53]
	s_add_u32 s52, s52, 0x16b80
	s_addc_u32 s53, s53, 0
	global_load_dwordx4 v[108:111], v212, s[52:53]
	s_add_u32 s52, s52, 0x16b80
	s_addc_u32 s53, s53, 0
	global_load_dwordx4 v[112:115], v212, s[52:53]
	s_add_u32 s52, s52, 0x16b80
	s_addc_u32 s53, s53, 0
	global_load_dwordx4 v[116:119], v212, s[52:53]
	s_add_u32 s52, s52, 0x16b80
	s_addc_u32 s53, s53, 0
	global_load_dwordx4 v[120:123], v212, s[52:53]
	s_add_u32 s52, s52, 0x16b80
	s_addc_u32 s53, s53, 0
	global_load_dwordx4 v[124:127], v212, s[52:53]
	s_add_u32 s52, s52, 0x16b80
	s_addc_u32 s53, s53, 0
	global_load_dwordx4 v[128:131], v212, s[52:53]
	s_add_u32 s52, s52, 0x16b80
	s_addc_u32 s53, s53, 0
	global_load_dwordx4 v[132:135], v212, s[52:53]
	s_add_u32 s52, s52, 0x16b80
	s_addc_u32 s53, s53, 0
	global_load_dwordx4 v[136:139], v212, s[52:53]
	s_add_u32 s52, s52, 0x16b80
	s_addc_u32 s53, s53, 0
	global_load_dwordx4 v[140:143], v212, s[52:53]
	s_mov_b32 s58, 1
.Lf8t_win8bcd1_loop:
	s_add_i32 s59, s19, s96
	s_cmp_lt_u32 s59, 0x200
	s_cbranch_scc0 .Lf8t_win8bcd1_a_nonext
	s_mul_hi_u32 s20, s59, 0x10000000
	s_mul_i32 s21, s20, 16
	s_sub_i32 s21, s59, s21
	s_lshl_b32 s62, s20, 7
	s_lshl_b32 s63, s21, 8
	s_add_i32 s24, s62, s16
	s_mul_i32 s24, s24, 0x16b80
	s_lshl_b32 s25, s63, 2
	s_add_u32 s24, s24, s25
	s_add_u32 s52, s50, s24
	s_addc_u32 s53, s51, 0
	global_load_dwordx4 v[16:19], v212, s[52:53]
	s_add_u32 s52, s52, 0x16b80
	s_addc_u32 s53, s53, 0
	global_load_dwordx4 v[20:23], v212, s[52:53]
	s_add_u32 s52, s52, 0x16b80
	s_addc_u32 s53, s53, 0
	global_load_dwordx4 v[24:27], v212, s[52:53]
	s_add_u32 s52, s52, 0x16b80
	s_addc_u32 s53, s53, 0
	global_load_dwordx4 v[28:31], v212, s[52:53]
	s_add_u32 s52, s52, 0x16b80
	s_addc_u32 s53, s53, 0
	global_load_dwordx4 v[32:35], v212, s[52:53]
	s_add_u32 s52, s52, 0x16b80
	s_addc_u32 s53, s53, 0
	global_load_dwordx4 v[36:39], v212, s[52:53]
	s_add_u32 s52, s52, 0x16b80
	s_addc_u32 s53, s53, 0
	global_load_dwordx4 v[40:43], v212, s[52:53]
	s_add_u32 s52, s52, 0x16b80
	s_addc_u32 s53, s53, 0
	global_load_dwordx4 v[44:47], v212, s[52:53]
	s_add_u32 s52, s52, 0x16b80
	s_addc_u32 s53, s53, 0
	global_load_dwordx4 v[48:51], v212, s[52:53]
	s_add_u32 s52, s52, 0x16b80
	s_addc_u32 s53, s53, 0
	global_load_dwordx4 v[52:55], v212, s[52:53]
	s_add_u32 s52, s52, 0x16b80
	s_addc_u32 s53, s53, 0
	global_load_dwordx4 v[56:59], v212, s[52:53]
	s_add_u32 s52, s52, 0x16b80
	s_addc_u32 s53, s53, 0
	global_load_dwordx4 v[60:63], v212, s[52:53]
	s_add_u32 s52, s52, 0x16b80
	s_addc_u32 s53, s53, 0
	global_load_dwordx4 v[64:67], v212, s[52:53]
	s_add_u32 s52, s52, 0x16b80
	s_addc_u32 s53, s53, 0
	global_load_dwordx4 v[68:71], v212, s[52:53]
	s_add_u32 s52, s52, 0x16b80
	s_addc_u32 s53, s53, 0
	global_load_dwordx4 v[144:147], v212, s[52:53]
	s_add_u32 s52, s52, 0x16b80
	s_addc_u32 s53, s53, 0
	global_load_dwordx4 v[148:151], v212, s[52:53]
	s_cmp_eq_u32 s58, 1
	s_cbranch_scc1 .Lf8t_win8bcd1_a_first
	s_waitcnt vmcnt(20)
	s_branch .Lf8t_win8bcd1_a_go

; #define LAS __attribute__((address_space(3)))
; __device__ __forceinline__ unsigned pk4_i8(float a, float b, float c, float d, float s) {
;     const unsigned ua = __float_as_uint(__builtin_amdgcn_fmed3f(a * s, -127.f, 127.f) + 12582912.f), ub = __float_as_uint(__builtin_amdgcn_fmed3f(b * s, -127.f, 127.f) + 12582912.f);
;     const unsigned uc = __float_as_uint(__builtin_amdgcn_fmed3f(c * s, -127.f, 127.f) + 12582912.f), ud = __float_as_uint(__builtin_amdgcn_fmed3f(d * s, -127.f, 127.f) + 12582912.f);
;     return (ua & 0xffu) | ((ub & 0xffu) << 8) | ((uc & 0xffu) << 16) | (ud << 24);
;     ...
;         for (int j = 0; j < 2; ++j) { const int n = (lane >> 2) + 16 * j; const LAS float* sp = scr + (16 * c) * 33 + n;
;             u32x4 o;
;             if (QI8) { o.x = pk4_i8(sp[0 * 33], sp[1 * 33], sp[2 * 33], sp[3 * 33], scl); o.y = pk4_i8(sp[4 * 33], sp[5 * 33], sp[6 * 33], sp[7 * 33], scl);
;                 o.z = pk4_i8(sp[8 * 33], sp[9 * 33], sp[10 * 33], sp[11 * 33], scl); o.w = pk4_i8(sp[12 * 33], sp[13 * 33], sp[14 * 33], sp[15 * 33], scl); }
.Lf8t_win8bcd1_a_go:
	s_mov_b32 s58, 0
	v_pk_mul_f32 v[80:81], v[80:81], s[36:37] op_sel_hi:[1,0]
	v_pk_mul_f32 v[82:83], v[82:83], s[36:37] op_sel_hi:[1,0]
	v_pk_mul_f32 v[84:85], v[84:85], s[36:37] op_sel_hi:[1,0]
	v_pk_mul_f32 v[86:87], v[86:87], s[36:37] op_sel_hi:[1,0]
	v_pk_mul_f32 v[88:89], v[88:89], s[36:37] op_sel_hi:[1,0]
	v_pk_mul_f32 v[90:91], v[90:91], s[36:37] op_sel_hi:[1,0]
	v_pk_mul_f32 v[92:93], v[92:93], s[36:37] op_sel_hi:[1,0]
	v_pk_mul_f32 v[94:95], v[94:95], s[36:37] op_sel_hi:[1,0]
	v_pk_mul_f32 v[96:97], v[96:97], s[36:37] op_sel_hi:[1,0]
	v_pk_mul_f32 v[98:99], v[98:99], s[36:37] op_sel_hi:[1,0]
	v_pk_mul_f32 v[100:101], v[100:101], s[36:37] op_sel_hi:[1,0]
	v_pk_mul_f32 v[102:103], v[102:103], s[36:37] op_sel_hi:[1,0]
	v_pk_mul_f32 v[104:105], v[104:105], s[36:37] op_sel_hi:[1,0]
	v_pk_mul_f32 v[106:107], v[106:107], s[36:37] op_sel_hi:[1,0]
	v_pk_mul_f32 v[108:109], v[108:109], s[36:37] op_sel_hi:[1,0]
	v_pk_mul_f32 v[110:111], v[110:111], s[36:37] op_sel_hi:[1,0]
	v_pk_mul_f32 v[112:113], v[112:113], s[36:37] op_sel_hi:[1,0]
	v_pk_mul_f32 v[114:115], v[114:115], s[36:37] op_sel_hi:[1,0]
	v_pk_mul_f32 v[116:117], v[116:117], s[36:37] op_sel_hi:[1,0]
	v_pk_mul_f32 v[118:119], v[118:119], s[36:37] op_sel_hi:[1,0]
	v_pk_mul_f32 v[120:121], v[120:121], s[36:37] op_sel_hi:[1,0]
	v_pk_mul_f32 v[122:123], v[122:123], s[36:37] op_sel_hi:[1,0]
	v_pk_mul_f32 v[124:125], v[124:125], s[36:37] op_sel_hi:[1,0]
	v_pk_mul_f32 v[126:127], v[126:127], s[36:37] op_sel_hi:[1,0]
	v_pk_mul_f32 v[128:129], v[128:129], s[36:37] op_sel_hi:[1,0]
	v_pk_mul_f32 v[130:131], v[130:131], s[36:37] op_sel_hi:[1,0]
	v_pk_mul_f32 v[132:133], v[132:133], s[36:37] op_sel_hi:[1,0]
	v_pk_mul_f32 v[134:135], v[134:135], s[36:37] op_sel_hi:[1,0]
	v_pk_mul_f32 v[136:137], v[136:137], s[36:37] op_sel_hi:[1,0]
	v_pk_mul_f32 v[138:139], v[138:139], s[36:37] op_sel_hi:[1,0]
	v_pk_mul_f32 v[140:141], v[140:141], s[36:37] op_sel_hi:[1,0]
	v_pk_mul_f32 v[142:143], v[142:143], s[36:37] op_sel_hi:[1,0]
	v_med3_f32 v80, v80, s40, v216
	v_med3_f32 v81, v81, s40, v216
	v_med3_f32 v82, v82, s40, v216
	v_med3_f32 v83, v83, s40, v216
	v_med3_f32 v84, v84, s40, v216
	v_med3_f32 v85, v85, s40, v216
	v_med3_f32 v86, v86, s40, v216
	v_med3_f32 v87, v87, s40, v216
	v_med3_f32 v88, v88, s40, v216
	v_med3_f32 v89, v89, s40, v216
	v_med3_f32 v90, v90, s40, v216
	v_med3_f32 v91, v91, s40, v216
	v_med3_f32 v92, v92, s40, v216
	v_med3_f32 v93, v93, s40, v216
	v_med3_f32 v94, v94, s40, v216
	v_med3_f32 v95, v95, s40, v216
	v_med3_f32 v96, v96, s40, v216
	v_med3_f32 v97, v97, s40, v216
	v_med3_f32 v98, v98, s40, v216
	v_med3_f32 v99, v99, s40, v216
	v_med3_f32 v100, v100, s40, v216
	v_med3_f32 v101, v101, s40, v216
	v_med3_f32 v102, v102, s40, v216
	v_med3_f32 v103, v103, s40, v216
	v_med3_f32 v104, v104, s40, v216
	v_med3_f32 v105, v105, s40, v216
	v_med3_f32 v106, v106, s40, v216
	v_med3_f32 v107, v107, s40, v216
	v_med3_f32 v108, v108, s40, v216
	v_med3_f32 v109, v109, s40, v216
	v_med3_f32 v110, v110, s40, v216
	v_med3_f32 v111, v111, s40, v216
	v_med3_f32 v112, v112, s40, v216
	v_med3_f32 v113, v113, s40, v216
	v_med3_f32 v114, v114, s40, v216
	v_med3_f32 v115, v115, s40, v216
	v_med3_f32 v116, v116, s40, v216
	v_med3_f32 v117, v117, s40, v216
	v_med3_f32 v118, v118, s40, v216
	v_med3_f32 v119, v119, s40, v216
	v_med3_f32 v120, v120, s40, v216
	v_med3_f32 v121, v121, s40, v216
	v_med3_f32 v122, v122, s40, v216
	v_med3_f32 v123, v123, s40, v216
	v_med3_f32 v124, v124, s40, v216
	v_med3_f32 v125, v125, s40, v216
	v_med3_f32 v126, v126, s40, v216
	v_med3_f32 v127, v127, s40, v216
	v_med3_f32 v128, v128, s40, v216
	v_med3_f32 v129, v129, s40, v216
	v_med3_f32 v130, v130, s40, v216
	v_med3_f32 v131, v131, s40, v216
	v_med3_f32 v132, v132, s40, v216
	v_med3_f32 v133, v133, s40, v216
	v_med3_f32 v134, v134, s40, v216
	v_med3_f32 v135, v135, s40, v216
	v_med3_f32 v136, v136, s40, v216
	v_med3_f32 v137, v137, s40, v216
	v_med3_f32 v138, v138, s40, v216
	v_med3_f32 v139, v139, s40, v216
	v_med3_f32 v140, v140, s40, v216
	v_med3_f32 v141, v141, s40, v216
	v_med3_f32 v142, v142, s40, v216
	v_med3_f32 v143, v143, s40, v216
	v_pk_add_f32 v[80:81], v[80:81], s[38:39] op_sel_hi:[1,0]
	v_pk_add_f32 v[82:83], v[82:83], s[38:39] op_sel_hi:[1,0]
	v_pk_add_f32 v[84:85], v[84:85], s[38:39] op_sel_hi:[1,0]
	v_pk_add_f32 v[86:87], v[86:87], s[38:39] op_sel_hi:[1,0]
	v_pk_add_f32 v[88:89], v[88:89], s[38:39] op_sel_hi:[1,0]
	v_pk_add_f32 v[90:91], v[90:91], s[38:39] op_sel_hi:[1,0]
	v_pk_add_f32 v[92:93], v[92:93], s[38:39] op_sel_hi:[1,0]
	v_pk_add_f32 v[94:95], v[94:95], s[38:39] op_sel_hi:[1,0]
	v_pk_add_f32 v[96:97], v[96:97], s[38:39] op_sel_hi:[1,0]
	v_pk_add_f32 v[98:99], v[98:99], s[38:39] op_sel_hi:[1,0]
	v_pk_add_f32 v[100:101], v[100:101], s[38:39] op_sel_hi:[1,0]
	v_pk_add_f32 v[102:103], v[102:103], s[38:39] op_sel_hi:[1,0]
	v_pk_add_f32 v[104:105], v[104:105], s[38:39] op_sel_hi:[1,0]
	v_pk_add_f32 v[106:107], v[106:107], s[38:39] op_sel_hi:[1,0]
	v_pk_add_f32 v[108:109], v[108:109], s[38:39] op_sel_hi:[1,0]
	v_pk_add_f32 v[110:111], v[110:111], s[38:39] op_sel_hi:[1,0]
	v_pk_add_f32 v[112:113], v[112:113], s[38:39] op_sel_hi:[1,0]
	v_pk_add_f32 v[114:115], v[114:115], s[38:39] op_sel_hi:[1,0]
	v_pk_add_f32 v[116:117], v[116:117], s[38:39] op_sel_hi:[1,0]
	v_pk_add_f32 v[118:119], v[118:119], s[38:39] op_sel_hi:[1,0]
; #define LAS __attribute__((address_space(3)))
; __device__ __forceinline__ unsigned pk4_f8(float a, float b, float c, float d) { int w = __builtin_amdgcn_cvt_pk_fp8_f32(a, b, 0, false); w = __builtin_amdgcn_cvt_pk_fp8_f32(c, d, w, true); return (unsigned)w; }
; #define LDS_WAIT() asm volatile("s_waitcnt lgkmcnt(0)" ::: "memory")
;     ...
;     for (int item = F.gw; item < nitems; item += F.NGW) { const int kb = item / nblk, nb = item % nblk, k0 = 64 * kb, n0 = 32 * nb;
;         int dr0 = n0; if (MAP == 1) { if (n0 < DFF) dr0 = (n0 >> 7) * 256 + (n0 & 127); else { const int uo = n0 - DFF; dr0 = (uo >> 7) * 256 + 128 + (uo & 127); } }
; #pragma unroll 8
;         for (int i = 0; i < 32; ++i) { const int kk = 2 * i + (lane >> 5); scr[kk * 33 + (lane & 31)] = W[(size_t)(k0 + kk) * ldw + n0 + (lane & 31)]; }
;         LDS_WAIT(); asm volatile("" ::: "memory");
;         const int c = lane & 3;
; #pragma unroll
;         for (int j = 0; j < 2; ++j) { const int n = (lane >> 2) + 16 * j; const LAS float* sp = scr + (16 * c) * 33 + n;
;             u32x4 o;
;             if (QI8) { o.x = pk4_i8(sp[0 * 33], sp[1 * 33], sp[2 * 33], sp[3 * 33], scl); o.y = pk4_i8(sp[4 * 33], sp[5 * 33], sp[6 * 33], sp[7 * 33], scl);
;                 o.z = pk4_i8(sp[8 * 33], sp[9 * 33], sp[10 * 33], sp[11 * 33], scl); o.w = pk4_i8(sp[12 * 33], sp[13 * 33], sp[14 * 33], sp[15 * 33], scl); }
;             else {
;             o.x = pk4_f8(sp[0 * 33] * scl, sp[1 * 33] * scl, sp[2 * 33] * scl, sp[3 * 33] * scl); o.y = pk4_f8(sp[4 * 33] * scl, sp[5 * 33] * scl, sp[6 * 33] * scl, sp[7 * 33] * scl);
;             o.z = pk4_f8(sp[8 * 33] * scl, sp[9 * 33] * scl, sp[10 * 33] * scl, sp[11 * 33] * scl); o.w = pk4_f8(sp[12 * 33] * scl, sp[13 * 33] * scl, sp[14 * 33] * scl, sp[15 * 33] * scl); }
;             *(u32x4*)(WT + (size_t)(dr0 + n) * K + k0 + 16 * c) = o; }
;         LDS_WAIT(); asm volatile("" ::: "memory"); }
	v_pk_add_f32 v[120:121], v[120:121], s[38:39] op_sel_hi:[1,0]
	v_pk_add_f32 v[122:123], v[122:123], s[38:39] op_sel_hi:[1,0]
	v_pk_add_f32 v[124:125], v[124:125], s[38:39] op_sel_hi:[1,0]
	v_pk_add_f32 v[126:127], v[126:127], s[38:39] op_sel_hi:[1,0]
	v_pk_add_f32 v[128:129], v[128:129], s[38:39] op_sel_hi:[1,0]
	v_pk_add_f32 v[130:131], v[130:131], s[38:39] op_sel_hi:[1,0]
	v_pk_add_f32 v[132:133], v[132:133], s[38:39] op_sel_hi:[1,0]
	v_pk_add_f32 v[134:135], v[134:135], s[38:39] op_sel_hi:[1,0]
	v_pk_add_f32 v[136:137], v[136:137], s[38:39] op_sel_hi:[1,0]
	v_pk_add_f32 v[138:139], v[138:139], s[38:39] op_sel_hi:[1,0]
	v_pk_add_f32 v[140:141], v[140:141], s[38:39] op_sel_hi:[1,0]
	v_pk_add_f32 v[142:143], v[142:143], s[38:39] op_sel_hi:[1,0]
	v_perm_b32 v204, v84, v80, s41
	v_perm_b32 v205, v92, v88, s41
	v_perm_b32 v184, v205, v204, s42
	v_perm_b32 v204, v100, v96, s41
	v_perm_b32 v205, v108, v104, s41
	v_perm_b32 v185, v205, v204, s42
	v_perm_b32 v204, v116, v112, s41
	v_perm_b32 v205, v124, v120, s41
	v_perm_b32 v186, v205, v204, s42
	v_perm_b32 v204, v132, v128, s41
	v_perm_b32 v205, v140, v136, s41
	v_perm_b32 v187, v205, v204, s42
	v_perm_b32 v204, v85, v81, s41
	v_perm_b32 v205, v93, v89, s41
	v_perm_b32 v188, v205, v204, s42
	v_perm_b32 v204, v101, v97, s41
	v_perm_b32 v205, v109, v105, s41
	v_perm_b32 v189, v205, v204, s42
	v_perm_b32 v204, v117, v113, s41
	v_perm_b32 v205, v125, v121, s41
	v_perm_b32 v190, v205, v204, s42
	v_perm_b32 v204, v133, v129, s41
	v_perm_b32 v205, v141, v137, s41
	v_perm_b32 v191, v205, v204, s42
	v_perm_b32 v204, v86, v82, s41
	v_perm_b32 v205, v94, v90, s41
	v_perm_b32 v192, v205, v204, s42
	v_perm_b32 v204, v102, v98, s41
	v_perm_b32 v205, v110, v106, s41
	v_perm_b32 v193, v205, v204, s42
	v_perm_b32 v204, v118, v114, s41
	v_perm_b32 v205, v126, v122, s41
	v_perm_b32 v194, v205, v204, s42
	v_perm_b32 v204, v134, v130, s41
	v_perm_b32 v205, v142, v138, s41
	v_perm_b32 v195, v205, v204, s42
	v_perm_b32 v204, v87, v83, s41
	v_perm_b32 v205, v95, v91, s41
	v_perm_b32 v196, v205, v204, s42
	v_perm_b32 v204, v103, v99, s41
	v_perm_b32 v205, v111, v107, s41
	v_perm_b32 v197, v205, v204, s42
	v_perm_b32 v204, v119, v115, s41
	v_perm_b32 v205, v127, v123, s41
	v_perm_b32 v198, v205, v204, s42
	v_perm_b32 v204, v135, v131, s41
	v_perm_b32 v205, v143, v139, s41
	v_perm_b32 v199, v205, v204, s42
	ds_write_b128 v213, v[184:187] offset:0
	ds_write_b128 v213, v[188:191] offset:144
	ds_write_b128 v213, v[192:195] offset:288
	ds_write_b128 v213, v[196:199] offset:432
	s_mov_b32 s26, s61
	s_add_i32 s26, s26, s17
	s_mul_i32 s26, s26, 0x1000
	s_add_u32 s26, s26, s60
	s_add_u32 s54, s44, s26
	s_addc_u32 s55, s45, 0
	s_waitcnt lgkmcnt(0)
	s_barrier
	ds_read_b128 v[184:187], v214 offset:0
	ds_read_b128 v[188:191], v214 offset:1152
	ds_read_b128 v[192:195], v214 offset:2304
	ds_read_b128 v[196:199], v214 offset:3456
	s_waitcnt lgkmcnt(3)
	global_store_dwordx4 v215, v[184:187], s[54:55]
	s_add_u32 s54, s54, 0x8000
	s_addc_u32 s55, s55, 0
	s_waitcnt lgkmcnt(2)
	global_store_dwordx4 v215, v[188:191], s[54:55]
	s_add_u32 s54, s54, 0x8000
	s_addc_u32 s55, s55, 0
	s_waitcnt lgkmcnt(1)
	global_store_dwordx4 v215, v[192:195], s[54:55]
	s_add_u32 s54, s54, 0x8000
	s_addc_u32 s55, s55, 0
	s_waitcnt lgkmcnt(0)
	global_store_dwordx4 v215, v[196:199], s[54:55]
	s_mov_b32 s19, s59
	s_cmp_lt_u32 s19, 0x200
	s_cbranch_scc0 .Lf8t_win8bcd1_end
	s_add_i32 s59, s19, s96
	s_cmp_lt_u32 s59, 0x200
	s_cbranch_scc0 .Lf8t_win8bcd1_b_nonext
	s_mul_hi_u32 s20, s59, 0x10000000
	s_mul_i32 s21, s20, 16
	s_sub_i32 s21, s59, s21
	s_lshl_b32 s60, s20, 7
	s_lshl_b32 s61, s21, 8
	s_add_i32 s24, s60, s16
	s_mul_i32 s24, s24, 0x16b80
	s_lshl_b32 s25, s61, 2
	s_add_u32 s24, s24, s25
	s_add_u32 s52, s50, s24
	s_addc_u32 s53, s51, 0
	global_load_dwordx4 v[80:83], v212, s[52:53]
	s_add_u32 s52, s52, 0x16b80
	s_addc_u32 s53, s53, 0
	global_load_dwordx4 v[84:87], v212, s[52:53]
	s_add_u32 s52, s52, 0x16b80
	s_addc_u32 s53, s53, 0
	global_load_dwordx4 v[88:91], v212, s[52:53]
	s_add_u32 s52, s52, 0x16b80
	s_addc_u32 s53, s53, 0
	global_load_dwordx4 v[92:95], v212, s[52:53]
	s_add_u32 s52, s52, 0x16b80
	s_addc_u32 s53, s53, 0
	global_load_dwordx4 v[96:99], v212, s[52:53]
	s_add_u32 s52, s52, 0x16b80
	s_addc_u32 s53, s53, 0
	global_load_dwordx4 v[100:103], v212, s[52:53]
	s_add_u32 s52, s52, 0x16b80
	s_addc_u32 s53, s53, 0
	global_load_dwordx4 v[104:107], v212, s[52:53]
	s_add_u32 s52, s52, 0x16b80
	s_addc_u32 s53, s53, 0
	global_load_dwordx4 v[108:111], v212, s[52:53]
	s_add_u32 s52, s52, 0x16b80
	s_addc_u32 s53, s53, 0
	global_load_dwordx4 v[112:115], v212, s[52:53]
	s_add_u32 s52, s52, 0x16b80
	s_addc_u32 s53, s53, 0
	global_load_dwordx4 v[116:119], v212, s[52:53]
	s_add_u32 s52, s52, 0x16b80
	s_addc_u32 s53, s53, 0
	global_load_dwordx4 v[120:123], v212, s[52:53]
	s_add_u32 s52, s52, 0x16b80
	s_addc_u32 s53, s53, 0
	global_load_dwordx4 v[124:127], v212, s[52:53]
	s_add_u32 s52, s52, 0x16b80
	s_addc_u32 s53, s53, 0
	global_load_dwordx4 v[128:131], v212, s[52:53]
	s_add_u32 s52, s52, 0x16b80
	s_addc_u32 s53, s53, 0
	global_load_dwordx4 v[132:135], v212, s[52:53]
	s_add_u32 s52, s52, 0x16b80
	s_addc_u32 s53, s53, 0
	global_load_dwordx4 v[136:139], v212, s[52:53]
	s_add_u32 s52, s52, 0x16b80
	s_addc_u32 s53, s53, 0
	global_load_dwordx4 v[140:143], v212, s[52:53]
	s_waitcnt vmcnt(20)
	s_branch .Lf8t_win8bcd1_b_go

; #define LAS __attribute__((address_space(3)))
; __device__ __forceinline__ unsigned pk4_i8(float a, float b, float c, float d, float s) {
;     const unsigned ua = __float_as_uint(__builtin_amdgcn_fmed3f(a * s, -127.f, 127.f) + 12582912.f), ub = __float_as_uint(__builtin_amdgcn_fmed3f(b * s, -127.f, 127.f) + 12582912.f);
;     const unsigned uc = __float_as_uint(__builtin_amdgcn_fmed3f(c * s, -127.f, 127.f) + 12582912.f), ud = __float_as_uint(__builtin_amdgcn_fmed3f(d * s, -127.f, 127.f) + 12582912.f);
;     return (ua & 0xffu) | ((ub & 0xffu) << 8) | ((uc & 0xffu) << 16) | (ud << 24);
;     ...
;         for (int j = 0; j < 2; ++j) { const int n = (lane >> 2) + 16 * j; const LAS float* sp = scr + (16 * c) * 33 + n;
;             u32x4 o;
;             if (QI8) { o.x = pk4_i8(sp[0 * 33], sp[1 * 33], sp[2 * 33], sp[3 * 33], scl); o.y = pk4_i8(sp[4 * 33], sp[5 * 33], sp[6 * 33], sp[7 * 33], scl);
;                 o.z = pk4_i8(sp[8 * 33], sp[9 * 33], sp[10 * 33], sp[11 * 33], scl); o.w = pk4_i8(sp[12 * 33], sp[13 * 33], sp[14 * 33], sp[15 * 33], scl); }
.Lf8t_win8bcd1_b_go:
	v_pk_mul_f32 v[16:17], v[16:17], s[36:37] op_sel_hi:[1,0]
	v_pk_mul_f32 v[18:19], v[18:19], s[36:37] op_sel_hi:[1,0]
	v_pk_mul_f32 v[20:21], v[20:21], s[36:37] op_sel_hi:[1,0]
	v_pk_mul_f32 v[22:23], v[22:23], s[36:37] op_sel_hi:[1,0]
	v_pk_mul_f32 v[24:25], v[24:25], s[36:37] op_sel_hi:[1,0]
	v_pk_mul_f32 v[26:27], v[26:27], s[36:37] op_sel_hi:[1,0]
	v_pk_mul_f32 v[28:29], v[28:29], s[36:37] op_sel_hi:[1,0]
	v_pk_mul_f32 v[30:31], v[30:31], s[36:37] op_sel_hi:[1,0]
	v_pk_mul_f32 v[32:33], v[32:33], s[36:37] op_sel_hi:[1,0]
	v_pk_mul_f32 v[34:35], v[34:35], s[36:37] op_sel_hi:[1,0]
	v_pk_mul_f32 v[36:37], v[36:37], s[36:37] op_sel_hi:[1,0]
	v_pk_mul_f32 v[38:39], v[38:39], s[36:37] op_sel_hi:[1,0]
	v_pk_mul_f32 v[40:41], v[40:41], s[36:37] op_sel_hi:[1,0]
	v_pk_mul_f32 v[42:43], v[42:43], s[36:37] op_sel_hi:[1,0]
	v_pk_mul_f32 v[44:45], v[44:45], s[36:37] op_sel_hi:[1,0]
	v_pk_mul_f32 v[46:47], v[46:47], s[36:37] op_sel_hi:[1,0]
	v_pk_mul_f32 v[48:49], v[48:49], s[36:37] op_sel_hi:[1,0]
	v_pk_mul_f32 v[50:51], v[50:51], s[36:37] op_sel_hi:[1,0]
	v_pk_mul_f32 v[52:53], v[52:53], s[36:37] op_sel_hi:[1,0]
	v_pk_mul_f32 v[54:55], v[54:55], s[36:37] op_sel_hi:[1,0]
	v_pk_mul_f32 v[56:57], v[56:57], s[36:37] op_sel_hi:[1,0]
	v_pk_mul_f32 v[58:59], v[58:59], s[36:37] op_sel_hi:[1,0]
	v_pk_mul_f32 v[60:61], v[60:61], s[36:37] op_sel_hi:[1,0]
	v_pk_mul_f32 v[62:63], v[62:63], s[36:37] op_sel_hi:[1,0]
	v_pk_mul_f32 v[64:65], v[64:65], s[36:37] op_sel_hi:[1,0]
	v_pk_mul_f32 v[66:67], v[66:67], s[36:37] op_sel_hi:[1,0]
	v_pk_mul_f32 v[68:69], v[68:69], s[36:37] op_sel_hi:[1,0]
	v_pk_mul_f32 v[70:71], v[70:71], s[36:37] op_sel_hi:[1,0]
	v_pk_mul_f32 v[144:145], v[144:145], s[36:37] op_sel_hi:[1,0]
	v_pk_mul_f32 v[146:147], v[146:147], s[36:37] op_sel_hi:[1,0]
	v_pk_mul_f32 v[148:149], v[148:149], s[36:37] op_sel_hi:[1,0]
	v_pk_mul_f32 v[150:151], v[150:151], s[36:37] op_sel_hi:[1,0]
	v_med3_f32 v16, v16, s40, v216
	v_med3_f32 v17, v17, s40, v216
	v_med3_f32 v18, v18, s40, v216
	v_med3_f32 v19, v19, s40, v216
	v_med3_f32 v20, v20, s40, v216
	v_med3_f32 v21, v21, s40, v216
	v_med3_f32 v22, v22, s40, v216
	v_med3_f32 v23, v23, s40, v216
	v_med3_f32 v24, v24, s40, v216
	v_med3_f32 v25, v25, s40, v216
	v_med3_f32 v26, v26, s40, v216
	v_med3_f32 v27, v27, s40, v216
	v_med3_f32 v28, v28, s40, v216
	v_med3_f32 v29, v29, s40, v216
	v_med3_f32 v30, v30, s40, v216
	v_med3_f32 v31, v31, s40, v216
	v_med3_f32 v32, v32, s40, v216
	v_med3_f32 v33, v33, s40, v216
	v_med3_f32 v34, v34, s40, v216
	v_med3_f32 v35, v35, s40, v216
	v_med3_f32 v36, v36, s40, v216
	v_med3_f32 v37, v37, s40, v216
	v_med3_f32 v38, v38, s40, v216
	v_med3_f32 v39, v39, s40, v216
	v_med3_f32 v40, v40, s40, v216
	v_med3_f32 v41, v41, s40, v216
	v_med3_f32 v42, v42, s40, v216
	v_med3_f32 v43, v43, s40, v216
	v_med3_f32 v44, v44, s40, v216
	v_med3_f32 v45, v45, s40, v216
	v_med3_f32 v46, v46, s40, v216
	v_med3_f32 v47, v47, s40, v216
	v_med3_f32 v48, v48, s40, v216
	v_med3_f32 v49, v49, s40, v216
	v_med3_f32 v50, v50, s40, v216
	v_med3_f32 v51, v51, s40, v216
	v_med3_f32 v52, v52, s40, v216
	v_med3_f32 v53, v53, s40, v216
	v_med3_f32 v54, v54, s40, v216
	v_med3_f32 v55, v55, s40, v216
	v_med3_f32 v56, v56, s40, v216
	v_med3_f32 v57, v57, s40, v216
	v_med3_f32 v58, v58, s40, v216
	v_med3_f32 v59, v59, s40, v216
	v_med3_f32 v60, v60, s40, v216
	v_med3_f32 v61, v61, s40, v216
	v_med3_f32 v62, v62, s40, v216
	v_med3_f32 v63, v63, s40, v216
	v_med3_f32 v64, v64, s40, v216
	v_med3_f32 v65, v65, s40, v216
	v_med3_f32 v66, v66, s40, v216
	v_med3_f32 v67, v67, s40, v216
	v_med3_f32 v68, v68, s40, v216
	v_med3_f32 v69, v69, s40, v216
	v_med3_f32 v70, v70, s40, v216
	v_med3_f32 v71, v71, s40, v216
	v_med3_f32 v144, v144, s40, v216
	v_med3_f32 v145, v145, s40, v216
	v_med3_f32 v146, v146, s40, v216
	v_med3_f32 v147, v147, s40, v216
	v_med3_f32 v148, v148, s40, v216
	v_med3_f32 v149, v149, s40, v216
	v_med3_f32 v150, v150, s40, v216
	v_med3_f32 v151, v151, s40, v216
	v_pk_add_f32 v[16:17], v[16:17], s[38:39] op_sel_hi:[1,0]
	v_pk_add_f32 v[18:19], v[18:19], s[38:39] op_sel_hi:[1,0]
	v_pk_add_f32 v[20:21], v[20:21], s[38:39] op_sel_hi:[1,0]
	v_pk_add_f32 v[22:23], v[22:23], s[38:39] op_sel_hi:[1,0]
	v_pk_add_f32 v[24:25], v[24:25], s[38:39] op_sel_hi:[1,0]
; #define LAS __attribute__((address_space(3)))
; __device__ __forceinline__ unsigned pk4_f8(float a, float b, float c, float d) { int w = __builtin_amdgcn_cvt_pk_fp8_f32(a, b, 0, false); w = __builtin_amdgcn_cvt_pk_fp8_f32(c, d, w, true); return (unsigned)w; }
; #define LDS_WAIT() asm volatile("s_waitcnt lgkmcnt(0)" ::: "memory")
;     ...
;         for (int i = 0; i < 32; ++i) { const int kk = 2 * i + (lane >> 5); scr[kk * 33 + (lane & 31)] = W[(size_t)(k0 + kk) * ldw + n0 + (lane & 31)]; }
;         LDS_WAIT(); asm volatile("" ::: "memory");
;         const int c = lane & 3;
; #pragma unroll
;         for (int j = 0; j < 2; ++j) { const int n = (lane >> 2) + 16 * j; const LAS float* sp = scr + (16 * c) * 33 + n;
;             u32x4 o;
;             if (QI8) { o.x = pk4_i8(sp[0 * 33], sp[1 * 33], sp[2 * 33], sp[3 * 33], scl); o.y = pk4_i8(sp[4 * 33], sp[5 * 33], sp[6 * 33], sp[7 * 33], scl);
;                 o.z = pk4_i8(sp[8 * 33], sp[9 * 33], sp[10 * 33], sp[11 * 33], scl); o.w = pk4_i8(sp[12 * 33], sp[13 * 33], sp[14 * 33], sp[15 * 33], scl); }
;             else {
;             o.x = pk4_f8(sp[0 * 33] * scl, sp[1 * 33] * scl, sp[2 * 33] * scl, sp[3 * 33] * scl); o.y = pk4_f8(sp[4 * 33] * scl, sp[5 * 33] * scl, sp[6 * 33] * scl, sp[7 * 33] * scl);
;             o.z = pk4_f8(sp[8 * 33] * scl, sp[9 * 33] * scl, sp[10 * 33] * scl, sp[11 * 33] * scl); o.w = pk4_f8(sp[12 * 33] * scl, sp[13 * 33] * scl, sp[14 * 33] * scl, sp[15 * 33] * scl); }
;             *(u32x4*)(WT + (size_t)(dr0 + n) * K + k0 + 16 * c) = o; }
	v_pk_add_f32 v[26:27], v[26:27], s[38:39] op_sel_hi:[1,0]
	v_pk_add_f32 v[28:29], v[28:29], s[38:39] op_sel_hi:[1,0]
	v_pk_add_f32 v[30:31], v[30:31], s[38:39] op_sel_hi:[1,0]
	v_pk_add_f32 v[32:33], v[32:33], s[38:39] op_sel_hi:[1,0]
	v_pk_add_f32 v[34:35], v[34:35], s[38:39] op_sel_hi:[1,0]
	v_pk_add_f32 v[36:37], v[36:37], s[38:39] op_sel_hi:[1,0]
	v_pk_add_f32 v[38:39], v[38:39], s[38:39] op_sel_hi:[1,0]
	v_pk_add_f32 v[40:41], v[40:41], s[38:39] op_sel_hi:[1,0]
	v_pk_add_f32 v[42:43], v[42:43], s[38:39] op_sel_hi:[1,0]
	v_pk_add_f32 v[44:45], v[44:45], s[38:39] op_sel_hi:[1,0]
	v_pk_add_f32 v[46:47], v[46:47], s[38:39] op_sel_hi:[1,0]
	v_pk_add_f32 v[48:49], v[48:49], s[38:39] op_sel_hi:[1,0]
	v_pk_add_f32 v[50:51], v[50:51], s[38:39] op_sel_hi:[1,0]
	v_pk_add_f32 v[52:53], v[52:53], s[38:39] op_sel_hi:[1,0]
	v_pk_add_f32 v[54:55], v[54:55], s[38:39] op_sel_hi:[1,0]
	v_pk_add_f32 v[56:57], v[56:57], s[38:39] op_sel_hi:[1,0]
	v_pk_add_f32 v[58:59], v[58:59], s[38:39] op_sel_hi:[1,0]
	v_pk_add_f32 v[60:61], v[60:61], s[38:39] op_sel_hi:[1,0]
	v_pk_add_f32 v[62:63], v[62:63], s[38:39] op_sel_hi:[1,0]
	v_pk_add_f32 v[64:65], v[64:65], s[38:39] op_sel_hi:[1,0]
	v_pk_add_f32 v[66:67], v[66:67], s[38:39] op_sel_hi:[1,0]
	v_pk_add_f32 v[68:69], v[68:69], s[38:39] op_sel_hi:[1,0]
	v_pk_add_f32 v[70:71], v[70:71], s[38:39] op_sel_hi:[1,0]
	v_pk_add_f32 v[144:145], v[144:145], s[38:39] op_sel_hi:[1,0]
	v_pk_add_f32 v[146:147], v[146:147], s[38:39] op_sel_hi:[1,0]
	v_pk_add_f32 v[148:149], v[148:149], s[38:39] op_sel_hi:[1,0]
	v_pk_add_f32 v[150:151], v[150:151], s[38:39] op_sel_hi:[1,0]
	v_perm_b32 v204, v20, v16, s41
	v_perm_b32 v205, v28, v24, s41
	v_perm_b32 v184, v205, v204, s42
	v_perm_b32 v204, v36, v32, s41
	v_perm_b32 v205, v44, v40, s41
	v_perm_b32 v185, v205, v204, s42
	v_perm_b32 v204, v52, v48, s41
	v_perm_b32 v205, v60, v56, s41
	v_perm_b32 v186, v205, v204, s42
	v_perm_b32 v204, v68, v64, s41
	v_perm_b32 v205, v148, v144, s41
	v_perm_b32 v187, v205, v204, s42
	v_perm_b32 v204, v21, v17, s41
	v_perm_b32 v205, v29, v25, s41
	v_perm_b32 v188, v205, v204, s42
	v_perm_b32 v204, v37, v33, s41
	v_perm_b32 v205, v45, v41, s41
	v_perm_b32 v189, v205, v204, s42
	v_perm_b32 v204, v53, v49, s41
	v_perm_b32 v205, v61, v57, s41
	v_perm_b32 v190, v205, v204, s42
	v_perm_b32 v204, v69, v65, s41
	v_perm_b32 v205, v149, v145, s41
	v_perm_b32 v191, v205, v204, s42
	v_perm_b32 v204, v22, v18, s41
	v_perm_b32 v205, v30, v26, s41
	v_perm_b32 v192, v205, v204, s42
	v_perm_b32 v204, v38, v34, s41
	v_perm_b32 v205, v46, v42, s41
	v_perm_b32 v193, v205, v204, s42
	v_perm_b32 v204, v54, v50, s41
	v_perm_b32 v205, v62, v58, s41
	v_perm_b32 v194, v205, v204, s42
	v_perm_b32 v204, v70, v66, s41
	v_perm_b32 v205, v150, v146, s41
	v_perm_b32 v195, v205, v204, s42
	v_perm_b32 v204, v23, v19, s41
	v_perm_b32 v205, v31, v27, s41
	v_perm_b32 v196, v205, v204, s42
	v_perm_b32 v204, v39, v35, s41
	v_perm_b32 v205, v47, v43, s41
	v_perm_b32 v197, v205, v204, s42
	v_perm_b32 v204, v55, v51, s41
	v_perm_b32 v205, v63, v59, s41
	v_perm_b32 v198, v205, v204, s42
	v_perm_b32 v204, v71, v67, s41
	v_perm_b32 v205, v151, v147, s41
	v_perm_b32 v199, v205, v204, s42
	ds_write_b128 v213, v[184:187] offset:36864
	ds_write_b128 v213, v[188:191] offset:37008
	ds_write_b128 v213, v[192:195] offset:37152
	ds_write_b128 v213, v[196:199] offset:37296
	s_mov_b32 s26, s63
	s_add_i32 s26, s26, s17
	s_mul_i32 s26, s26, 0x1000
	s_add_u32 s26, s26, s62
	s_add_u32 s54, s44, s26
	s_addc_u32 s55, s45, 0
	s_waitcnt lgkmcnt(0)
	s_barrier
	ds_read_b128 v[184:187], v214 offset:36864
	ds_read_b128 v[188:191], v214 offset:38016
	ds_read_b128 v[192:195], v214 offset:39168
	ds_read_b128 v[196:199], v214 offset:40320
	s_waitcnt lgkmcnt(3)
	global_store_dwordx4 v215, v[184:187], s[54:55]
	s_add_u32 s54, s54, 0x8000
	s_addc_u32 s55, s55, 0
	s_waitcnt lgkmcnt(2)
	global_store_dwordx4 v215, v[188:191], s[54:55]
	s_add_u32 s54, s54, 0x8000
	s_addc_u32 s55, s55, 0
	s_waitcnt lgkmcnt(1)
	global_store_dwordx4 v215, v[192:195], s[54:55]
	s_add_u32 s54, s54, 0x8000
	s_addc_u32 s55, s55, 0
	s_waitcnt lgkmcnt(0)
	global_store_dwordx4 v215, v[196:199], s[54:55]
	s_mov_b32 s19, s59
	s_cmp_lt_u32 s19, 0x200
	s_cbranch_scc1 .Lf8t_win8bcd1_loop

;     ...
;     for (int item = F.gw; item < nitems; item += F.NGW) { const int kb = item / nblk, nb = item % nblk, k0 = 64 * kb, n0 = 32 * nb;
;         int dr0 = n0; if (MAP == 1) { if (n0 < DFF) dr0 = (n0 >> 7) * 256 + (n0 & 127); else { const int uo = n0 - DFF; dr0 = (uo >> 7) * 256 + 128 + (uo & 127); } }
; #pragma unroll 8
;         for (int i = 0; i < 32; ++i) { const int kk = 2 * i + (lane >> 5); scr[kk * 33 + (lane & 31)] = W[(size_t)(k0 + kk) * ldw + n0 + (lane & 31)]; }
; __device__ __forceinline__ void p0_prologue(Frame& F) {
;     ...
;     transpose_f8_matrix<0, true>(F, F.in[I_WOUT], D, D, F.ws + WS_WOUT, I8_WOUT);
.LBB0_67:
	s_andn2_b64 vcc, exec, s[6:7]
	s_cbranch_vccnz .LBB0_72
	s_barrier
	s_load_dwordx2 s[50:51], s[74:75], 0xd8
	v_readlane_b32 s16, v240, 2
	v_lshlrev_b32_e32 v212, 4, v178
	v_mov_b32_e32 v216, 0x42fe0000
	s_mov_b32 s36, 0x45559673
	s_mov_b32 s37, 0
	s_mov_b32 s38, 0x4b400000
	s_mov_b32 s39, 0
	s_mov_b32 s40, 0xc2fe0000
	s_mov_b32 s41, 0x0c0c0400
	s_mov_b32 s42, 0x05040100
	s_lshl_b32 s17, s16, 5
	v_mul_u32_u24_e32 v213, 0x240, v178
	s_lshl_b32 s18, s16, 4
	v_add_u32_e32 v213, s18, v213
	v_lshrrev_b32_e32 v204, 3, v178
	v_and_b32_e32 v205, 7, v178
	s_lshl_b32 s18, s16, 5
	v_add_u32_e32 v206, s18, v204
	v_mul_u32_u24_e32 v214, 0x90, v206
	v_lshl_add_u32 v214, v205, 4, v214
	v_mul_u32_u24_e32 v215, 0x1000, v204
	v_lshl_add_u32 v215, v205, 4, v215
	s_lshl_b32 s16, s16, 4
	s_waitcnt lgkmcnt(0)
	s_add_u32 s44, s90, 0x69d00000
	s_addc_u32 s45, s91, 0
	s_mov_b32 s19, s2
	s_cmp_lt_u32 s19, 0x200
	s_cbranch_scc0 .Lf8t_wout0_end
	s_mul_hi_u32 s20, s19, 0x10000000
	s_mul_i32 s21, s20, 16
	s_sub_i32 s21, s19, s21
	s_lshl_b32 s60, s20, 7
	s_lshl_b32 s61, s21, 8
	s_add_i32 s24, s60, s16
	s_mul_i32 s24, s24, 0x4000
	s_lshl_b32 s25, s61, 2
	s_add_u32 s24, s24, s25
	s_add_u32 s52, s50, s24
	s_addc_u32 s53, s51, 0
	global_load_dwordx4 v[80:83], v212, s[52:53]
	s_add_u32 s52, s52, 0x4000
	s_addc_u32 s53, s53, 0
	global_load_dwordx4 v[84:87], v212, s[52:53]
	s_add_u32 s52, s52, 0x4000
	s_addc_u32 s53, s53, 0
	global_load_dwordx4 v[88:91], v212, s[52:53]
	s_add_u32 s52, s52, 0x4000
	s_addc_u32 s53, s53, 0
	global_load_dwordx4 v[92:95], v212, s[52:53]
	s_add_u32 s52, s52, 0x4000
	s_addc_u32 s53, s53, 0
	global_load_dwordx4 v[96:99], v212, s[52:53]
	s_add_u32 s52, s52, 0x4000
	s_addc_u32 s53, s53, 0
	global_load_dwordx4 v[100:103], v212, s[52:53]
	s_add_u32 s52, s52, 0x4000
	s_addc_u32 s53, s53, 0
	global_load_dwordx4 v[104:107], v212, s[52:53]
	s_add_u32 s52, s52, 0x4000
	s_addc_u32 s53, s53, 0
	global_load_dwordx4 v[108:111], v212, s[52:53]
	s_add_u32 s52, s52, 0x4000
	s_addc_u32 s53, s53, 0
	global_load_dwordx4 v[112:115], v212, s[52:53]
	s_add_u32 s52, s52, 0x4000
	s_addc_u32 s53, s53, 0
	global_load_dwordx4 v[116:119], v212, s[52:53]
	s_add_u32 s52, s52, 0x4000
	s_addc_u32 s53, s53, 0
	global_load_dwordx4 v[120:123], v212, s[52:53]
	s_add_u32 s52, s52, 0x4000
	s_addc_u32 s53, s53, 0
	global_load_dwordx4 v[124:127], v212, s[52:53]
	s_add_u32 s52, s52, 0x4000
	s_addc_u32 s53, s53, 0
	global_load_dwordx4 v[128:131], v212, s[52:53]
	s_add_u32 s52, s52, 0x4000
	s_addc_u32 s53, s53, 0
	global_load_dwordx4 v[132:135], v212, s[52:53]
	s_add_u32 s52, s52, 0x4000
	s_addc_u32 s53, s53, 0
	global_load_dwordx4 v[136:139], v212, s[52:53]
	s_add_u32 s52, s52, 0x4000
	s_addc_u32 s53, s53, 0
	global_load_dwordx4 v[140:143], v212, s[52:53]
	s_mov_b32 s58, 1
.Lf8t_wout0_loop:
	s_add_i32 s59, s19, s96
	s_cmp_lt_u32 s59, 0x200
	s_cbranch_scc0 .Lf8t_wout0_a_nonext
	s_mul_hi_u32 s20, s59, 0x10000000
	s_mul_i32 s21, s20, 16
	s_sub_i32 s21, s59, s21
	s_lshl_b32 s62, s20, 7
	s_lshl_b32 s63, s21, 8
	s_add_i32 s24, s62, s16
	s_mul_i32 s24, s24, 0x4000
	s_lshl_b32 s25, s63, 2
	s_add_u32 s24, s24, s25
	s_add_u32 s52, s50, s24
	s_addc_u32 s53, s51, 0
	global_load_dwordx4 v[16:19], v212, s[52:53]
	s_add_u32 s52, s52, 0x4000
	s_addc_u32 s53, s53, 0
	global_load_dwordx4 v[20:23], v212, s[52:53]
	s_add_u32 s52, s52, 0x4000
	s_addc_u32 s53, s53, 0
	global_load_dwordx4 v[24:27], v212, s[52:53]
	s_add_u32 s52, s52, 0x4000
	s_addc_u32 s53, s53, 0
	global_load_dwordx4 v[28:31], v212, s[52:53]
	s_add_u32 s52, s52, 0x4000
	s_addc_u32 s53, s53, 0
	global_load_dwordx4 v[32:35], v212, s[52:53]
	s_add_u32 s52, s52, 0x4000
	s_addc_u32 s53, s53, 0
	global_load_dwordx4 v[36:39], v212, s[52:53]
	s_add_u32 s52, s52, 0x4000
	s_addc_u32 s53, s53, 0
	global_load_dwordx4 v[40:43], v212, s[52:53]
	s_add_u32 s52, s52, 0x4000
	s_addc_u32 s53, s53, 0
	global_load_dwordx4 v[44:47], v212, s[52:53]
	s_add_u32 s52, s52, 0x4000
	s_addc_u32 s53, s53, 0
	global_load_dwordx4 v[48:51], v212, s[52:53]
	s_add_u32 s52, s52, 0x4000
	s_addc_u32 s53, s53, 0
	global_load_dwordx4 v[52:55], v212, s[52:53]
	s_add_u32 s52, s52, 0x4000
	s_addc_u32 s53, s53, 0
	global_load_dwordx4 v[56:59], v212, s[52:53]
	s_add_u32 s52, s52, 0x4000
	s_addc_u32 s53, s53, 0
	global_load_dwordx4 v[60:63], v212, s[52:53]
	s_add_u32 s52, s52, 0x4000
	s_addc_u32 s53, s53, 0
	global_load_dwordx4 v[64:67], v212, s[52:53]
	s_add_u32 s52, s52, 0x4000
	s_addc_u32 s53, s53, 0
	global_load_dwordx4 v[68:71], v212, s[52:53]
	s_add_u32 s52, s52, 0x4000
	s_addc_u32 s53, s53, 0
	global_load_dwordx4 v[144:147], v212, s[52:53]
	s_add_u32 s52, s52, 0x4000
	s_addc_u32 s53, s53, 0
	global_load_dwordx4 v[148:151], v212, s[52:53]
	s_cmp_eq_u32 s58, 1
	s_cbranch_scc1 .Lf8t_wout0_a_first
	s_waitcnt vmcnt(20)
	s_branch .Lf8t_wout0_a_go

; __device__ __forceinline__ unsigned pk4_i8(float a, float b, float c, float d, float s) {
;     const unsigned ua = __float_as_uint(__builtin_amdgcn_fmed3f(a * s, -127.f, 127.f) + 12582912.f), ub = __float_as_uint(__builtin_amdgcn_fmed3f(b * s, -127.f, 127.f) + 12582912.f);
;     const unsigned uc = __float_as_uint(__builtin_amdgcn_fmed3f(c * s, -127.f, 127.f) + 12582912.f), ud = __float_as_uint(__builtin_amdgcn_fmed3f(d * s, -127.f, 127.f) + 12582912.f);
;     return (ua & 0xffu) | ((ub & 0xffu) << 8) | ((uc & 0xffu) << 16) | (ud << 24);
;     ...
;             if (QI8) { o.x = pk4_i8(sp[0 * 33], sp[1 * 33], sp[2 * 33], sp[3 * 33], scl); o.y = pk4_i8(sp[4 * 33], sp[5 * 33], sp[6 * 33], sp[7 * 33], scl);
;                 o.z = pk4_i8(sp[8 * 33], sp[9 * 33], sp[10 * 33], sp[11 * 33], scl); o.w = pk4_i8(sp[12 * 33], sp[13 * 33], sp[14 * 33], sp[15 * 33], scl); }
.Lf8t_wout0_a_go:
	s_mov_b32 s58, 0
	v_pk_mul_f32 v[80:81], v[80:81], s[36:37] op_sel_hi:[1,0]
	v_pk_mul_f32 v[82:83], v[82:83], s[36:37] op_sel_hi:[1,0]
	v_pk_mul_f32 v[84:85], v[84:85], s[36:37] op_sel_hi:[1,0]
	v_pk_mul_f32 v[86:87], v[86:87], s[36:37] op_sel_hi:[1,0]
	v_pk_mul_f32 v[88:89], v[88:89], s[36:37] op_sel_hi:[1,0]
	v_pk_mul_f32 v[90:91], v[90:91], s[36:37] op_sel_hi:[1,0]
	v_pk_mul_f32 v[92:93], v[92:93], s[36:37] op_sel_hi:[1,0]
	v_pk_mul_f32 v[94:95], v[94:95], s[36:37] op_sel_hi:[1,0]
	v_pk_mul_f32 v[96:97], v[96:97], s[36:37] op_sel_hi:[1,0]
	v_pk_mul_f32 v[98:99], v[98:99], s[36:37] op_sel_hi:[1,0]
	v_pk_mul_f32 v[100:101], v[100:101], s[36:37] op_sel_hi:[1,0]
	v_pk_mul_f32 v[102:103], v[102:103], s[36:37] op_sel_hi:[1,0]
	v_pk_mul_f32 v[104:105], v[104:105], s[36:37] op_sel_hi:[1,0]
	v_pk_mul_f32 v[106:107], v[106:107], s[36:37] op_sel_hi:[1,0]
	v_pk_mul_f32 v[108:109], v[108:109], s[36:37] op_sel_hi:[1,0]
	v_pk_mul_f32 v[110:111], v[110:111], s[36:37] op_sel_hi:[1,0]
	v_pk_mul_f32 v[112:113], v[112:113], s[36:37] op_sel_hi:[1,0]
	v_pk_mul_f32 v[114:115], v[114:115], s[36:37] op_sel_hi:[1,0]
	v_pk_mul_f32 v[116:117], v[116:117], s[36:37] op_sel_hi:[1,0]
	v_pk_mul_f32 v[118:119], v[118:119], s[36:37] op_sel_hi:[1,0]
	v_pk_mul_f32 v[120:121], v[120:121], s[36:37] op_sel_hi:[1,0]
	v_pk_mul_f32 v[122:123], v[122:123], s[36:37] op_sel_hi:[1,0]
	v_pk_mul_f32 v[124:125], v[124:125], s[36:37] op_sel_hi:[1,0]
	v_pk_mul_f32 v[126:127], v[126:127], s[36:37] op_sel_hi:[1,0]
	v_pk_mul_f32 v[128:129], v[128:129], s[36:37] op_sel_hi:[1,0]
	v_pk_mul_f32 v[130:131], v[130:131], s[36:37] op_sel_hi:[1,0]
	v_pk_mul_f32 v[132:133], v[132:133], s[36:37] op_sel_hi:[1,0]
	v_pk_mul_f32 v[134:135], v[134:135], s[36:37] op_sel_hi:[1,0]
	v_pk_mul_f32 v[136:137], v[136:137], s[36:37] op_sel_hi:[1,0]
	v_pk_mul_f32 v[138:139], v[138:139], s[36:37] op_sel_hi:[1,0]
	v_pk_mul_f32 v[140:141], v[140:141], s[36:37] op_sel_hi:[1,0]
	v_pk_mul_f32 v[142:143], v[142:143], s[36:37] op_sel_hi:[1,0]
	v_med3_f32 v80, v80, s40, v216
	v_med3_f32 v81, v81, s40, v216
	v_med3_f32 v82, v82, s40, v216
	v_med3_f32 v83, v83, s40, v216
	v_med3_f32 v84, v84, s40, v216
	v_med3_f32 v85, v85, s40, v216
	v_med3_f32 v86, v86, s40, v216
	v_med3_f32 v87, v87, s40, v216
	v_med3_f32 v88, v88, s40, v216
	v_med3_f32 v89, v89, s40, v216
	v_med3_f32 v90, v90, s40, v216
	v_med3_f32 v91, v91, s40, v216
	v_med3_f32 v92, v92, s40, v216
	v_med3_f32 v93, v93, s40, v216
	v_med3_f32 v94, v94, s40, v216
	v_med3_f32 v95, v95, s40, v216
	v_med3_f32 v96, v96, s40, v216
	v_med3_f32 v97, v97, s40, v216
	v_med3_f32 v98, v98, s40, v216
	v_med3_f32 v99, v99, s40, v216
	v_med3_f32 v100, v100, s40, v216
	v_med3_f32 v101, v101, s40, v216
	v_med3_f32 v102, v102, s40, v216
	v_med3_f32 v103, v103, s40, v216
	v_med3_f32 v104, v104, s40, v216
	v_med3_f32 v105, v105, s40, v216
	v_med3_f32 v106, v106, s40, v216
	v_med3_f32 v107, v107, s40, v216
	v_med3_f32 v108, v108, s40, v216
	v_med3_f32 v109, v109, s40, v216
	v_med3_f32 v110, v110, s40, v216
	v_med3_f32 v111, v111, s40, v216
	v_med3_f32 v112, v112, s40, v216
	v_med3_f32 v113, v113, s40, v216
	v_med3_f32 v114, v114, s40, v216
	v_med3_f32 v115, v115, s40, v216
	v_med3_f32 v116, v116, s40, v216
	v_med3_f32 v117, v117, s40, v216
	v_med3_f32 v118, v118, s40, v216
	v_med3_f32 v119, v119, s40, v216
	v_med3_f32 v120, v120, s40, v216
	v_med3_f32 v121, v121, s40, v216
	v_med3_f32 v122, v122, s40, v216
	v_med3_f32 v123, v123, s40, v216
	v_med3_f32 v124, v124, s40, v216
	v_med3_f32 v125, v125, s40, v216
	v_med3_f32 v126, v126, s40, v216
	v_med3_f32 v127, v127, s40, v216
	v_med3_f32 v128, v128, s40, v216
	v_med3_f32 v129, v129, s40, v216
	v_med3_f32 v130, v130, s40, v216
	v_med3_f32 v131, v131, s40, v216
	v_med3_f32 v132, v132, s40, v216
	v_med3_f32 v133, v133, s40, v216
	v_med3_f32 v134, v134, s40, v216
	v_med3_f32 v135, v135, s40, v216
	v_med3_f32 v136, v136, s40, v216
	v_med3_f32 v137, v137, s40, v216
	v_med3_f32 v138, v138, s40, v216
	v_med3_f32 v139, v139, s40, v216
	v_med3_f32 v140, v140, s40, v216
	v_med3_f32 v141, v141, s40, v216
	v_med3_f32 v142, v142, s40, v216
	v_med3_f32 v143, v143, s40, v216
	v_pk_add_f32 v[80:81], v[80:81], s[38:39] op_sel_hi:[1,0]
	v_pk_add_f32 v[82:83], v[82:83], s[38:39] op_sel_hi:[1,0]
	v_pk_add_f32 v[84:85], v[84:85], s[38:39] op_sel_hi:[1,0]
	v_pk_add_f32 v[86:87], v[86:87], s[38:39] op_sel_hi:[1,0]
	v_pk_add_f32 v[88:89], v[88:89], s[38:39] op_sel_hi:[1,0]
	v_pk_add_f32 v[90:91], v[90:91], s[38:39] op_sel_hi:[1,0]
	v_pk_add_f32 v[92:93], v[92:93], s[38:39] op_sel_hi:[1,0]
	v_pk_add_f32 v[94:95], v[94:95], s[38:39] op_sel_hi:[1,0]
	v_pk_add_f32 v[96:97], v[96:97], s[38:39] op_sel_hi:[1,0]
	v_pk_add_f32 v[98:99], v[98:99], s[38:39] op_sel_hi:[1,0]
	v_pk_add_f32 v[100:101], v[100:101], s[38:39] op_sel_hi:[1,0]
	v_pk_add_f32 v[102:103], v[102:103], s[38:39] op_sel_hi:[1,0]
	v_pk_add_f32 v[104:105], v[104:105], s[38:39] op_sel_hi:[1,0]
	v_pk_add_f32 v[106:107], v[106:107], s[38:39] op_sel_hi:[1,0]
	v_pk_add_f32 v[108:109], v[108:109], s[38:39] op_sel_hi:[1,0]
	v_pk_add_f32 v[110:111], v[110:111], s[38:39] op_sel_hi:[1,0]
	v_pk_add_f32 v[112:113], v[112:113], s[38:39] op_sel_hi:[1,0]
	v_pk_add_f32 v[114:115], v[114:115], s[38:39] op_sel_hi:[1,0]
	v_pk_add_f32 v[116:117], v[116:117], s[38:39] op_sel_hi:[1,0]
	v_pk_add_f32 v[118:119], v[118:119], s[38:39] op_sel_hi:[1,0]
; __device__ __forceinline__ unsigned pk4_f8(float a, float b, float c, float d) { int w = __builtin_amdgcn_cvt_pk_fp8_f32(a, b, 0, false); w = __builtin_amdgcn_cvt_pk_fp8_f32(c, d, w, true); return (unsigned)w; }
;     ...
;     for (int item = F.gw; item < nitems; item += F.NGW) { const int kb = item / nblk, nb = item % nblk, k0 = 64 * kb, n0 = 32 * nb;
;         int dr0 = n0; if (MAP == 1) { if (n0 < DFF) dr0 = (n0 >> 7) * 256 + (n0 & 127); else { const int uo = n0 - DFF; dr0 = (uo >> 7) * 256 + 128 + (uo & 127); } }
; #pragma unroll 8
;         for (int i = 0; i < 32; ++i) { const int kk = 2 * i + (lane >> 5); scr[kk * 33 + (lane & 31)] = W[(size_t)(k0 + kk) * ldw + n0 + (lane & 31)]; }
;     ...
;             if (QI8) { o.x = pk4_i8(sp[0 * 33], sp[1 * 33], sp[2 * 33], sp[3 * 33], scl); o.y = pk4_i8(sp[4 * 33], sp[5 * 33], sp[6 * 33], sp[7 * 33], scl);
;                 o.z = pk4_i8(sp[8 * 33], sp[9 * 33], sp[10 * 33], sp[11 * 33], scl); o.w = pk4_i8(sp[12 * 33], sp[13 * 33], sp[14 * 33], sp[15 * 33], scl); }
;             else {
;             o.x = pk4_f8(sp[0 * 33] * scl, sp[1 * 33] * scl, sp[2 * 33] * scl, sp[3 * 33] * scl); o.y = pk4_f8(sp[4 * 33] * scl, sp[5 * 33] * scl, sp[6 * 33] * scl, sp[7 * 33] * scl);
;             o.z = pk4_f8(sp[8 * 33] * scl, sp[9 * 33] * scl, sp[10 * 33] * scl, sp[11 * 33] * scl); o.w = pk4_f8(sp[12 * 33] * scl, sp[13 * 33] * scl, sp[14 * 33] * scl, sp[15 * 33] * scl); }
;             *(u32x4*)(WT + (size_t)(dr0 + n) * K + k0 + 16 * c) = o; }
	v_pk_add_f32 v[120:121], v[120:121], s[38:39] op_sel_hi:[1,0]
	v_pk_add_f32 v[122:123], v[122:123], s[38:39] op_sel_hi:[1,0]
	v_pk_add_f32 v[124:125], v[124:125], s[38:39] op_sel_hi:[1,0]
	v_pk_add_f32 v[126:127], v[126:127], s[38:39] op_sel_hi:[1,0]
	v_pk_add_f32 v[128:129], v[128:129], s[38:39] op_sel_hi:[1,0]
	v_pk_add_f32 v[130:131], v[130:131], s[38:39] op_sel_hi:[1,0]
	v_pk_add_f32 v[132:133], v[132:133], s[38:39] op_sel_hi:[1,0]
	v_pk_add_f32 v[134:135], v[134:135], s[38:39] op_sel_hi:[1,0]
	v_pk_add_f32 v[136:137], v[136:137], s[38:39] op_sel_hi:[1,0]
	v_pk_add_f32 v[138:139], v[138:139], s[38:39] op_sel_hi:[1,0]
	v_pk_add_f32 v[140:141], v[140:141], s[38:39] op_sel_hi:[1,0]
	v_pk_add_f32 v[142:143], v[142:143], s[38:39] op_sel_hi:[1,0]
	v_perm_b32 v204, v84, v80, s41
	v_perm_b32 v205, v92, v88, s41
	v_perm_b32 v184, v205, v204, s42
	v_perm_b32 v204, v100, v96, s41
	v_perm_b32 v205, v108, v104, s41
	v_perm_b32 v185, v205, v204, s42
	v_perm_b32 v204, v116, v112, s41
	v_perm_b32 v205, v124, v120, s41
	v_perm_b32 v186, v205, v204, s42
	v_perm_b32 v204, v132, v128, s41
	v_perm_b32 v205, v140, v136, s41
	v_perm_b32 v187, v205, v204, s42
	v_perm_b32 v204, v85, v81, s41
	v_perm_b32 v205, v93, v89, s41
	v_perm_b32 v188, v205, v204, s42
	v_perm_b32 v204, v101, v97, s41
	v_perm_b32 v205, v109, v105, s41
	v_perm_b32 v189, v205, v204, s42
	v_perm_b32 v204, v117, v113, s41
	v_perm_b32 v205, v125, v121, s41
	v_perm_b32 v190, v205, v204, s42
	v_perm_b32 v204, v133, v129, s41
	v_perm_b32 v205, v141, v137, s41
	v_perm_b32 v191, v205, v204, s42
	v_perm_b32 v204, v86, v82, s41
	v_perm_b32 v205, v94, v90, s41
	v_perm_b32 v192, v205, v204, s42
	v_perm_b32 v204, v102, v98, s41
	v_perm_b32 v205, v110, v106, s41
	v_perm_b32 v193, v205, v204, s42
	v_perm_b32 v204, v118, v114, s41
	v_perm_b32 v205, v126, v122, s41
	v_perm_b32 v194, v205, v204, s42
	v_perm_b32 v204, v134, v130, s41
	v_perm_b32 v205, v142, v138, s41
	v_perm_b32 v195, v205, v204, s42
	v_perm_b32 v204, v87, v83, s41
	v_perm_b32 v205, v95, v91, s41
	v_perm_b32 v196, v205, v204, s42
	v_perm_b32 v204, v103, v99, s41
	v_perm_b32 v205, v111, v107, s41
	v_perm_b32 v197, v205, v204, s42
	v_perm_b32 v204, v119, v115, s41
	v_perm_b32 v205, v127, v123, s41
	v_perm_b32 v198, v205, v204, s42
	v_perm_b32 v204, v135, v131, s41
	v_perm_b32 v205, v143, v139, s41
	v_perm_b32 v199, v205, v204, s42
	ds_write_b128 v213, v[184:187] offset:0
	ds_write_b128 v213, v[188:191] offset:144
	ds_write_b128 v213, v[192:195] offset:288
	ds_write_b128 v213, v[196:199] offset:432
	s_mov_b32 s26, s61
	s_add_i32 s26, s26, s17
	s_mul_i32 s26, s26, 0x1000
	s_add_u32 s26, s26, s60
	s_add_u32 s54, s44, s26
	s_addc_u32 s55, s45, 0
	s_waitcnt lgkmcnt(0)
	s_barrier
	ds_read_b128 v[184:187], v214 offset:0
	ds_read_b128 v[188:191], v214 offset:1152
	ds_read_b128 v[192:195], v214 offset:2304
	ds_read_b128 v[196:199], v214 offset:3456
	s_waitcnt lgkmcnt(3)
	global_store_dwordx4 v215, v[184:187], s[54:55]
	s_add_u32 s54, s54, 0x8000
	s_addc_u32 s55, s55, 0
	s_waitcnt lgkmcnt(2)
	global_store_dwordx4 v215, v[188:191], s[54:55]
	s_add_u32 s54, s54, 0x8000
	s_addc_u32 s55, s55, 0
	s_waitcnt lgkmcnt(1)
	global_store_dwordx4 v215, v[192:195], s[54:55]
	s_add_u32 s54, s54, 0x8000
	s_addc_u32 s55, s55, 0
	s_waitcnt lgkmcnt(0)
	global_store_dwordx4 v215, v[196:199], s[54:55]
	s_mov_b32 s19, s59
	s_cmp_lt_u32 s19, 0x200
	s_cbranch_scc0 .Lf8t_wout0_end
	s_add_i32 s59, s19, s96
	s_cmp_lt_u32 s59, 0x200
	s_cbranch_scc0 .Lf8t_wout0_b_nonext
	s_mul_hi_u32 s20, s59, 0x10000000
	s_mul_i32 s21, s20, 16
	s_sub_i32 s21, s59, s21
	s_lshl_b32 s60, s20, 7
	s_lshl_b32 s61, s21, 8
	s_add_i32 s24, s60, s16
	s_mul_i32 s24, s24, 0x4000
	s_lshl_b32 s25, s61, 2
	s_add_u32 s24, s24, s25
	s_add_u32 s52, s50, s24
	s_addc_u32 s53, s51, 0
	global_load_dwordx4 v[80:83], v212, s[52:53]
	s_add_u32 s52, s52, 0x4000
	s_addc_u32 s53, s53, 0
	global_load_dwordx4 v[84:87], v212, s[52:53]
	s_add_u32 s52, s52, 0x4000
	s_addc_u32 s53, s53, 0
	global_load_dwordx4 v[88:91], v212, s[52:53]
	s_add_u32 s52, s52, 0x4000
	s_addc_u32 s53, s53, 0
	global_load_dwordx4 v[92:95], v212, s[52:53]
	s_add_u32 s52, s52, 0x4000
	s_addc_u32 s53, s53, 0
	global_load_dwordx4 v[96:99], v212, s[52:53]
	s_add_u32 s52, s52, 0x4000
	s_addc_u32 s53, s53, 0
	global_load_dwordx4 v[100:103], v212, s[52:53]
	s_add_u32 s52, s52, 0x4000
	s_addc_u32 s53, s53, 0
	global_load_dwordx4 v[104:107], v212, s[52:53]
	s_add_u32 s52, s52, 0x4000
	s_addc_u32 s53, s53, 0
	global_load_dwordx4 v[108:111], v212, s[52:53]
	s_add_u32 s52, s52, 0x4000
	s_addc_u32 s53, s53, 0
	global_load_dwordx4 v[112:115], v212, s[52:53]
	s_add_u32 s52, s52, 0x4000
	s_addc_u32 s53, s53, 0
	global_load_dwordx4 v[116:119], v212, s[52:53]
	s_add_u32 s52, s52, 0x4000
	s_addc_u32 s53, s53, 0
	global_load_dwordx4 v[120:123], v212, s[52:53]
	s_add_u32 s52, s52, 0x4000
	s_addc_u32 s53, s53, 0
	global_load_dwordx4 v[124:127], v212, s[52:53]
	s_add_u32 s52, s52, 0x4000
	s_addc_u32 s53, s53, 0
	global_load_dwordx4 v[128:131], v212, s[52:53]
	s_add_u32 s52, s52, 0x4000
	s_addc_u32 s53, s53, 0
	global_load_dwordx4 v[132:135], v212, s[52:53]
	s_add_u32 s52, s52, 0x4000
	s_addc_u32 s53, s53, 0
	global_load_dwordx4 v[136:139], v212, s[52:53]
	s_add_u32 s52, s52, 0x4000
	s_addc_u32 s53, s53, 0
	global_load_dwordx4 v[140:143], v212, s[52:53]
	s_waitcnt vmcnt(20)
	s_branch .Lf8t_wout0_b_go

;     ...
;     for (int item = F.gw; item < nitems; item += F.NGW) { const int kb = item / nblk, nb = item % nblk, k0 = 64 * kb, n0 = 32 * nb;
;         int dr0 = n0; if (MAP == 1) { if (n0 < DFF) dr0 = (n0 >> 7) * 256 + (n0 & 127); else { const int uo = n0 - DFF; dr0 = (uo >> 7) * 256 + 128 + (uo & 127); } }
; #pragma unroll 8
;         for (int i = 0; i < 32; ++i) { const int kk = 2 * i + (lane >> 5); scr[kk * 33 + (lane & 31)] = W[(size_t)(k0 + kk) * ldw + n0 + (lane & 31)]; }
; __global__ void __launch_bounds__(512, 2) fwd_kernel(Params P) {
;     ...
;     transpose_f8_matrix<1, true>(F, P.in[I_F2IN], D, NFF, P.ws + WS_WFI, I8_W);
.LBB0_1170:
	v_readlane_b32 s0, v240, 3
	v_readlane_b32 s1, v240, 4
	v_readlane_b32 s80, v240, 31
	s_andn2_b64 vcc, exec, s[0:1]
	v_lshlrev_b32_e32 v2, 2, v164
	v_readlane_b32 s81, v240, 32
	s_cbranch_vccnz .LBB0_1179
	s_barrier
	s_load_dwordx2 s[50:51], s[74:75], 0xf0
	v_readlane_b32 s16, v240, 2
	v_lshlrev_b32_e32 v212, 4, v178
	v_mov_b32_e32 v216, 0x42fe0000
	s_mov_b32 s36, 0x44fe0000
	s_mov_b32 s37, 0
	s_mov_b32 s38, 0x4b400000
	s_mov_b32 s39, 0
	s_mov_b32 s40, 0xc2fe0000
	s_mov_b32 s41, 0x0c0c0400
	s_mov_b32 s42, 0x05040100
	s_lshl_b32 s17, s16, 5
	s_and_b32 s18, s16, 4
	s_lshl_b32 s18, s18, 5
	s_add_i32 s17, s17, s18
	v_mul_u32_u24_e32 v213, 0x240, v178
	s_lshl_b32 s18, s16, 4
	v_add_u32_e32 v213, s18, v213
	v_lshrrev_b32_e32 v204, 3, v178
	v_and_b32_e32 v205, 7, v178
	s_lshl_b32 s18, s16, 5
	v_add_u32_e32 v206, s18, v204
	v_mul_u32_u24_e32 v214, 0x90, v206
	v_lshl_add_u32 v214, v205, 4, v214
	v_mul_u32_u24_e32 v215, 0x1000, v204
	v_lshl_add_u32 v215, v205, 4, v215
	s_lshl_b32 s16, s16, 4
	s_waitcnt lgkmcnt(0)
	s_add_u32 s44, s90, 0x8300000
	s_addc_u32 s45, s91, 0
	s_mov_b32 s19, s2
	s_cmp_lt_u32 s19, 0xac0
	s_cbranch_scc0 .Lf8t_f2in0_end
	s_mul_hi_u32 s20, s19, 0x2fa0be9
	s_mul_i32 s21, s20, 86
	s_sub_i32 s21, s19, s21
	s_lshl_b32 s60, s20, 7
	s_lshl_b32 s61, s21, 8
	s_add_i32 s24, s60, s16
	s_mul_i32 s24, s24, 0x15800
	s_lshl_b32 s25, s61, 2
	s_add_u32 s24, s24, s25
	s_add_u32 s52, s50, s24
	s_addc_u32 s53, s51, 0
	global_load_dwordx4 v[80:83], v212, s[52:53]
	s_add_u32 s52, s52, 0x15800
	s_addc_u32 s53, s53, 0
	global_load_dwordx4 v[84:87], v212, s[52:53]
	s_add_u32 s52, s52, 0x15800
	s_addc_u32 s53, s53, 0
	global_load_dwordx4 v[88:91], v212, s[52:53]
	s_add_u32 s52, s52, 0x15800
	s_addc_u32 s53, s53, 0
	global_load_dwordx4 v[92:95], v212, s[52:53]
	s_add_u32 s52, s52, 0x15800
	s_addc_u32 s53, s53, 0
	global_load_dwordx4 v[96:99], v212, s[52:53]
	s_add_u32 s52, s52, 0x15800
	s_addc_u32 s53, s53, 0
	global_load_dwordx4 v[100:103], v212, s[52:53]
	s_add_u32 s52, s52, 0x15800
	s_addc_u32 s53, s53, 0
	global_load_dwordx4 v[104:107], v212, s[52:53]
	s_add_u32 s52, s52, 0x15800
	s_addc_u32 s53, s53, 0
	global_load_dwordx4 v[108:111], v212, s[52:53]
	s_add_u32 s52, s52, 0x15800
	s_addc_u32 s53, s53, 0
	global_load_dwordx4 v[112:115], v212, s[52:53]
	s_add_u32 s52, s52, 0x15800
	s_addc_u32 s53, s53, 0
	global_load_dwordx4 v[116:119], v212, s[52:53]
	s_add_u32 s52, s52, 0x15800
	s_addc_u32 s53, s53, 0
	global_load_dwordx4 v[120:123], v212, s[52:53]
	s_add_u32 s52, s52, 0x15800
	s_addc_u32 s53, s53, 0
	global_load_dwordx4 v[124:127], v212, s[52:53]
	s_add_u32 s52, s52, 0x15800
	s_addc_u32 s53, s53, 0
	global_load_dwordx4 v[128:131], v212, s[52:53]
	s_add_u32 s52, s52, 0x15800
	s_addc_u32 s53, s53, 0
	global_load_dwordx4 v[132:135], v212, s[52:53]
	s_add_u32 s52, s52, 0x15800
	s_addc_u32 s53, s53, 0
	global_load_dwordx4 v[136:139], v212, s[52:53]
	s_add_u32 s52, s52, 0x15800
	s_addc_u32 s53, s53, 0
	global_load_dwordx4 v[140:143], v212, s[52:53]
	s_mov_b32 s58, 1

;     ...
;     for (int item = F.gw; item < nitems; item += F.NGW) { const int kb = item / nblk, nb = item % nblk, k0 = 64 * kb, n0 = 32 * nb;
;         int dr0 = n0; if (MAP == 1) { if (n0 < DFF) dr0 = (n0 >> 7) * 256 + (n0 & 127); else { const int uo = n0 - DFF; dr0 = (uo >> 7) * 256 + 128 + (uo & 127); } }
; #pragma unroll 8
;         for (int i = 0; i < 32; ++i) { const int kk = 2 * i + (lane >> 5); scr[kk * 33 + (lane & 31)] = W[(size_t)(k0 + kk) * ldw + n0 + (lane & 31)]; }
; __global__ void __launch_bounds__(512, 2) fwd_kernel(Params P) {
;     ...
;     transpose_f8_matrix<0>(F, P.in[I_F2DN], DFF, D, P.ws + WS_WFD, pg8::W8SCALE_DN); }
.LBB0_1179:
	v_readlane_b32 s0, v240, 5
	v_readlane_b32 s1, v240, 6
	s_andn2_b64 vcc, exec, s[0:1]
	s_cbranch_vccnz .LBB0_1184
	s_barrier
	s_load_dwordx2 s[50:51], s[74:75], 0xf8
	v_readlane_b32 s16, v240, 2
	v_lshlrev_b32_e32 v212, 4, v178
	v_mov_b32_e32 v216, 0x42fe0000
	s_mov_b32 s36, 0x43000000
	s_mov_b32 s37, 0
	s_mov_b32 s38, 0x4b400000
	s_mov_b32 s39, 0
	s_mov_b32 s40, 0xc2fe0000
	s_mov_b32 s41, 0x0c0c0400
	s_mov_b32 s42, 0x05040100
	s_lshl_b32 s17, s16, 5
	v_mul_u32_u24_e32 v213, 0x240, v178
	s_lshl_b32 s18, s16, 4
	v_add_u32_e32 v213, s18, v213
	v_lshrrev_b32_e32 v204, 3, v178
	v_and_b32_e32 v205, 7, v178
	s_lshl_b32 s18, s16, 5
	v_add_u32_e32 v206, s18, v204
	v_mul_u32_u24_e32 v214, 0x90, v206
	v_lshl_add_u32 v214, v205, 4, v214
	v_mul_u32_u24_e32 v215, 0x2b00, v204
	v_lshl_add_u32 v215, v205, 4, v215
	s_lshl_b32 s16, s16, 4
	s_waitcnt lgkmcnt(0)
	s_add_u32 s44, s90, 0x12f00000
	s_addc_u32 s45, s91, 0
	s_mov_b32 s19, s2
	s_cmp_lt_u32 s19, 0x560
	s_cbranch_scc0 .Lf8t_f2dn0_end
	s_mul_hi_u32 s20, s19, 0x10000000
	s_mul_i32 s21, s20, 16
	s_sub_i32 s21, s19, s21
	s_lshl_b32 s60, s20, 7
	s_lshl_b32 s61, s21, 8
	s_add_i32 s24, s60, s16
	s_mul_i32 s24, s24, 0x4000
	s_lshl_b32 s25, s61, 2
	s_add_u32 s24, s24, s25
	s_add_u32 s52, s50, s24
	s_addc_u32 s53, s51, 0
	global_load_dwordx4 v[80:83], v212, s[52:53]
	s_add_u32 s52, s52, 0x4000
	s_addc_u32 s53, s53, 0
	global_load_dwordx4 v[84:87], v212, s[52:53]
	s_add_u32 s52, s52, 0x4000
	s_addc_u32 s53, s53, 0
	global_load_dwordx4 v[88:91], v212, s[52:53]
	s_add_u32 s52, s52, 0x4000
	s_addc_u32 s53, s53, 0
	global_load_dwordx4 v[92:95], v212, s[52:53]
	s_add_u32 s52, s52, 0x4000
	s_addc_u32 s53, s53, 0
	global_load_dwordx4 v[96:99], v212, s[52:53]
	s_add_u32 s52, s52, 0x4000
	s_addc_u32 s53, s53, 0
	global_load_dwordx4 v[100:103], v212, s[52:53]
	s_add_u32 s52, s52, 0x4000
	s_addc_u32 s53, s53, 0
	global_load_dwordx4 v[104:107], v212, s[52:53]
	s_add_u32 s52, s52, 0x4000
	s_addc_u32 s53, s53, 0
	global_load_dwordx4 v[108:111], v212, s[52:53]
	s_add_u32 s52, s52, 0x4000
	s_addc_u32 s53, s53, 0
	global_load_dwordx4 v[112:115], v212, s[52:53]
	s_add_u32 s52, s52, 0x4000
	s_addc_u32 s53, s53, 0
	global_load_dwordx4 v[116:119], v212, s[52:53]
	s_add_u32 s52, s52, 0x4000
	s_addc_u32 s53, s53, 0
	global_load_dwordx4 v[120:123], v212, s[52:53]
	s_add_u32 s52, s52, 0x4000
	s_addc_u32 s53, s53, 0
	global_load_dwordx4 v[124:127], v212, s[52:53]
	s_add_u32 s52, s52, 0x4000
	s_addc_u32 s53, s53, 0
	global_load_dwordx4 v[128:131], v212, s[52:53]
	s_add_u32 s52, s52, 0x4000
	s_addc_u32 s53, s53, 0
	global_load_dwordx4 v[132:135], v212, s[52:53]
	s_add_u32 s52, s52, 0x4000
	s_addc_u32 s53, s53, 0
	global_load_dwordx4 v[136:139], v212, s[52:53]
	s_add_u32 s52, s52, 0x4000
	s_addc_u32 s53, s53, 0
	global_load_dwordx4 v[140:143], v212, s[52:53]
	s_mov_b32 s58, 1

; __device__ __forceinline__ void xcd_barrier(const XcdBarrier& b) {
;     asm volatile("s_waitcnt vmcnt(0)" ::: "memory");
;     __syncthreads();
;     if (threadIdx.x == 0) {
;         unsigned* bar = b.bar;
;         __builtin_amdgcn_s_waitcnt(0);
;         unsigned nloc = b.st[0], nx = b.st[1];
;         if (nloc == 0u) { xcd_barrier_complete(bar, b.x, nloc, nx); b.st[0] = nloc; b.st[1] = nx; }
.Lf8t_f2dn0_end:
	s_waitcnt vmcnt(0) lgkmcnt(0)
	s_barrier
.LBB0_1184:
	s_waitcnt vmcnt(0)
	s_barrier
	s_and_saveexec_b64 s[0:1], s[80:81]
	s_cbranch_execz .LBB0_1236
	s_add_i32 s3, 0, 0x23f20
	v_mov_b32_e32 v1, s3
	s_waitcnt vmcnt(0) expcnt(0) lgkmcnt(0)
	ds_read_b32 v3, v1
	s_add_i32 s3, 0, 0x23f24
	v_mov_b32_e32 v1, s3
	ds_read_b32 v1, v1
	s_waitcnt lgkmcnt(1)
	v_cmp_ne_u32_e32 vcc, 0, v3
	s_cbranch_vccnz .LBB0_1200
	s_load_dwordx2 s[10:11], s[82:83], 0x4
	s_add_u32 s4, s90, 0x1200
	s_addc_u32 s5, s91, 0
	s_add_u32 s6, s90, 0x1400
	s_addc_u32 s7, s91, 0
	s_waitcnt lgkmcnt(0)
	s_mul_i32 s3, s10, s96
	s_add_u32 s10, s90, 0x1500
	s_mul_i32 s3, s3, s11
	s_addc_u32 s11, s91, 0
	s_add_u32 s12, s90, 0x1600
	s_addc_u32 s13, s91, 0
	s_add_u32 s14, s90, 0x1700
	s_addc_u32 s15, s91, 0
	s_add_u32 s16, s90, 0x1800
	s_addc_u32 s17, s91, 0
	s_add_u32 s18, s90, 0x1900
	s_addc_u32 s19, s91, 0
	s_add_u32 s20, s90, 0x1a00
	s_addc_u32 s21, s91, 0
	s_add_u32 s22, s90, 0x1b00
	s_addc_u32 s23, s91, 0
	s_add_u32 s24, s90, 0x1c00
	s_addc_u32 s25, s91, 0
	s_add_u32 s26, s90, 0x1d00
	s_addc_u32 s27, s91, 0
	s_add_u32 s28, s90, 0x1e00
	s_addc_u32 s29, s91, 0
	s_add_u32 s30, s90, 0x1f00
	s_addc_u32 s31, s91, 0
	s_add_u32 s34, s90, 0x2000
	s_addc_u32 s35, s91, 0
	s_add_u32 s36, s90, 0x2100
	s_addc_u32 s37, s91, 0
	s_add_u32 s38, s90, 0x2200
	s_addc_u32 s39, s91, 0
	s_add_u32 s40, s90, 0x2300
	s_addc_u32 s41, s91, 0
	s_mov_b32 s33, 1
	v_mov_b32_e32 v17, 0
	s_branch .LBB0_1188
